# K-loop trim: drop redundant post-barrier lgkmcnt(0) and mid-segment setprio 0/1 pairs
# speedup vs baseline: 1.0005x; 1.0005x over previous
.LBB0_323:
	s_add_u32 s26, s24, 0xfffc0080
	s_addc_u32 s27, s25, -1
	s_add_i32 s36, 0, 0x10000
	s_cmp_eq_u32 s21, 12
	s_cselect_b32 s57, s17, s27
	s_cselect_b32 s56, s16, s26
	v_add_u32_e32 v142, s36, v161
	s_cselect_b32 s27, s19, s15
	s_cselect_b32 s26, s18, s13
	s_add_i32 s38, 0, 0x14000
	ds_read_b128 v[144:147], v142
	ds_read_b128 v[148:151], v142 offset:1024
	ds_read_b128 v[152:155], v142 offset:2048
	ds_read_b128 v[178:181], v142 offset:3072
	v_add_u32_e32 v142, s38, v161
	ds_read_b128 v[182:185], v142
	ds_read_b128 v[186:189], v142 offset:1024
	ds_read_b128 v[190:193], v142 offset:2048
	ds_read_b128 v[194:197], v142 offset:3072
	v_lshl_add_u64 v[156:157], s[24:25], 0, v[140:141]
	s_add_i32 m0, s68, 0xc000
	ds_read_b128 v[198:201], v177
	ds_read_b128 v[202:205], v177 offset:1024
	ds_read_b128 v[206:209], v177 offset:2048
	ds_read_b128 v[210:213], v177 offset:3072
	ds_read_b128 v[214:217], v177 offset:4096
	ds_read_b128 v[222:225], v177 offset:5120
	ds_read_b128 v[226:229], v177 offset:6144
	ds_read_b128 v[230:233], v177 offset:7168
	global_load_lds_dwordx4 v[156:157], off
	v_lshl_add_u64 v[156:157], s[24:25], 0, v[138:139]
	s_add_i32 m0, s68, 0xe000
	s_nop 0
	global_load_lds_dwordx4 v[156:157], off
	s_waitcnt vmcnt(8)
	s_waitcnt lgkmcnt(0)
	s_barrier
	s_setprio 1
	v_mfma_i32_16x16x64_i8 v[126:129], v[144:147], v[198:201], v[126:129]
	v_mfma_i32_16x16x64_i8 v[118:121], v[152:155], v[198:201], v[118:121]
	v_mfma_i32_16x16x64_i8 v[110:113], v[144:147], v[206:209], v[110:113]
	v_mfma_i32_16x16x64_i8 v[102:105], v[152:155], v[206:209], v[102:105]
	v_mfma_i32_16x16x64_i8 v[94:97], v[144:147], v[214:217], v[94:97]
	v_mfma_i32_16x16x64_i8 v[86:89], v[152:155], v[214:217], v[86:89]
	v_mfma_i32_16x16x64_i8 v[78:81], v[144:147], v[226:229], v[78:81]
	v_mfma_i32_16x16x64_i8 v[70:73], v[152:155], v[226:229], v[70:73]
	v_mfma_i32_16x16x64_i8 v[126:129], v[148:151], v[202:205], v[126:129]
	v_mfma_i32_16x16x64_i8 v[118:121], v[178:181], v[202:205], v[118:121]
	v_mfma_i32_16x16x64_i8 v[110:113], v[148:151], v[210:213], v[110:113]
	v_mfma_i32_16x16x64_i8 v[102:105], v[178:181], v[210:213], v[102:105]
	v_mfma_i32_16x16x64_i8 v[94:97], v[148:151], v[222:225], v[94:97]
	v_mfma_i32_16x16x64_i8 v[86:89], v[178:181], v[222:225], v[86:89]
	v_mfma_i32_16x16x64_i8 v[78:81], v[148:151], v[230:233], v[78:81]
	v_mfma_i32_16x16x64_i8 v[70:73], v[178:181], v[230:233], v[70:73]
	v_mfma_i32_16x16x64_i8 v[122:125], v[182:185], v[198:201], v[122:125]
	v_mfma_i32_16x16x64_i8 v[114:117], v[190:193], v[198:201], v[114:117]
	v_mfma_i32_16x16x64_i8 v[106:109], v[182:185], v[206:209], v[106:109]
	v_mfma_i32_16x16x64_i8 v[98:101], v[190:193], v[206:209], v[98:101]
	v_mfma_i32_16x16x64_i8 v[90:93], v[182:185], v[214:217], v[90:93]
	v_mfma_i32_16x16x64_i8 v[82:85], v[190:193], v[214:217], v[82:85]
	v_mfma_i32_16x16x64_i8 v[74:77], v[182:185], v[226:229], v[74:77]
	v_mfma_i32_16x16x64_i8 v[66:69], v[190:193], v[226:229], v[66:69]
	v_mfma_i32_16x16x64_i8 v[122:125], v[186:189], v[202:205], v[122:125]
	v_mfma_i32_16x16x64_i8 v[114:117], v[194:197], v[202:205], v[114:117]
	v_mfma_i32_16x16x64_i8 v[106:109], v[186:189], v[210:213], v[106:109]
	v_mfma_i32_16x16x64_i8 v[98:101], v[194:197], v[210:213], v[98:101]
	v_mfma_i32_16x16x64_i8 v[90:93], v[186:189], v[222:225], v[90:93]
	v_mfma_i32_16x16x64_i8 v[82:85], v[194:197], v[222:225], v[82:85]
	v_mfma_i32_16x16x64_i8 v[74:77], v[186:189], v[230:233], v[74:77]
	v_mfma_i32_16x16x64_i8 v[66:69], v[194:197], v[230:233], v[66:69]
	s_setprio 0
	s_barrier
	s_add_i32 s36, s36, s23
	v_lshl_add_u64 v[156:157], s[26:27], 0, v[162:163]
	s_mov_b32 m0, s36
	ds_read_b128 v[198:201], v177 offset:16384
	ds_read_b128 v[202:205], v177 offset:17408
	ds_read_b128 v[206:209], v177 offset:18432
	ds_read_b128 v[210:213], v177 offset:19456
	ds_read_b128 v[214:217], v177 offset:20480
	ds_read_b128 v[222:225], v177 offset:21504
	ds_read_b128 v[226:229], v177 offset:22528
	ds_read_b128 v[230:233], v177 offset:23552
	global_load_lds_dwordx4 v[156:157], off
	s_add_i32 m0, s36, 0x2000
	s_add_u32 s36, s26, 0x80000
	v_lshl_add_u64 v[174:175], s[26:27], 0, v[134:135]
	s_addc_u32 s37, s27, 0
	s_add_i32 s38, s38, s23
	global_load_lds_dwordx4 v[174:175], off
	v_lshl_add_u64 v[234:235], s[36:37], 0, v[162:163]
	s_mov_b32 m0, s38
	v_lshl_add_u64 v[236:237], s[56:57], 0, v[132:133]
	global_load_lds_dwordx4 v[234:235], off
	v_lshl_add_u64 v[234:235], s[36:37], 0, v[134:135]
	s_add_i32 m0, s38, 0x2000
	s_nop 0
	global_load_lds_dwordx4 v[234:235], off
	v_lshl_add_u64 v[234:235], s[56:57], 0, v[130:131]
	s_mov_b32 m0, s68
	s_nop 0
	global_load_lds_dwordx4 v[234:235], off
	s_mov_b32 m0, s69
	s_nop 0
	global_load_lds_dwordx4 v[236:237], off
	s_waitcnt vmcnt(8)
	s_waitcnt lgkmcnt(0)
	s_barrier
	s_setprio 1
	v_mfma_i32_16x16x64_i8 v[62:65], v[144:147], v[198:201], v[62:65]
	v_mfma_i32_16x16x64_i8 v[54:57], v[152:155], v[198:201], v[54:57]
	v_mfma_i32_16x16x64_i8 v[46:49], v[144:147], v[206:209], v[46:49]
	v_mfma_i32_16x16x64_i8 v[38:41], v[152:155], v[206:209], v[38:41]
	v_mfma_i32_16x16x64_i8 v[30:33], v[144:147], v[214:217], v[30:33]
	v_mfma_i32_16x16x64_i8 v[22:25], v[152:155], v[214:217], v[22:25]
	v_mfma_i32_16x16x64_i8 v[14:17], v[144:147], v[226:229], v[14:17]
	v_mfma_i32_16x16x64_i8 v[6:9], v[152:155], v[226:229], v[6:9]
	v_mfma_i32_16x16x64_i8 v[62:65], v[148:151], v[202:205], v[62:65]
	v_mfma_i32_16x16x64_i8 v[54:57], v[178:181], v[202:205], v[54:57]
	v_mfma_i32_16x16x64_i8 v[46:49], v[148:151], v[210:213], v[46:49]
	v_mfma_i32_16x16x64_i8 v[38:41], v[178:181], v[210:213], v[38:41]
	v_mfma_i32_16x16x64_i8 v[30:33], v[148:151], v[222:225], v[30:33]
	v_mfma_i32_16x16x64_i8 v[22:25], v[178:181], v[222:225], v[22:25]
	v_mfma_i32_16x16x64_i8 v[14:17], v[148:151], v[230:233], v[14:17]
	v_mfma_i32_16x16x64_i8 v[6:9], v[178:181], v[230:233], v[6:9]
	v_mfma_i32_16x16x64_i8 v[58:61], v[182:185], v[198:201], v[58:61]
	v_mfma_i32_16x16x64_i8 v[50:53], v[190:193], v[198:201], v[50:53]
	v_mfma_i32_16x16x64_i8 v[42:45], v[182:185], v[206:209], v[42:45]
	v_mfma_i32_16x16x64_i8 v[34:37], v[190:193], v[206:209], v[34:37]
	v_mfma_i32_16x16x64_i8 v[26:29], v[182:185], v[214:217], v[26:29]
	v_mfma_i32_16x16x64_i8 v[18:21], v[190:193], v[214:217], v[18:21]
	v_mfma_i32_16x16x64_i8 v[10:13], v[182:185], v[226:229], v[10:13]
	v_mfma_i32_16x16x64_i8 v[2:5], v[190:193], v[226:229], v[2:5]
	v_mfma_i32_16x16x64_i8 v[58:61], v[186:189], v[202:205], v[58:61]
	v_mfma_i32_16x16x64_i8 v[50:53], v[194:197], v[202:205], v[50:53]
	v_mfma_i32_16x16x64_i8 v[42:45], v[186:189], v[210:213], v[42:45]
	v_mfma_i32_16x16x64_i8 v[34:37], v[194:197], v[210:213], v[34:37]
	v_mfma_i32_16x16x64_i8 v[26:29], v[186:189], v[222:225], v[26:29]
	v_mfma_i32_16x16x64_i8 v[18:21], v[194:197], v[222:225], v[18:21]
	v_mfma_i32_16x16x64_i8 v[10:13], v[186:189], v[230:233], v[10:13]
	v_mfma_i32_16x16x64_i8 v[2:5], v[194:197], v[230:233], v[2:5]
	s_setprio 0
	s_barrier
	s_add_i32 s38, 0, 0x18000
	v_add_u32_e32 v142, s38, v161
	s_add_i32 s39, 0, 0x1c000
	ds_read_b128 v[144:147], v142
	ds_read_b128 v[148:151], v142 offset:1024
	ds_read_b128 v[152:155], v142 offset:2048
	ds_read_b128 v[178:181], v142 offset:3072
	v_add_u32_e32 v142, s39, v161
	ds_read_b128 v[182:185], v142
	ds_read_b128 v[186:189], v142 offset:1024
	ds_read_b128 v[190:193], v142 offset:2048
	ds_read_b128 v[194:197], v142 offset:3072
	s_add_u32 s36, s56, 0x40000
	s_addc_u32 s37, s57, 0
	s_mov_b32 m0, s70
	v_lshl_add_u64 v[238:239], s[36:37], 0, v[130:131]
	ds_read_b128 v[198:201], v177 offset:32768
	ds_read_b128 v[202:205], v177 offset:33792
	ds_read_b128 v[206:209], v177 offset:34816
	ds_read_b128 v[210:213], v177 offset:35840
	ds_read_b128 v[214:217], v177 offset:36864
	ds_read_b128 v[222:225], v177 offset:37888
	ds_read_b128 v[226:229], v177 offset:38912
	ds_read_b128 v[230:233], v177 offset:39936
	global_load_lds_dwordx4 v[238:239], off
	v_lshl_add_u64 v[238:239], s[36:37], 0, v[132:133]
	s_mov_b32 m0, s71
	s_nop 0
	global_load_lds_dwordx4 v[238:239], off
	s_waitcnt vmcnt(8)
	s_waitcnt lgkmcnt(0)
	s_barrier
	s_setprio 1
	v_mfma_i32_16x16x64_i8 v[126:129], v[144:147], v[198:201], v[126:129]
	v_mfma_i32_16x16x64_i8 v[118:121], v[152:155], v[198:201], v[118:121]
	v_mfma_i32_16x16x64_i8 v[110:113], v[144:147], v[206:209], v[110:113]
	v_mfma_i32_16x16x64_i8 v[102:105], v[152:155], v[206:209], v[102:105]
	v_mfma_i32_16x16x64_i8 v[94:97], v[144:147], v[214:217], v[94:97]
	v_mfma_i32_16x16x64_i8 v[86:89], v[152:155], v[214:217], v[86:89]
	v_mfma_i32_16x16x64_i8 v[78:81], v[144:147], v[226:229], v[78:81]
	v_mfma_i32_16x16x64_i8 v[70:73], v[152:155], v[226:229], v[70:73]
	v_mfma_i32_16x16x64_i8 v[126:129], v[148:151], v[202:205], v[126:129]
	v_mfma_i32_16x16x64_i8 v[118:121], v[178:181], v[202:205], v[118:121]
	v_mfma_i32_16x16x64_i8 v[110:113], v[148:151], v[210:213], v[110:113]
	v_mfma_i32_16x16x64_i8 v[102:105], v[178:181], v[210:213], v[102:105]
	v_mfma_i32_16x16x64_i8 v[94:97], v[148:151], v[222:225], v[94:97]
	v_mfma_i32_16x16x64_i8 v[86:89], v[178:181], v[222:225], v[86:89]
	v_mfma_i32_16x16x64_i8 v[78:81], v[148:151], v[230:233], v[78:81]
	v_mfma_i32_16x16x64_i8 v[70:73], v[178:181], v[230:233], v[70:73]
	v_mfma_i32_16x16x64_i8 v[122:125], v[182:185], v[198:201], v[122:125]
	v_mfma_i32_16x16x64_i8 v[114:117], v[190:193], v[198:201], v[114:117]
	v_mfma_i32_16x16x64_i8 v[106:109], v[182:185], v[206:209], v[106:109]
	v_mfma_i32_16x16x64_i8 v[98:101], v[190:193], v[206:209], v[98:101]
	v_mfma_i32_16x16x64_i8 v[90:93], v[182:185], v[214:217], v[90:93]
	v_mfma_i32_16x16x64_i8 v[82:85], v[190:193], v[214:217], v[82:85]
	v_mfma_i32_16x16x64_i8 v[74:77], v[182:185], v[226:229], v[74:77]
	v_mfma_i32_16x16x64_i8 v[66:69], v[190:193], v[226:229], v[66:69]
	v_mfma_i32_16x16x64_i8 v[122:125], v[186:189], v[202:205], v[122:125]
	v_mfma_i32_16x16x64_i8 v[114:117], v[194:197], v[202:205], v[114:117]
	v_mfma_i32_16x16x64_i8 v[106:109], v[186:189], v[210:213], v[106:109]
	v_mfma_i32_16x16x64_i8 v[98:101], v[194:197], v[210:213], v[98:101]
	v_mfma_i32_16x16x64_i8 v[90:93], v[186:189], v[222:225], v[90:93]
	v_mfma_i32_16x16x64_i8 v[82:85], v[194:197], v[222:225], v[82:85]
	v_mfma_i32_16x16x64_i8 v[74:77], v[186:189], v[230:233], v[74:77]
	v_mfma_i32_16x16x64_i8 v[66:69], v[194:197], v[230:233], v[66:69]
	s_setprio 0
	s_barrier
	s_add_i32 s36, s38, s23
	v_lshl_add_u64 v[156:157], v[156:157], 0, s[44:45]
	s_mov_b32 m0, s36
	ds_read_b128 v[198:201], v177 offset:49152
	ds_read_b128 v[202:205], v177 offset:50176
	ds_read_b128 v[206:209], v177 offset:51200
	ds_read_b128 v[210:213], v177 offset:52224
	ds_read_b128 v[214:217], v177 offset:53248
	ds_read_b128 v[222:225], v177 offset:54272
	ds_read_b128 v[226:229], v177 offset:55296
	ds_read_b128 v[230:233], v177 offset:56320
	global_load_lds_dwordx4 v[156:157], off
	s_add_i32 m0, s36, 0x2000
	s_add_u32 s26, s26, 0x80080
	v_lshl_add_u64 v[156:157], v[174:175], 0, s[44:45]
	s_addc_u32 s27, s27, 0
	s_add_i32 s36, s39, s23
	global_load_lds_dwordx4 v[156:157], off
	v_lshl_add_u64 v[156:157], s[26:27], 0, v[162:163]
	s_mov_b32 m0, s36
	s_nop 0
	global_load_lds_dwordx4 v[156:157], off
	v_lshl_add_u64 v[156:157], s[26:27], 0, v[134:135]
	s_add_i32 m0, s36, 0x2000
	s_nop 0
	global_load_lds_dwordx4 v[156:157], off
	v_lshl_add_u64 v[156:157], v[234:235], 0, s[44:45]
	s_mov_b32 m0, s72
	s_nop 0
	global_load_lds_dwordx4 v[156:157], off
	v_lshl_add_u64 v[156:157], v[236:237], 0, s[44:45]
	s_mov_b32 m0, s73
	s_nop 0
	global_load_lds_dwordx4 v[156:157], off
	s_waitcnt vmcnt(8)
	s_waitcnt lgkmcnt(0)
	s_barrier
	s_setprio 1
	v_mfma_i32_16x16x64_i8 v[62:65], v[144:147], v[198:201], v[62:65]
	v_mfma_i32_16x16x64_i8 v[54:57], v[152:155], v[198:201], v[54:57]
	v_mfma_i32_16x16x64_i8 v[46:49], v[144:147], v[206:209], v[46:49]
	v_mfma_i32_16x16x64_i8 v[38:41], v[152:155], v[206:209], v[38:41]
	v_mfma_i32_16x16x64_i8 v[30:33], v[144:147], v[214:217], v[30:33]
	v_mfma_i32_16x16x64_i8 v[22:25], v[152:155], v[214:217], v[22:25]
	v_mfma_i32_16x16x64_i8 v[14:17], v[144:147], v[226:229], v[14:17]
	v_mfma_i32_16x16x64_i8 v[6:9], v[152:155], v[226:229], v[6:9]
	v_mfma_i32_16x16x64_i8 v[62:65], v[148:151], v[202:205], v[62:65]
	v_mfma_i32_16x16x64_i8 v[54:57], v[178:181], v[202:205], v[54:57]
	v_mfma_i32_16x16x64_i8 v[46:49], v[148:151], v[210:213], v[46:49]
	v_mfma_i32_16x16x64_i8 v[38:41], v[178:181], v[210:213], v[38:41]
	v_mfma_i32_16x16x64_i8 v[30:33], v[148:151], v[222:225], v[30:33]
	v_mfma_i32_16x16x64_i8 v[22:25], v[178:181], v[222:225], v[22:25]
	v_mfma_i32_16x16x64_i8 v[14:17], v[148:151], v[230:233], v[14:17]
	v_mfma_i32_16x16x64_i8 v[6:9], v[178:181], v[230:233], v[6:9]
	v_mfma_i32_16x16x64_i8 v[58:61], v[182:185], v[198:201], v[58:61]
	v_mfma_i32_16x16x64_i8 v[50:53], v[190:193], v[198:201], v[50:53]
	v_mfma_i32_16x16x64_i8 v[42:45], v[182:185], v[206:209], v[42:45]
	v_mfma_i32_16x16x64_i8 v[34:37], v[190:193], v[206:209], v[34:37]
	v_mfma_i32_16x16x64_i8 v[26:29], v[182:185], v[214:217], v[26:29]
	v_mfma_i32_16x16x64_i8 v[18:21], v[190:193], v[214:217], v[18:21]
	v_mfma_i32_16x16x64_i8 v[10:13], v[182:185], v[226:229], v[10:13]
	v_mfma_i32_16x16x64_i8 v[2:5], v[190:193], v[226:229], v[2:5]
	v_mfma_i32_16x16x64_i8 v[58:61], v[186:189], v[202:205], v[58:61]
	v_mfma_i32_16x16x64_i8 v[50:53], v[194:197], v[202:205], v[50:53]
	v_mfma_i32_16x16x64_i8 v[42:45], v[186:189], v[210:213], v[42:45]
	v_mfma_i32_16x16x64_i8 v[34:37], v[194:197], v[210:213], v[34:37]
	v_mfma_i32_16x16x64_i8 v[26:29], v[186:189], v[222:225], v[26:29]
	v_mfma_i32_16x16x64_i8 v[18:21], v[194:197], v[222:225], v[18:21]
	v_mfma_i32_16x16x64_i8 v[10:13], v[186:189], v[230:233], v[10:13]
	v_mfma_i32_16x16x64_i8 v[2:5], v[194:197], v[230:233], v[2:5]
	s_setprio 0
	s_barrier
	s_add_i32 s21, s21, 2
	s_add_u32 s13, s13, 0x100
	s_addc_u32 s15, s15, 0
	s_add_u32 s24, s24, 0x100
	s_addc_u32 s25, s25, 0
	s_cmp_gt_u32 s21, 13
	s_cbranch_scc0 .LBB0_323
	s_and_b64 vcc, exec, s[10:11]
	s_cbranch_vccz .LBB0_326
	s_barrier

.LBB0_437:
	s_add_u32 s26, s24, 0x4000
	s_addc_u32 s27, s25, 0
	s_cmpk_eq_i32 s82, 0x54
	s_cselect_b32 s58, s20, s26
	s_cselect_b32 s59, s21, s27
	s_cselect_b32 s56, s22, s80
	s_cselect_b32 s57, s23, s81
	s_add_u32 s26, s58, 0x8000
	s_addc_u32 s27, s59, 0
	s_add_i32 s36, 0, 0x10000
	s_add_i32 s38, 0, 0x14000
	v_add_u32_e32 v126, s36, v197
	v_add_u32_e32 v168, s38, v197
	ds_read_b128 v[114:117], v126
	ds_read_b128 v[118:121], v126 offset:1024
	ds_read_b128 v[122:125], v126 offset:2048
	ds_read_b128 v[126:129], v126 offset:3072
	ds_read_b128 v[138:141], v168
	ds_read_b128 v[142:145], v168 offset:1024
	ds_read_b128 v[154:157], v168 offset:2048
	ds_read_b128 v[178:181], v168 offset:3072
	v_lshl_add_u64 v[194:195], s[24:25], 0, v[176:177]
	s_add_i32 m0, s63, 0xc000
	ds_read_b128 v[182:185], v199
	ds_read_b128 v[186:189], v199 offset:1024
	ds_read_b128 v[190:193], v199 offset:2048
	ds_read_b128 v[200:203], v199 offset:3072
	ds_read_b128 v[204:207], v199 offset:4096
	ds_read_b128 v[208:211], v199 offset:5120
	ds_read_b128 v[212:215], v199 offset:6144
	ds_read_b128 v[222:225], v199 offset:7168
	global_load_lds_dwordx4 v[194:195], off
	v_lshl_add_u64 v[194:195], s[24:25], 0, v[174:175]
	s_add_i32 m0, s63, 0xe000
	s_nop 0
	global_load_lds_dwordx4 v[194:195], off
	s_waitcnt vmcnt(8)
	s_waitcnt lgkmcnt(0)
	s_barrier
	s_setprio 1
	v_mfma_f32_16x16x32_bf16 v[150:153], v[114:117], v[182:185], v[150:153]
	v_mfma_f32_16x16x32_bf16 v[146:149], v[122:125], v[182:185], v[146:149]
	v_mfma_f32_16x16x32_bf16 v[110:113], v[114:117], v[190:193], v[110:113]
	v_mfma_f32_16x16x32_bf16 v[106:109], v[122:125], v[190:193], v[106:109]
	v_mfma_f32_16x16x32_bf16 v[94:97], v[114:117], v[204:207], v[94:97]
	v_mfma_f32_16x16x32_bf16 v[90:93], v[122:125], v[204:207], v[90:93]
	v_mfma_f32_16x16x32_bf16 v[78:81], v[114:117], v[212:215], v[78:81]
	v_mfma_f32_16x16x32_bf16 v[74:77], v[122:125], v[212:215], v[74:77]
	v_mfma_f32_16x16x32_bf16 v[150:153], v[118:121], v[186:189], v[150:153]
	v_mfma_f32_16x16x32_bf16 v[146:149], v[126:129], v[186:189], v[146:149]
	v_mfma_f32_16x16x32_bf16 v[110:113], v[118:121], v[200:203], v[110:113]
	v_mfma_f32_16x16x32_bf16 v[106:109], v[126:129], v[200:203], v[106:109]
	v_mfma_f32_16x16x32_bf16 v[94:97], v[118:121], v[208:211], v[94:97]
	v_mfma_f32_16x16x32_bf16 v[90:93], v[126:129], v[208:211], v[90:93]
	v_mfma_f32_16x16x32_bf16 v[78:81], v[118:121], v[222:225], v[78:81]
	v_mfma_f32_16x16x32_bf16 v[74:77], v[126:129], v[222:225], v[74:77]
	v_mfma_f32_16x16x32_bf16 v[134:137], v[138:141], v[182:185], v[134:137]
	v_mfma_f32_16x16x32_bf16 v[130:133], v[154:157], v[182:185], v[130:133]
	v_mfma_f32_16x16x32_bf16 v[102:105], v[138:141], v[190:193], v[102:105]
	v_mfma_f32_16x16x32_bf16 v[98:101], v[154:157], v[190:193], v[98:101]
	v_mfma_f32_16x16x32_bf16 v[86:89], v[138:141], v[204:207], v[86:89]
	v_mfma_f32_16x16x32_bf16 v[82:85], v[154:157], v[204:207], v[82:85]
	v_mfma_f32_16x16x32_bf16 v[70:73], v[138:141], v[212:215], v[70:73]
	v_mfma_f32_16x16x32_bf16 v[66:69], v[154:157], v[212:215], v[66:69]
	v_mfma_f32_16x16x32_bf16 v[134:137], v[142:145], v[186:189], v[134:137]
	v_mfma_f32_16x16x32_bf16 v[130:133], v[178:181], v[186:189], v[130:133]
	v_mfma_f32_16x16x32_bf16 v[102:105], v[142:145], v[200:203], v[102:105]
	v_mfma_f32_16x16x32_bf16 v[98:101], v[178:181], v[200:203], v[98:101]
	v_mfma_f32_16x16x32_bf16 v[86:89], v[142:145], v[208:211], v[86:89]
	v_mfma_f32_16x16x32_bf16 v[82:85], v[178:181], v[208:211], v[82:85]
	v_mfma_f32_16x16x32_bf16 v[70:73], v[142:145], v[222:225], v[70:73]
	v_mfma_f32_16x16x32_bf16 v[66:69], v[178:181], v[222:225], v[66:69]
	s_setprio 0
	s_barrier
	s_add_i32 s36, s36, s62
	v_lshl_add_u64 v[194:195], s[56:57], 0, v[162:163]
	s_mov_b32 m0, s36
	ds_read_b128 v[182:185], v199 offset:16384
	ds_read_b128 v[186:189], v199 offset:17408
	ds_read_b128 v[190:193], v199 offset:18432
	ds_read_b128 v[200:203], v199 offset:19456
	ds_read_b128 v[204:207], v199 offset:20480
	ds_read_b128 v[208:211], v199 offset:21504
	ds_read_b128 v[212:215], v199 offset:22528
	ds_read_b128 v[222:225], v199 offset:23552
	global_load_lds_dwordx4 v[194:195], off
	s_add_i32 m0, s36, 0x2000
	s_add_u32 s36, s56, 0x160000
	v_lshl_add_u64 v[216:217], s[56:57], 0, v[172:173]
	s_addc_u32 s37, s57, 0
	s_add_i32 s38, s38, s62
	global_load_lds_dwordx4 v[216:217], off
	v_lshl_add_u64 v[226:227], s[36:37], 0, v[162:163]
	s_mov_b32 m0, s38
	s_nop 0
	global_load_lds_dwordx4 v[226:227], off
	v_lshl_add_u64 v[226:227], s[36:37], 0, v[172:173]
	s_add_i32 m0, s38, 0x2000
	s_nop 0
	global_load_lds_dwordx4 v[226:227], off
	v_lshl_add_u64 v[226:227], s[58:59], 0, v[158:159]
	s_mov_b32 m0, s63
	s_nop 0
	global_load_lds_dwordx4 v[226:227], off
	v_lshl_add_u64 v[226:227], s[58:59], 0, v[160:161]
	s_mov_b32 m0, s64
	s_nop 0
	global_load_lds_dwordx4 v[226:227], off
	s_waitcnt vmcnt(8)
	s_waitcnt lgkmcnt(0)
	s_barrier
	s_setprio 1
	v_mfma_f32_16x16x32_bf16 v[62:65], v[114:117], v[182:185], v[62:65]
	v_mfma_f32_16x16x32_bf16 v[58:61], v[122:125], v[182:185], v[58:61]
	v_mfma_f32_16x16x32_bf16 v[46:49], v[114:117], v[190:193], v[46:49]
	v_mfma_f32_16x16x32_bf16 v[42:45], v[122:125], v[190:193], v[42:45]
	v_mfma_f32_16x16x32_bf16 v[30:33], v[114:117], v[204:207], v[30:33]
	v_mfma_f32_16x16x32_bf16 v[26:29], v[122:125], v[204:207], v[26:29]
	v_mfma_f32_16x16x32_bf16 v[14:17], v[114:117], v[212:215], v[14:17]
	v_mfma_f32_16x16x32_bf16 v[10:13], v[122:125], v[212:215], v[10:13]
	v_mfma_f32_16x16x32_bf16 v[62:65], v[118:121], v[186:189], v[62:65]
	v_mfma_f32_16x16x32_bf16 v[58:61], v[126:129], v[186:189], v[58:61]
	v_mfma_f32_16x16x32_bf16 v[46:49], v[118:121], v[200:203], v[46:49]
	v_mfma_f32_16x16x32_bf16 v[42:45], v[126:129], v[200:203], v[42:45]
	v_mfma_f32_16x16x32_bf16 v[30:33], v[118:121], v[208:211], v[30:33]
	v_mfma_f32_16x16x32_bf16 v[26:29], v[126:129], v[208:211], v[26:29]
	v_mfma_f32_16x16x32_bf16 v[14:17], v[118:121], v[222:225], v[14:17]
	v_mfma_f32_16x16x32_bf16 v[10:13], v[126:129], v[222:225], v[10:13]
	v_mfma_f32_16x16x32_bf16 v[54:57], v[138:141], v[182:185], v[54:57]
	v_mfma_f32_16x16x32_bf16 v[50:53], v[154:157], v[182:185], v[50:53]
	v_mfma_f32_16x16x32_bf16 v[38:41], v[138:141], v[190:193], v[38:41]
	v_mfma_f32_16x16x32_bf16 v[34:37], v[154:157], v[190:193], v[34:37]
	v_mfma_f32_16x16x32_bf16 v[22:25], v[138:141], v[204:207], v[22:25]
	v_mfma_f32_16x16x32_bf16 v[18:21], v[154:157], v[204:207], v[18:21]
	v_mfma_f32_16x16x32_bf16 v[6:9], v[138:141], v[212:215], v[6:9]
	v_mfma_f32_16x16x32_bf16 v[2:5], v[154:157], v[212:215], v[2:5]
	v_mfma_f32_16x16x32_bf16 v[54:57], v[142:145], v[186:189], v[54:57]
	v_mfma_f32_16x16x32_bf16 v[50:53], v[178:181], v[186:189], v[50:53]
	v_mfma_f32_16x16x32_bf16 v[38:41], v[142:145], v[200:203], v[38:41]
	v_mfma_f32_16x16x32_bf16 v[34:37], v[178:181], v[200:203], v[34:37]
	v_mfma_f32_16x16x32_bf16 v[22:25], v[142:145], v[208:211], v[22:25]
	v_mfma_f32_16x16x32_bf16 v[18:21], v[178:181], v[208:211], v[18:21]
	v_mfma_f32_16x16x32_bf16 v[6:9], v[142:145], v[222:225], v[6:9]
	v_mfma_f32_16x16x32_bf16 v[2:5], v[178:181], v[222:225], v[2:5]
	s_setprio 0
	s_barrier
	s_add_i32 s38, 0, 0x18000
	s_add_i32 s39, 0, 0x1c000
	v_add_u32_e32 v126, s38, v197
	v_add_u32_e32 v168, s39, v197
	ds_read_b128 v[114:117], v126
	ds_read_b128 v[118:121], v126 offset:1024
	ds_read_b128 v[122:125], v126 offset:2048
	ds_read_b128 v[126:129], v126 offset:3072
	ds_read_b128 v[138:141], v168
	ds_read_b128 v[142:145], v168 offset:1024
	ds_read_b128 v[154:157], v168 offset:2048
	ds_read_b128 v[178:181], v168 offset:3072
	s_add_u32 s36, s58, 0x4000
	s_addc_u32 s37, s59, 0
	s_mov_b32 m0, s65
	v_lshl_add_u64 v[226:227], s[36:37], 0, v[158:159]
	ds_read_b128 v[182:185], v199 offset:32768
	ds_read_b128 v[186:189], v199 offset:33792
	ds_read_b128 v[190:193], v199 offset:34816
	ds_read_b128 v[200:203], v199 offset:35840
	ds_read_b128 v[204:207], v199 offset:36864
	ds_read_b128 v[208:211], v199 offset:37888
	ds_read_b128 v[212:215], v199 offset:38912
	ds_read_b128 v[222:225], v199 offset:39936
	global_load_lds_dwordx4 v[226:227], off
	v_lshl_add_u64 v[226:227], s[36:37], 0, v[160:161]
	s_mov_b32 m0, s66
	s_nop 0
	global_load_lds_dwordx4 v[226:227], off
	s_waitcnt vmcnt(8)
	s_waitcnt lgkmcnt(0)
	s_barrier
	s_setprio 1
	v_mfma_f32_16x16x32_bf16 v[150:153], v[114:117], v[182:185], v[150:153]
	v_mfma_f32_16x16x32_bf16 v[146:149], v[122:125], v[182:185], v[146:149]
	v_mfma_f32_16x16x32_bf16 v[110:113], v[114:117], v[190:193], v[110:113]
	v_mfma_f32_16x16x32_bf16 v[106:109], v[122:125], v[190:193], v[106:109]
	v_mfma_f32_16x16x32_bf16 v[94:97], v[114:117], v[204:207], v[94:97]
	v_mfma_f32_16x16x32_bf16 v[90:93], v[122:125], v[204:207], v[90:93]
	v_mfma_f32_16x16x32_bf16 v[78:81], v[114:117], v[212:215], v[78:81]
	v_mfma_f32_16x16x32_bf16 v[74:77], v[122:125], v[212:215], v[74:77]
	v_mfma_f32_16x16x32_bf16 v[150:153], v[118:121], v[186:189], v[150:153]
	v_mfma_f32_16x16x32_bf16 v[146:149], v[126:129], v[186:189], v[146:149]
	v_mfma_f32_16x16x32_bf16 v[110:113], v[118:121], v[200:203], v[110:113]
	v_mfma_f32_16x16x32_bf16 v[106:109], v[126:129], v[200:203], v[106:109]
	v_mfma_f32_16x16x32_bf16 v[94:97], v[118:121], v[208:211], v[94:97]
	v_mfma_f32_16x16x32_bf16 v[90:93], v[126:129], v[208:211], v[90:93]
	v_mfma_f32_16x16x32_bf16 v[78:81], v[118:121], v[222:225], v[78:81]
	v_mfma_f32_16x16x32_bf16 v[74:77], v[126:129], v[222:225], v[74:77]
	v_mfma_f32_16x16x32_bf16 v[134:137], v[138:141], v[182:185], v[134:137]
	v_mfma_f32_16x16x32_bf16 v[130:133], v[154:157], v[182:185], v[130:133]
	v_mfma_f32_16x16x32_bf16 v[102:105], v[138:141], v[190:193], v[102:105]
	v_mfma_f32_16x16x32_bf16 v[98:101], v[154:157], v[190:193], v[98:101]
	v_mfma_f32_16x16x32_bf16 v[86:89], v[138:141], v[204:207], v[86:89]
	v_mfma_f32_16x16x32_bf16 v[82:85], v[154:157], v[204:207], v[82:85]
	v_mfma_f32_16x16x32_bf16 v[70:73], v[138:141], v[212:215], v[70:73]
	v_mfma_f32_16x16x32_bf16 v[66:69], v[154:157], v[212:215], v[66:69]
	v_mfma_f32_16x16x32_bf16 v[134:137], v[142:145], v[186:189], v[134:137]
	v_mfma_f32_16x16x32_bf16 v[130:133], v[178:181], v[186:189], v[130:133]
	v_mfma_f32_16x16x32_bf16 v[102:105], v[142:145], v[200:203], v[102:105]
	v_mfma_f32_16x16x32_bf16 v[98:101], v[178:181], v[200:203], v[98:101]
	v_mfma_f32_16x16x32_bf16 v[86:89], v[142:145], v[208:211], v[86:89]
	v_mfma_f32_16x16x32_bf16 v[82:85], v[178:181], v[208:211], v[82:85]
	v_mfma_f32_16x16x32_bf16 v[70:73], v[142:145], v[222:225], v[70:73]
	v_mfma_f32_16x16x32_bf16 v[66:69], v[178:181], v[222:225], v[66:69]
	s_setprio 0
	s_barrier
	s_add_i32 s36, s38, s62
	v_lshl_add_u64 v[194:195], v[194:195], 0, s[44:45]
	s_mov_b32 m0, s36
	ds_read_b128 v[182:185], v199 offset:49152
	ds_read_b128 v[186:189], v199 offset:50176
	ds_read_b128 v[190:193], v199 offset:51200
	ds_read_b128 v[200:203], v199 offset:52224
	ds_read_b128 v[204:207], v199 offset:53248
	ds_read_b128 v[208:211], v199 offset:54272
	ds_read_b128 v[212:215], v199 offset:55296
	ds_read_b128 v[222:225], v199 offset:56320
	global_load_lds_dwordx4 v[194:195], off
	s_add_i32 m0, s36, 0x2000
	s_add_u32 s36, s56, 0x160080
	v_lshl_add_u64 v[194:195], v[216:217], 0, s[44:45]
	s_addc_u32 s37, s57, 0
	s_add_i32 s38, s39, s62
	global_load_lds_dwordx4 v[194:195], off
	v_lshl_add_u64 v[194:195], s[36:37], 0, v[162:163]
	s_mov_b32 m0, s38
	s_nop 0
	global_load_lds_dwordx4 v[194:195], off
	v_lshl_add_u64 v[194:195], s[36:37], 0, v[172:173]
	s_add_i32 m0, s38, 0x2000
	s_nop 0
	global_load_lds_dwordx4 v[194:195], off
	v_lshl_add_u64 v[194:195], s[26:27], 0, v[158:159]
	s_mov_b32 m0, s67
	s_nop 0
	global_load_lds_dwordx4 v[194:195], off
	v_lshl_add_u64 v[194:195], s[26:27], 0, v[160:161]
	s_mov_b32 m0, s68
	s_nop 0
	global_load_lds_dwordx4 v[194:195], off
	s_waitcnt vmcnt(8)
	s_waitcnt lgkmcnt(0)
	s_barrier
	s_setprio 1
	v_mfma_f32_16x16x32_bf16 v[62:65], v[114:117], v[182:185], v[62:65]
	v_mfma_f32_16x16x32_bf16 v[58:61], v[122:125], v[182:185], v[58:61]
	v_mfma_f32_16x16x32_bf16 v[46:49], v[114:117], v[190:193], v[46:49]
	v_mfma_f32_16x16x32_bf16 v[42:45], v[122:125], v[190:193], v[42:45]
	v_mfma_f32_16x16x32_bf16 v[30:33], v[114:117], v[204:207], v[30:33]
	v_mfma_f32_16x16x32_bf16 v[26:29], v[122:125], v[204:207], v[26:29]
	v_mfma_f32_16x16x32_bf16 v[14:17], v[114:117], v[212:215], v[14:17]
	v_mfma_f32_16x16x32_bf16 v[10:13], v[122:125], v[212:215], v[10:13]
	v_mfma_f32_16x16x32_bf16 v[62:65], v[118:121], v[186:189], v[62:65]
	v_mfma_f32_16x16x32_bf16 v[58:61], v[126:129], v[186:189], v[58:61]
	v_mfma_f32_16x16x32_bf16 v[46:49], v[118:121], v[200:203], v[46:49]
	v_mfma_f32_16x16x32_bf16 v[42:45], v[126:129], v[200:203], v[42:45]
	v_mfma_f32_16x16x32_bf16 v[30:33], v[118:121], v[208:211], v[30:33]
	v_mfma_f32_16x16x32_bf16 v[26:29], v[126:129], v[208:211], v[26:29]
	v_mfma_f32_16x16x32_bf16 v[14:17], v[118:121], v[222:225], v[14:17]
	v_mfma_f32_16x16x32_bf16 v[10:13], v[126:129], v[222:225], v[10:13]
	v_mfma_f32_16x16x32_bf16 v[54:57], v[138:141], v[182:185], v[54:57]
	v_mfma_f32_16x16x32_bf16 v[50:53], v[154:157], v[182:185], v[50:53]
	v_mfma_f32_16x16x32_bf16 v[38:41], v[138:141], v[190:193], v[38:41]
	v_mfma_f32_16x16x32_bf16 v[34:37], v[154:157], v[190:193], v[34:37]
	v_mfma_f32_16x16x32_bf16 v[22:25], v[138:141], v[204:207], v[22:25]
	v_mfma_f32_16x16x32_bf16 v[18:21], v[154:157], v[204:207], v[18:21]
	v_mfma_f32_16x16x32_bf16 v[6:9], v[138:141], v[212:215], v[6:9]
	v_mfma_f32_16x16x32_bf16 v[2:5], v[154:157], v[212:215], v[2:5]
	v_mfma_f32_16x16x32_bf16 v[54:57], v[142:145], v[186:189], v[54:57]
	v_mfma_f32_16x16x32_bf16 v[50:53], v[178:181], v[186:189], v[50:53]
	v_mfma_f32_16x16x32_bf16 v[38:41], v[142:145], v[200:203], v[38:41]
	v_mfma_f32_16x16x32_bf16 v[34:37], v[178:181], v[200:203], v[34:37]
	v_mfma_f32_16x16x32_bf16 v[22:25], v[142:145], v[208:211], v[22:25]
	v_mfma_f32_16x16x32_bf16 v[18:21], v[178:181], v[208:211], v[18:21]
	v_mfma_f32_16x16x32_bf16 v[6:9], v[142:145], v[222:225], v[6:9]
	v_mfma_f32_16x16x32_bf16 v[2:5], v[178:181], v[222:225], v[2:5]
	s_setprio 0
	s_barrier
	s_add_i32 s82, s82, 2
	s_add_u32 s24, s24, 0x10000
	s_addc_u32 s25, s25, 0
	s_add_u32 s80, s80, 0x100
	s_addc_u32 s81, s81, 0
	s_cmpk_gt_u32 s82, 0x55
	s_cbranch_scc0 .LBB0_437
	s_and_b64 vcc, exec, s[18:19]
	s_cbranch_vccz .LBB0_440
	s_barrier

.LBB0_643:
	s_add_u32 s36, s58, 0xfff80080
	s_addc_u32 s37, s59, -1
	s_add_i32 s38, 0, 0x10000
	s_cmp_eq_u32 s64, 28
	s_cselect_b32 s63, s23, s37
	s_cselect_b32 s62, s22, s36
	s_cselect_b32 s61, s25, s57
	s_cselect_b32 s60, s24, s21
	s_add_i32 s39, 0, 0x14000
	v_add_u32_e32 v152, s38, v161
	v_add_u32_e32 v156, s39, v161
	ds_read_b128 v[140:143], v152
	ds_read_b128 v[144:147], v152 offset:1024
	ds_read_b128 v[148:151], v152 offset:2048
	ds_read_b128 v[152:155], v152 offset:3072
	ds_read_b128 v[180:183], v156
	ds_read_b128 v[184:187], v156 offset:1024
	ds_read_b128 v[188:191], v156 offset:2048
	ds_read_b128 v[192:195], v156 offset:3072
	v_lshl_add_u64 v[172:173], s[58:59], 0, v[138:139]
	s_add_i32 m0, s41, 0xc000
	ds_read_b128 v[196:199], v179
	ds_read_b128 v[200:203], v179 offset:1024
	ds_read_b128 v[204:207], v179 offset:2048
	ds_read_b128 v[208:211], v179 offset:3072
	ds_read_b128 v[212:215], v179 offset:4096
	ds_read_b128 v[222:225], v179 offset:5120
	ds_read_b128 v[226:229], v179 offset:6144
	ds_read_b128 v[230:233], v179 offset:7168
	global_load_lds_dwordx4 v[172:173], off
	v_lshl_add_u64 v[172:173], s[58:59], 0, v[136:137]
	s_add_i32 m0, s41, 0xe000
	s_nop 0
	global_load_lds_dwordx4 v[172:173], off
	s_waitcnt vmcnt(8)
	s_waitcnt lgkmcnt(0)
	s_barrier
	s_setprio 1
	v_mfma_f32_16x16x32_bf16 v[126:129], v[140:143], v[196:199], v[126:129]
	v_mfma_f32_16x16x32_bf16 v[86:89], v[148:151], v[196:199], v[86:89]
	v_mfma_f32_16x16x32_bf16 v[118:121], v[140:143], v[204:207], v[118:121]
	v_mfma_f32_16x16x32_bf16 v[94:97], v[148:151], v[204:207], v[94:97]
	v_mfma_f32_16x16x32_bf16 v[106:109], v[140:143], v[212:215], v[106:109]
	v_mfma_f32_16x16x32_bf16 v[102:105], v[148:151], v[212:215], v[102:105]
	v_mfma_f32_16x16x32_bf16 v[78:81], v[140:143], v[226:229], v[78:81]
	v_mfma_f32_16x16x32_bf16 v[74:77], v[148:151], v[226:229], v[74:77]
	v_mfma_f32_16x16x32_bf16 v[126:129], v[144:147], v[200:203], v[126:129]
	v_mfma_f32_16x16x32_bf16 v[86:89], v[152:155], v[200:203], v[86:89]
	v_mfma_f32_16x16x32_bf16 v[118:121], v[144:147], v[208:211], v[118:121]
	v_mfma_f32_16x16x32_bf16 v[94:97], v[152:155], v[208:211], v[94:97]
	v_mfma_f32_16x16x32_bf16 v[106:109], v[144:147], v[222:225], v[106:109]
	v_mfma_f32_16x16x32_bf16 v[102:105], v[152:155], v[222:225], v[102:105]
	v_mfma_f32_16x16x32_bf16 v[78:81], v[144:147], v[230:233], v[78:81]
	v_mfma_f32_16x16x32_bf16 v[74:77], v[152:155], v[230:233], v[74:77]
	v_mfma_f32_16x16x32_bf16 v[122:125], v[180:183], v[196:199], v[122:125]
	v_mfma_f32_16x16x32_bf16 v[98:101], v[188:191], v[196:199], v[98:101]
	v_mfma_f32_16x16x32_bf16 v[114:117], v[180:183], v[204:207], v[114:117]
	v_mfma_f32_16x16x32_bf16 v[110:113], v[188:191], v[204:207], v[110:113]
	v_mfma_f32_16x16x32_bf16 v[90:93], v[180:183], v[212:215], v[90:93]
	v_mfma_f32_16x16x32_bf16 v[82:85], v[188:191], v[212:215], v[82:85]
	v_mfma_f32_16x16x32_bf16 v[70:73], v[180:183], v[226:229], v[70:73]
	v_mfma_f32_16x16x32_bf16 v[66:69], v[188:191], v[226:229], v[66:69]
	v_mfma_f32_16x16x32_bf16 v[122:125], v[184:187], v[200:203], v[122:125]
	v_mfma_f32_16x16x32_bf16 v[98:101], v[192:195], v[200:203], v[98:101]
	v_mfma_f32_16x16x32_bf16 v[114:117], v[184:187], v[208:211], v[114:117]
	v_mfma_f32_16x16x32_bf16 v[110:113], v[192:195], v[208:211], v[110:113]
	v_mfma_f32_16x16x32_bf16 v[90:93], v[184:187], v[222:225], v[90:93]
	v_mfma_f32_16x16x32_bf16 v[82:85], v[192:195], v[222:225], v[82:85]
	v_mfma_f32_16x16x32_bf16 v[70:73], v[184:187], v[230:233], v[70:73]
	v_mfma_f32_16x16x32_bf16 v[66:69], v[192:195], v[230:233], v[66:69]
	s_setprio 0
	s_barrier
	s_add_i32 s36, s38, s72
	v_lshl_add_u64 v[172:173], s[60:61], 0, v[162:163]
	s_mov_b32 m0, s36
	ds_read_b128 v[196:199], v179 offset:16384
	ds_read_b128 v[200:203], v179 offset:17408
	ds_read_b128 v[204:207], v179 offset:18432
	ds_read_b128 v[208:211], v179 offset:19456
	ds_read_b128 v[212:215], v179 offset:20480
	ds_read_b128 v[222:225], v179 offset:21504
	ds_read_b128 v[226:229], v179 offset:22528
	ds_read_b128 v[230:233], v179 offset:23552
	global_load_lds_dwordx4 v[172:173], off
	s_add_i32 m0, s36, 0x2000
	s_add_u32 s36, s60, 0x80000
	v_lshl_add_u64 v[216:217], s[60:61], 0, v[134:135]
	s_addc_u32 s37, s61, 0
	s_add_i32 s38, s39, s72
	global_load_lds_dwordx4 v[216:217], off
	v_lshl_add_u64 v[234:235], s[36:37], 0, v[162:163]
	s_mov_b32 m0, s38
	v_lshl_add_u64 v[236:237], s[62:63], 0, v[132:133]
	global_load_lds_dwordx4 v[234:235], off
	v_lshl_add_u64 v[234:235], s[36:37], 0, v[134:135]
	s_add_i32 m0, s38, 0x2000
	s_nop 0
	global_load_lds_dwordx4 v[234:235], off
	v_lshl_add_u64 v[234:235], s[62:63], 0, v[130:131]
	s_mov_b32 m0, s41
	s_nop 0
	global_load_lds_dwordx4 v[234:235], off
	s_mov_b32 m0, s66
	s_nop 0
	global_load_lds_dwordx4 v[236:237], off
	s_waitcnt vmcnt(8)
	s_waitcnt lgkmcnt(0)
	s_barrier
	s_setprio 1
	v_mfma_f32_16x16x32_bf16 v[62:65], v[140:143], v[196:199], v[62:65]
	v_mfma_f32_16x16x32_bf16 v[58:61], v[148:151], v[196:199], v[58:61]
	v_mfma_f32_16x16x32_bf16 v[46:49], v[140:143], v[204:207], v[46:49]
	v_mfma_f32_16x16x32_bf16 v[42:45], v[148:151], v[204:207], v[42:45]
	v_mfma_f32_16x16x32_bf16 v[30:33], v[140:143], v[212:215], v[30:33]
	v_mfma_f32_16x16x32_bf16 v[26:29], v[148:151], v[212:215], v[26:29]
	v_mfma_f32_16x16x32_bf16 v[14:17], v[140:143], v[226:229], v[14:17]
	v_mfma_f32_16x16x32_bf16 v[10:13], v[148:151], v[226:229], v[10:13]
	v_mfma_f32_16x16x32_bf16 v[62:65], v[144:147], v[200:203], v[62:65]
	v_mfma_f32_16x16x32_bf16 v[58:61], v[152:155], v[200:203], v[58:61]
	v_mfma_f32_16x16x32_bf16 v[46:49], v[144:147], v[208:211], v[46:49]
	v_mfma_f32_16x16x32_bf16 v[42:45], v[152:155], v[208:211], v[42:45]
	v_mfma_f32_16x16x32_bf16 v[30:33], v[144:147], v[222:225], v[30:33]
	v_mfma_f32_16x16x32_bf16 v[26:29], v[152:155], v[222:225], v[26:29]
	v_mfma_f32_16x16x32_bf16 v[14:17], v[144:147], v[230:233], v[14:17]
	v_mfma_f32_16x16x32_bf16 v[10:13], v[152:155], v[230:233], v[10:13]
	v_mfma_f32_16x16x32_bf16 v[54:57], v[180:183], v[196:199], v[54:57]
	v_mfma_f32_16x16x32_bf16 v[50:53], v[188:191], v[196:199], v[50:53]
	v_mfma_f32_16x16x32_bf16 v[38:41], v[180:183], v[204:207], v[38:41]
	v_mfma_f32_16x16x32_bf16 v[34:37], v[188:191], v[204:207], v[34:37]
	v_mfma_f32_16x16x32_bf16 v[22:25], v[180:183], v[212:215], v[22:25]
	v_mfma_f32_16x16x32_bf16 v[18:21], v[188:191], v[212:215], v[18:21]
	v_mfma_f32_16x16x32_bf16 v[6:9], v[180:183], v[226:229], v[6:9]
	v_mfma_f32_16x16x32_bf16 v[2:5], v[188:191], v[226:229], v[2:5]
	v_mfma_f32_16x16x32_bf16 v[54:57], v[184:187], v[200:203], v[54:57]
	v_mfma_f32_16x16x32_bf16 v[50:53], v[192:195], v[200:203], v[50:53]
	v_mfma_f32_16x16x32_bf16 v[38:41], v[184:187], v[208:211], v[38:41]
	v_mfma_f32_16x16x32_bf16 v[34:37], v[192:195], v[208:211], v[34:37]
	v_mfma_f32_16x16x32_bf16 v[22:25], v[184:187], v[222:225], v[22:25]
	v_mfma_f32_16x16x32_bf16 v[18:21], v[192:195], v[222:225], v[18:21]
	v_mfma_f32_16x16x32_bf16 v[6:9], v[184:187], v[230:233], v[6:9]
	v_mfma_f32_16x16x32_bf16 v[2:5], v[192:195], v[230:233], v[2:5]
	s_setprio 0
	s_barrier
	s_add_i32 s38, 0, 0x18000
	s_add_i32 s39, 0, 0x1c000
	v_add_u32_e32 v152, s38, v161
	v_add_u32_e32 v156, s39, v161
	ds_read_b128 v[140:143], v152
	ds_read_b128 v[144:147], v152 offset:1024
	ds_read_b128 v[148:151], v152 offset:2048
	ds_read_b128 v[152:155], v152 offset:3072
	ds_read_b128 v[180:183], v156
	ds_read_b128 v[184:187], v156 offset:1024
	ds_read_b128 v[188:191], v156 offset:2048
	ds_read_b128 v[192:195], v156 offset:3072
	s_add_u32 s36, s62, 0x80000
	s_addc_u32 s37, s63, 0
	s_mov_b32 m0, s74
	v_lshl_add_u64 v[238:239], s[36:37], 0, v[130:131]
	ds_read_b128 v[196:199], v179 offset:32768
	ds_read_b128 v[200:203], v179 offset:33792
	ds_read_b128 v[204:207], v179 offset:34816
	ds_read_b128 v[208:211], v179 offset:35840
	ds_read_b128 v[212:215], v179 offset:36864
	ds_read_b128 v[222:225], v179 offset:37888
	ds_read_b128 v[226:229], v179 offset:38912
	ds_read_b128 v[230:233], v179 offset:39936
	global_load_lds_dwordx4 v[238:239], off
	v_lshl_add_u64 v[238:239], s[36:37], 0, v[132:133]
	s_mov_b32 m0, s75
	s_nop 0
	global_load_lds_dwordx4 v[238:239], off
	s_waitcnt vmcnt(8)
	s_waitcnt lgkmcnt(0)
	s_barrier
	s_setprio 1
	v_mfma_f32_16x16x32_bf16 v[126:129], v[140:143], v[196:199], v[126:129]
	v_mfma_f32_16x16x32_bf16 v[86:89], v[148:151], v[196:199], v[86:89]
	v_mfma_f32_16x16x32_bf16 v[118:121], v[140:143], v[204:207], v[118:121]
	v_mfma_f32_16x16x32_bf16 v[94:97], v[148:151], v[204:207], v[94:97]
	v_mfma_f32_16x16x32_bf16 v[106:109], v[140:143], v[212:215], v[106:109]
	v_mfma_f32_16x16x32_bf16 v[102:105], v[148:151], v[212:215], v[102:105]
	v_mfma_f32_16x16x32_bf16 v[78:81], v[140:143], v[226:229], v[78:81]
	v_mfma_f32_16x16x32_bf16 v[74:77], v[148:151], v[226:229], v[74:77]
	v_mfma_f32_16x16x32_bf16 v[126:129], v[144:147], v[200:203], v[126:129]
	v_mfma_f32_16x16x32_bf16 v[86:89], v[152:155], v[200:203], v[86:89]
	v_mfma_f32_16x16x32_bf16 v[118:121], v[144:147], v[208:211], v[118:121]
	v_mfma_f32_16x16x32_bf16 v[94:97], v[152:155], v[208:211], v[94:97]
	v_mfma_f32_16x16x32_bf16 v[106:109], v[144:147], v[222:225], v[106:109]
	v_mfma_f32_16x16x32_bf16 v[102:105], v[152:155], v[222:225], v[102:105]
	v_mfma_f32_16x16x32_bf16 v[78:81], v[144:147], v[230:233], v[78:81]
	v_mfma_f32_16x16x32_bf16 v[74:77], v[152:155], v[230:233], v[74:77]
	v_mfma_f32_16x16x32_bf16 v[122:125], v[180:183], v[196:199], v[122:125]
	v_mfma_f32_16x16x32_bf16 v[98:101], v[188:191], v[196:199], v[98:101]
	v_mfma_f32_16x16x32_bf16 v[114:117], v[180:183], v[204:207], v[114:117]
	v_mfma_f32_16x16x32_bf16 v[110:113], v[188:191], v[204:207], v[110:113]
	v_mfma_f32_16x16x32_bf16 v[90:93], v[180:183], v[212:215], v[90:93]
	v_mfma_f32_16x16x32_bf16 v[82:85], v[188:191], v[212:215], v[82:85]
	v_mfma_f32_16x16x32_bf16 v[70:73], v[180:183], v[226:229], v[70:73]
	v_mfma_f32_16x16x32_bf16 v[66:69], v[188:191], v[226:229], v[66:69]
	v_mfma_f32_16x16x32_bf16 v[122:125], v[184:187], v[200:203], v[122:125]
	v_mfma_f32_16x16x32_bf16 v[98:101], v[192:195], v[200:203], v[98:101]
	v_mfma_f32_16x16x32_bf16 v[114:117], v[184:187], v[208:211], v[114:117]
	v_mfma_f32_16x16x32_bf16 v[110:113], v[192:195], v[208:211], v[110:113]
	v_mfma_f32_16x16x32_bf16 v[90:93], v[184:187], v[222:225], v[90:93]
	v_mfma_f32_16x16x32_bf16 v[82:85], v[192:195], v[222:225], v[82:85]
	v_mfma_f32_16x16x32_bf16 v[70:73], v[184:187], v[230:233], v[70:73]
	v_mfma_f32_16x16x32_bf16 v[66:69], v[192:195], v[230:233], v[66:69]
	s_setprio 0
	s_barrier
	s_add_i32 s36, s38, s72
	v_lshl_add_u64 v[172:173], v[172:173], 0, s[44:45]
	s_mov_b32 m0, s36
	ds_read_b128 v[196:199], v179 offset:49152
	ds_read_b128 v[200:203], v179 offset:50176
	ds_read_b128 v[204:207], v179 offset:51200
	ds_read_b128 v[208:211], v179 offset:52224
	ds_read_b128 v[212:215], v179 offset:53248
	ds_read_b128 v[222:225], v179 offset:54272
	ds_read_b128 v[226:229], v179 offset:55296
	ds_read_b128 v[230:233], v179 offset:56320
	global_load_lds_dwordx4 v[172:173], off
	s_add_i32 m0, s36, 0x2000
	s_add_u32 s36, s60, 0x80080
	v_lshl_add_u64 v[172:173], v[216:217], 0, s[44:45]
	s_addc_u32 s37, s61, 0
	s_add_i32 s38, s39, s72
	global_load_lds_dwordx4 v[172:173], off
	v_lshl_add_u64 v[172:173], s[36:37], 0, v[162:163]
	s_mov_b32 m0, s38
	s_nop 0
	global_load_lds_dwordx4 v[172:173], off
	v_lshl_add_u64 v[172:173], s[36:37], 0, v[134:135]
	s_add_i32 m0, s38, 0x2000
	s_nop 0
	global_load_lds_dwordx4 v[172:173], off
	v_lshl_add_u64 v[172:173], v[234:235], 0, s[44:45]
	s_mov_b32 m0, s76
	s_nop 0
	global_load_lds_dwordx4 v[172:173], off
	v_lshl_add_u64 v[172:173], v[236:237], 0, s[44:45]
	s_mov_b32 m0, s77
	s_nop 0
	global_load_lds_dwordx4 v[172:173], off
	s_waitcnt vmcnt(8)
	s_waitcnt lgkmcnt(0)
	s_barrier
	s_setprio 1
	v_mfma_f32_16x16x32_bf16 v[62:65], v[140:143], v[196:199], v[62:65]
	v_mfma_f32_16x16x32_bf16 v[58:61], v[148:151], v[196:199], v[58:61]
	v_mfma_f32_16x16x32_bf16 v[46:49], v[140:143], v[204:207], v[46:49]
	v_mfma_f32_16x16x32_bf16 v[42:45], v[148:151], v[204:207], v[42:45]
	v_mfma_f32_16x16x32_bf16 v[30:33], v[140:143], v[212:215], v[30:33]
	v_mfma_f32_16x16x32_bf16 v[26:29], v[148:151], v[212:215], v[26:29]
	v_mfma_f32_16x16x32_bf16 v[14:17], v[140:143], v[226:229], v[14:17]
	v_mfma_f32_16x16x32_bf16 v[10:13], v[148:151], v[226:229], v[10:13]
	v_mfma_f32_16x16x32_bf16 v[62:65], v[144:147], v[200:203], v[62:65]
	v_mfma_f32_16x16x32_bf16 v[58:61], v[152:155], v[200:203], v[58:61]
	v_mfma_f32_16x16x32_bf16 v[46:49], v[144:147], v[208:211], v[46:49]
	v_mfma_f32_16x16x32_bf16 v[42:45], v[152:155], v[208:211], v[42:45]
	v_mfma_f32_16x16x32_bf16 v[30:33], v[144:147], v[222:225], v[30:33]
	v_mfma_f32_16x16x32_bf16 v[26:29], v[152:155], v[222:225], v[26:29]
	v_mfma_f32_16x16x32_bf16 v[14:17], v[144:147], v[230:233], v[14:17]
	v_mfma_f32_16x16x32_bf16 v[10:13], v[152:155], v[230:233], v[10:13]
	v_mfma_f32_16x16x32_bf16 v[54:57], v[180:183], v[196:199], v[54:57]
	v_mfma_f32_16x16x32_bf16 v[50:53], v[188:191], v[196:199], v[50:53]
	v_mfma_f32_16x16x32_bf16 v[38:41], v[180:183], v[204:207], v[38:41]
	v_mfma_f32_16x16x32_bf16 v[34:37], v[188:191], v[204:207], v[34:37]
	v_mfma_f32_16x16x32_bf16 v[22:25], v[180:183], v[212:215], v[22:25]
	v_mfma_f32_16x16x32_bf16 v[18:21], v[188:191], v[212:215], v[18:21]
	v_mfma_f32_16x16x32_bf16 v[6:9], v[180:183], v[226:229], v[6:9]
	v_mfma_f32_16x16x32_bf16 v[2:5], v[188:191], v[226:229], v[2:5]
	v_mfma_f32_16x16x32_bf16 v[54:57], v[184:187], v[200:203], v[54:57]
	v_mfma_f32_16x16x32_bf16 v[50:53], v[192:195], v[200:203], v[50:53]
	v_mfma_f32_16x16x32_bf16 v[38:41], v[184:187], v[208:211], v[38:41]
	v_mfma_f32_16x16x32_bf16 v[34:37], v[192:195], v[208:211], v[34:37]
	v_mfma_f32_16x16x32_bf16 v[22:25], v[184:187], v[222:225], v[22:25]
	v_mfma_f32_16x16x32_bf16 v[18:21], v[192:195], v[222:225], v[18:21]
	v_mfma_f32_16x16x32_bf16 v[6:9], v[184:187], v[230:233], v[6:9]
	v_mfma_f32_16x16x32_bf16 v[2:5], v[192:195], v[230:233], v[2:5]
	s_setprio 0
	s_barrier
	s_add_i32 s64, s64, 2
	s_add_u32 s21, s21, 0x100
	s_addc_u32 s57, s57, 0
	s_add_u32 s58, s58, 0x100
	s_addc_u32 s59, s59, 0
	s_cmp_gt_u32 s64, 29
	s_cbranch_scc0 .LBB0_643
	s_and_b64 vcc, exec, s[16:17]
	s_cbranch_vccz .LBB0_646
	s_barrier

.LBB0_696:
	s_add_u32 s36, s26, 0xfffc0080
	s_addc_u32 s37, s27, -1
	s_add_i32 s38, 0, 0x10000
	s_cmp_eq_u32 s60, 12
	s_cselect_b32 s59, s19, s37
	s_cselect_b32 s58, s18, s36
	v_add_u32_e32 v140, s38, v149
	s_cselect_b32 s57, s21, s17
	s_cselect_b32 s56, s20, s15
	s_add_i32 s39, 0, 0x14000
	ds_read_b128 v[156:159], v140
	ds_read_b128 v[172:175], v140 offset:1024
	ds_read_b128 v[190:193], v140 offset:2048
	ds_read_b128 v[194:197], v140 offset:3072
	v_add_u32_e32 v140, s39, v149
	ds_read_b128 v[198:201], v140
	ds_read_b128 v[202:205], v140 offset:1024
	ds_read_b128 v[206:209], v140 offset:2048
	ds_read_b128 v[210:213], v140 offset:3072
	v_lshl_add_u64 v[160:161], s[26:27], 0, v[138:139]
	s_add_i32 m0, s25, 0xc000
	ds_read_b128 v[214:217], v189
	ds_read_b128 v[222:225], v189 offset:1024
	ds_read_b128 v[226:229], v189 offset:2048
	ds_read_b128 v[230:233], v189 offset:3072
	ds_read_b128 v[234:237], v189 offset:4096
	ds_read_b128 v[238:241], v189 offset:5120
	ds_read_b128 v[242:245], v189 offset:6144
	ds_read_b128 v[246:249], v189 offset:7168
	global_load_lds_dwordx4 v[160:161], off
	v_lshl_add_u64 v[160:161], s[26:27], 0, v[136:137]
	s_add_i32 m0, s25, 0xe000
	s_nop 0
	global_load_lds_dwordx4 v[160:161], off
	s_waitcnt vmcnt(8)
	s_waitcnt lgkmcnt(0)
	s_barrier
	s_setprio 1
	v_mfma_i32_16x16x64_i8 v[126:129], v[156:159], v[214:217], v[126:129]
	v_mfma_i32_16x16x64_i8 v[122:125], v[190:193], v[214:217], v[122:125]
	v_mfma_i32_16x16x64_i8 v[118:121], v[156:159], v[226:229], v[118:121]
	v_mfma_i32_16x16x64_i8 v[114:117], v[190:193], v[226:229], v[114:117]
	v_mfma_i32_16x16x64_i8 v[110:113], v[156:159], v[234:237], v[110:113]
	v_mfma_i32_16x16x64_i8 v[106:109], v[190:193], v[234:237], v[106:109]
	v_mfma_i32_16x16x64_i8 v[102:105], v[156:159], v[242:245], v[102:105]
	v_mfma_i32_16x16x64_i8 v[98:101], v[190:193], v[242:245], v[98:101]
	v_mfma_i32_16x16x64_i8 v[126:129], v[172:175], v[222:225], v[126:129]
	v_mfma_i32_16x16x64_i8 v[122:125], v[194:197], v[222:225], v[122:125]
	v_mfma_i32_16x16x64_i8 v[118:121], v[172:175], v[230:233], v[118:121]
	v_mfma_i32_16x16x64_i8 v[114:117], v[194:197], v[230:233], v[114:117]
	v_mfma_i32_16x16x64_i8 v[110:113], v[172:175], v[238:241], v[110:113]
	v_mfma_i32_16x16x64_i8 v[106:109], v[194:197], v[238:241], v[106:109]
	v_mfma_i32_16x16x64_i8 v[102:105], v[172:175], v[246:249], v[102:105]
	v_mfma_i32_16x16x64_i8 v[98:101], v[194:197], v[246:249], v[98:101]
	v_mfma_i32_16x16x64_i8 v[62:65], v[198:201], v[214:217], v[62:65]
	v_mfma_i32_16x16x64_i8 v[58:61], v[206:209], v[214:217], v[58:61]
	v_mfma_i32_16x16x64_i8 v[54:57], v[198:201], v[226:229], v[54:57]
	v_mfma_i32_16x16x64_i8 v[50:53], v[206:209], v[226:229], v[50:53]
	v_mfma_i32_16x16x64_i8 v[46:49], v[198:201], v[234:237], v[46:49]
	v_mfma_i32_16x16x64_i8 v[42:45], v[206:209], v[234:237], v[42:45]
	v_mfma_i32_16x16x64_i8 v[38:41], v[198:201], v[242:245], v[38:41]
	v_mfma_i32_16x16x64_i8 v[34:37], v[206:209], v[242:245], v[34:37]
	v_mfma_i32_16x16x64_i8 v[62:65], v[202:205], v[222:225], v[62:65]
	v_mfma_i32_16x16x64_i8 v[58:61], v[210:213], v[222:225], v[58:61]
	v_mfma_i32_16x16x64_i8 v[54:57], v[202:205], v[230:233], v[54:57]
	v_mfma_i32_16x16x64_i8 v[50:53], v[210:213], v[230:233], v[50:53]
	v_mfma_i32_16x16x64_i8 v[46:49], v[202:205], v[238:241], v[46:49]
	v_mfma_i32_16x16x64_i8 v[42:45], v[210:213], v[238:241], v[42:45]
	v_mfma_i32_16x16x64_i8 v[38:41], v[202:205], v[246:249], v[38:41]
	v_mfma_i32_16x16x64_i8 v[34:37], v[210:213], v[246:249], v[34:37]
	s_setprio 0
	s_barrier
	s_add_i32 s36, s38, s23
	v_lshl_add_u64 v[160:161], s[56:57], 0, v[162:163]
	s_mov_b32 m0, s36
	ds_read_b128 v[214:217], v189 offset:16384
	ds_read_b128 v[222:225], v189 offset:17408
	ds_read_b128 v[226:229], v189 offset:18432
	ds_read_b128 v[230:233], v189 offset:19456
	ds_read_b128 v[234:237], v189 offset:20480
	ds_read_b128 v[238:241], v189 offset:21504
	ds_read_b128 v[242:245], v189 offset:22528
	ds_read_b128 v[246:249], v189 offset:23552
	global_load_lds_dwordx4 v[160:161], off
	s_add_i32 m0, s36, 0x2000
	s_add_u32 s36, s56, 0x80000
	v_lshl_add_u64 v[250:251], s[56:57], 0, v[134:135]
	s_addc_u32 s37, s57, 0
	s_add_i32 s38, s39, s23
	global_load_lds_dwordx4 v[250:251], off
	v_lshl_add_u64 v[252:253], s[36:37], 0, v[162:163]
	s_mov_b32 m0, s38
	v_lshl_add_u64 v[168:169], s[58:59], 0, v[132:133]
	global_load_lds_dwordx4 v[252:253], off
	v_lshl_add_u64 v[252:253], s[36:37], 0, v[134:135]
	s_add_i32 m0, s38, 0x2000
	s_nop 0
	global_load_lds_dwordx4 v[252:253], off
	v_lshl_add_u64 v[252:253], s[58:59], 0, v[130:131]
	s_mov_b32 m0, s25
	s_nop 0
	global_load_lds_dwordx4 v[252:253], off
	s_mov_b32 m0, s67
	s_nop 0
	global_load_lds_dwordx4 v[168:169], off
	s_waitcnt vmcnt(8)
	s_waitcnt lgkmcnt(0)
	s_barrier
	s_setprio 1
	v_mfma_i32_16x16x64_i8 v[94:97], v[156:159], v[214:217], v[94:97]
	v_mfma_i32_16x16x64_i8 v[90:93], v[190:193], v[214:217], v[90:93]
	v_mfma_i32_16x16x64_i8 v[86:89], v[156:159], v[226:229], v[86:89]
	v_mfma_i32_16x16x64_i8 v[82:85], v[190:193], v[226:229], v[82:85]
	v_mfma_i32_16x16x64_i8 v[78:81], v[156:159], v[234:237], v[78:81]
	v_mfma_i32_16x16x64_i8 v[74:77], v[190:193], v[234:237], v[74:77]
	v_mfma_i32_16x16x64_i8 v[70:73], v[156:159], v[242:245], v[70:73]
	v_mfma_i32_16x16x64_i8 v[66:69], v[190:193], v[242:245], v[66:69]
	v_mfma_i32_16x16x64_i8 v[94:97], v[172:175], v[222:225], v[94:97]
	v_mfma_i32_16x16x64_i8 v[90:93], v[194:197], v[222:225], v[90:93]
	v_mfma_i32_16x16x64_i8 v[86:89], v[172:175], v[230:233], v[86:89]
	v_mfma_i32_16x16x64_i8 v[82:85], v[194:197], v[230:233], v[82:85]
	v_mfma_i32_16x16x64_i8 v[78:81], v[172:175], v[238:241], v[78:81]
	v_mfma_i32_16x16x64_i8 v[74:77], v[194:197], v[238:241], v[74:77]
	v_mfma_i32_16x16x64_i8 v[70:73], v[172:175], v[246:249], v[70:73]
	v_mfma_i32_16x16x64_i8 v[66:69], v[194:197], v[246:249], v[66:69]
	v_mfma_i32_16x16x64_i8 v[30:33], v[198:201], v[214:217], v[30:33]
	v_mfma_i32_16x16x64_i8 v[26:29], v[206:209], v[214:217], v[26:29]
	v_mfma_i32_16x16x64_i8 v[22:25], v[198:201], v[226:229], v[22:25]
	v_mfma_i32_16x16x64_i8 v[18:21], v[206:209], v[226:229], v[18:21]
	v_mfma_i32_16x16x64_i8 v[14:17], v[198:201], v[234:237], v[14:17]
	v_mfma_i32_16x16x64_i8 v[10:13], v[206:209], v[234:237], v[10:13]
	v_mfma_i32_16x16x64_i8 v[6:9], v[198:201], v[242:245], v[6:9]
	v_mfma_i32_16x16x64_i8 v[2:5], v[206:209], v[242:245], v[2:5]
	v_mfma_i32_16x16x64_i8 v[30:33], v[202:205], v[222:225], v[30:33]
	v_mfma_i32_16x16x64_i8 v[26:29], v[210:213], v[222:225], v[26:29]
	v_mfma_i32_16x16x64_i8 v[22:25], v[202:205], v[230:233], v[22:25]
	v_mfma_i32_16x16x64_i8 v[18:21], v[210:213], v[230:233], v[18:21]
	v_mfma_i32_16x16x64_i8 v[14:17], v[202:205], v[238:241], v[14:17]
	v_mfma_i32_16x16x64_i8 v[10:13], v[210:213], v[238:241], v[10:13]
	v_mfma_i32_16x16x64_i8 v[6:9], v[202:205], v[246:249], v[6:9]
	v_mfma_i32_16x16x64_i8 v[2:5], v[210:213], v[246:249], v[2:5]
	s_setprio 0
	s_barrier
	s_add_i32 s38, 0, 0x18000
	v_add_u32_e32 v140, s38, v149
	s_add_i32 s39, 0, 0x1c000
	ds_read_b128 v[156:159], v140
	ds_read_b128 v[172:175], v140 offset:1024
	ds_read_b128 v[190:193], v140 offset:2048
	ds_read_b128 v[194:197], v140 offset:3072
	v_add_u32_e32 v140, s39, v149
	ds_read_b128 v[198:201], v140
	ds_read_b128 v[202:205], v140 offset:1024
	ds_read_b128 v[206:209], v140 offset:2048
	ds_read_b128 v[210:213], v140 offset:3072
	s_add_u32 s36, s58, 0x40000
	s_addc_u32 s37, s59, 0
	s_mov_b32 m0, s68
	v_lshl_add_u64 v[170:171], s[36:37], 0, v[130:131]
	ds_read_b128 v[214:217], v189 offset:32768
	ds_read_b128 v[222:225], v189 offset:33792
	ds_read_b128 v[226:229], v189 offset:34816
	ds_read_b128 v[230:233], v189 offset:35840
	ds_read_b128 v[234:237], v189 offset:36864
	ds_read_b128 v[238:241], v189 offset:37888
	ds_read_b128 v[242:245], v189 offset:38912
	ds_read_b128 v[246:249], v189 offset:39936
	global_load_lds_dwordx4 v[170:171], off
	v_lshl_add_u64 v[170:171], s[36:37], 0, v[132:133]
	s_mov_b32 m0, s69
	s_nop 0
	global_load_lds_dwordx4 v[170:171], off
	s_waitcnt vmcnt(8)
	s_waitcnt lgkmcnt(0)
	s_barrier
	s_setprio 1
	v_mfma_i32_16x16x64_i8 v[126:129], v[156:159], v[214:217], v[126:129]
	v_mfma_i32_16x16x64_i8 v[122:125], v[190:193], v[214:217], v[122:125]
	v_mfma_i32_16x16x64_i8 v[118:121], v[156:159], v[226:229], v[118:121]
	v_mfma_i32_16x16x64_i8 v[114:117], v[190:193], v[226:229], v[114:117]
	v_mfma_i32_16x16x64_i8 v[110:113], v[156:159], v[234:237], v[110:113]
	v_mfma_i32_16x16x64_i8 v[106:109], v[190:193], v[234:237], v[106:109]
	v_mfma_i32_16x16x64_i8 v[102:105], v[156:159], v[242:245], v[102:105]
	v_mfma_i32_16x16x64_i8 v[98:101], v[190:193], v[242:245], v[98:101]
	v_mfma_i32_16x16x64_i8 v[126:129], v[172:175], v[222:225], v[126:129]
	v_mfma_i32_16x16x64_i8 v[122:125], v[194:197], v[222:225], v[122:125]
	v_mfma_i32_16x16x64_i8 v[118:121], v[172:175], v[230:233], v[118:121]
	v_mfma_i32_16x16x64_i8 v[114:117], v[194:197], v[230:233], v[114:117]
	v_mfma_i32_16x16x64_i8 v[110:113], v[172:175], v[238:241], v[110:113]
	v_mfma_i32_16x16x64_i8 v[106:109], v[194:197], v[238:241], v[106:109]
	v_mfma_i32_16x16x64_i8 v[102:105], v[172:175], v[246:249], v[102:105]
	v_mfma_i32_16x16x64_i8 v[98:101], v[194:197], v[246:249], v[98:101]
	v_mfma_i32_16x16x64_i8 v[62:65], v[198:201], v[214:217], v[62:65]
	v_mfma_i32_16x16x64_i8 v[58:61], v[206:209], v[214:217], v[58:61]
	v_mfma_i32_16x16x64_i8 v[54:57], v[198:201], v[226:229], v[54:57]
	v_mfma_i32_16x16x64_i8 v[50:53], v[206:209], v[226:229], v[50:53]
	v_mfma_i32_16x16x64_i8 v[46:49], v[198:201], v[234:237], v[46:49]
	v_mfma_i32_16x16x64_i8 v[42:45], v[206:209], v[234:237], v[42:45]
	v_mfma_i32_16x16x64_i8 v[38:41], v[198:201], v[242:245], v[38:41]
	v_mfma_i32_16x16x64_i8 v[34:37], v[206:209], v[242:245], v[34:37]
	v_mfma_i32_16x16x64_i8 v[62:65], v[202:205], v[222:225], v[62:65]
	v_mfma_i32_16x16x64_i8 v[58:61], v[210:213], v[222:225], v[58:61]
	v_mfma_i32_16x16x64_i8 v[54:57], v[202:205], v[230:233], v[54:57]
	v_mfma_i32_16x16x64_i8 v[50:53], v[210:213], v[230:233], v[50:53]
	v_mfma_i32_16x16x64_i8 v[46:49], v[202:205], v[238:241], v[46:49]
	v_mfma_i32_16x16x64_i8 v[42:45], v[210:213], v[238:241], v[42:45]
	v_mfma_i32_16x16x64_i8 v[38:41], v[202:205], v[246:249], v[38:41]
	v_mfma_i32_16x16x64_i8 v[34:37], v[210:213], v[246:249], v[34:37]
	s_setprio 0
	s_barrier
	s_add_i32 s36, s38, s23
	v_lshl_add_u64 v[160:161], v[160:161], 0, s[44:45]
	s_mov_b32 m0, s36
	ds_read_b128 v[214:217], v189 offset:49152
	ds_read_b128 v[222:225], v189 offset:50176
	ds_read_b128 v[226:229], v189 offset:51200
	ds_read_b128 v[230:233], v189 offset:52224
	ds_read_b128 v[234:237], v189 offset:53248
	ds_read_b128 v[238:241], v189 offset:54272
	ds_read_b128 v[242:245], v189 offset:55296
	ds_read_b128 v[246:249], v189 offset:56320
	global_load_lds_dwordx4 v[160:161], off
	s_add_i32 m0, s36, 0x2000
	s_add_u32 s36, s56, 0x80080
	v_lshl_add_u64 v[160:161], v[250:251], 0, s[44:45]
	s_addc_u32 s37, s57, 0
	s_add_i32 s38, s39, s23
	global_load_lds_dwordx4 v[160:161], off
	v_lshl_add_u64 v[160:161], s[36:37], 0, v[162:163]
	s_mov_b32 m0, s38
	s_nop 0
	global_load_lds_dwordx4 v[160:161], off
	v_lshl_add_u64 v[160:161], s[36:37], 0, v[134:135]
	s_add_i32 m0, s38, 0x2000
	s_nop 0
	global_load_lds_dwordx4 v[160:161], off
	v_lshl_add_u64 v[160:161], v[252:253], 0, s[44:45]
	s_mov_b32 m0, s71
	s_nop 0
	global_load_lds_dwordx4 v[160:161], off
	v_lshl_add_u64 v[160:161], v[168:169], 0, s[44:45]
	s_mov_b32 m0, s72
	s_nop 0
	global_load_lds_dwordx4 v[160:161], off
	s_waitcnt vmcnt(8)
	s_waitcnt lgkmcnt(0)
	s_barrier
	s_setprio 1
	v_mfma_i32_16x16x64_i8 v[94:97], v[156:159], v[214:217], v[94:97]
	v_mfma_i32_16x16x64_i8 v[90:93], v[190:193], v[214:217], v[90:93]
	v_mfma_i32_16x16x64_i8 v[86:89], v[156:159], v[226:229], v[86:89]
	v_mfma_i32_16x16x64_i8 v[82:85], v[190:193], v[226:229], v[82:85]
	v_mfma_i32_16x16x64_i8 v[78:81], v[156:159], v[234:237], v[78:81]
	v_mfma_i32_16x16x64_i8 v[74:77], v[190:193], v[234:237], v[74:77]
	v_mfma_i32_16x16x64_i8 v[70:73], v[156:159], v[242:245], v[70:73]
	v_mfma_i32_16x16x64_i8 v[66:69], v[190:193], v[242:245], v[66:69]
	v_mfma_i32_16x16x64_i8 v[94:97], v[172:175], v[222:225], v[94:97]
	v_mfma_i32_16x16x64_i8 v[90:93], v[194:197], v[222:225], v[90:93]
	v_mfma_i32_16x16x64_i8 v[86:89], v[172:175], v[230:233], v[86:89]
	v_mfma_i32_16x16x64_i8 v[82:85], v[194:197], v[230:233], v[82:85]
	v_mfma_i32_16x16x64_i8 v[78:81], v[172:175], v[238:241], v[78:81]
	v_mfma_i32_16x16x64_i8 v[74:77], v[194:197], v[238:241], v[74:77]
	v_mfma_i32_16x16x64_i8 v[70:73], v[172:175], v[246:249], v[70:73]
	v_mfma_i32_16x16x64_i8 v[66:69], v[194:197], v[246:249], v[66:69]
	v_mfma_i32_16x16x64_i8 v[30:33], v[198:201], v[214:217], v[30:33]
	v_mfma_i32_16x16x64_i8 v[26:29], v[206:209], v[214:217], v[26:29]
	v_mfma_i32_16x16x64_i8 v[22:25], v[198:201], v[226:229], v[22:25]
	v_mfma_i32_16x16x64_i8 v[18:21], v[206:209], v[226:229], v[18:21]
	v_mfma_i32_16x16x64_i8 v[14:17], v[198:201], v[234:237], v[14:17]
	v_mfma_i32_16x16x64_i8 v[10:13], v[206:209], v[234:237], v[10:13]
	v_mfma_i32_16x16x64_i8 v[6:9], v[198:201], v[242:245], v[6:9]
	v_mfma_i32_16x16x64_i8 v[2:5], v[206:209], v[242:245], v[2:5]
	v_mfma_i32_16x16x64_i8 v[30:33], v[202:205], v[222:225], v[30:33]
	v_mfma_i32_16x16x64_i8 v[26:29], v[210:213], v[222:225], v[26:29]
	v_mfma_i32_16x16x64_i8 v[22:25], v[202:205], v[230:233], v[22:25]
	v_mfma_i32_16x16x64_i8 v[18:21], v[210:213], v[230:233], v[18:21]
	v_mfma_i32_16x16x64_i8 v[14:17], v[202:205], v[238:241], v[14:17]
	v_mfma_i32_16x16x64_i8 v[10:13], v[210:213], v[238:241], v[10:13]
	v_mfma_i32_16x16x64_i8 v[6:9], v[202:205], v[246:249], v[6:9]
	v_mfma_i32_16x16x64_i8 v[2:5], v[210:213], v[246:249], v[2:5]
	s_setprio 0
	s_barrier
	s_add_i32 s60, s60, 2
	s_add_u32 s15, s15, 0x100
	s_addc_u32 s17, s17, 0
	s_add_u32 s26, s26, 0x100
	s_addc_u32 s27, s27, 0
	s_cmp_gt_u32 s60, 13
	s_cbranch_scc0 .LBB0_696
	s_and_b64 vcc, exec, s[12:13]
	s_cbranch_vccz .LBB0_699
	s_barrier

.LBB0_968:
	s_add_i32 s76, s24, 2
	s_add_u32 s25, s22, 0xfff80080
	s_addc_u32 s26, s23, -1
	s_add_i32 s36, 0, 0x10000
	s_cmp_eq_u32 s56, s24
	s_cselect_b32 s27, s19, s26
	s_cselect_b32 s26, s18, s25
	s_cselect_b32 s25, s21, s75
	s_cselect_b32 s24, s20, s74
	s_add_i32 s38, 0, 0x14000
	v_add_u32_e32 v152, s36, v211
	v_add_u32_e32 v160, s38, v211
	ds_read_b128 v[140:143], v152
	ds_read_b128 v[144:147], v152 offset:1024
	ds_read_b128 v[148:151], v152 offset:2048
	ds_read_b128 v[152:155], v152 offset:3072
	ds_read_b128 v[156:159], v160
	ds_read_b128 v[172:175], v160 offset:1024
	ds_read_b128 v[176:179], v160 offset:2048
	ds_read_b128 v[180:183], v160 offset:3072
	v_lshl_add_u64 v[160:161], s[22:23], 0, v[138:139]
	s_add_i32 m0, s61, 0xc000
	ds_read_b128 v[184:187], v213
	ds_read_b128 v[188:191], v213 offset:1024
	ds_read_b128 v[192:195], v213 offset:2048
	ds_read_b128 v[196:199], v213 offset:3072
	ds_read_b128 v[200:203], v213 offset:4096
	ds_read_b128 v[204:207], v213 offset:5120
	ds_read_b128 v[222:225], v213 offset:6144
	ds_read_b128 v[226:229], v213 offset:7168
	global_load_lds_dwordx4 v[160:161], off
	v_lshl_add_u64 v[160:161], s[22:23], 0, v[136:137]
	s_add_i32 m0, s61, 0xe000
	s_nop 0
	global_load_lds_dwordx4 v[160:161], off
	s_waitcnt vmcnt(8)
	s_waitcnt lgkmcnt(0)
	s_barrier
	s_setprio 1
	v_mfma_f32_16x16x32_bf16 v[126:129], v[140:143], v[184:187], v[126:129]
	v_mfma_f32_16x16x32_bf16 v[122:125], v[148:151], v[184:187], v[122:125]
	v_mfma_f32_16x16x32_bf16 v[118:121], v[140:143], v[192:195], v[118:121]
	v_mfma_f32_16x16x32_bf16 v[114:117], v[148:151], v[192:195], v[114:117]
	v_mfma_f32_16x16x32_bf16 v[110:113], v[140:143], v[200:203], v[110:113]
	v_mfma_f32_16x16x32_bf16 v[106:109], v[148:151], v[200:203], v[106:109]
	v_mfma_f32_16x16x32_bf16 v[102:105], v[140:143], v[222:225], v[102:105]
	v_mfma_f32_16x16x32_bf16 v[98:101], v[148:151], v[222:225], v[98:101]
	v_mfma_f32_16x16x32_bf16 v[126:129], v[144:147], v[188:191], v[126:129]
	v_mfma_f32_16x16x32_bf16 v[122:125], v[152:155], v[188:191], v[122:125]
	v_mfma_f32_16x16x32_bf16 v[118:121], v[144:147], v[196:199], v[118:121]
	v_mfma_f32_16x16x32_bf16 v[114:117], v[152:155], v[196:199], v[114:117]
	v_mfma_f32_16x16x32_bf16 v[110:113], v[144:147], v[204:207], v[110:113]
	v_mfma_f32_16x16x32_bf16 v[106:109], v[152:155], v[204:207], v[106:109]
	v_mfma_f32_16x16x32_bf16 v[102:105], v[144:147], v[226:229], v[102:105]
	v_mfma_f32_16x16x32_bf16 v[98:101], v[152:155], v[226:229], v[98:101]
	v_mfma_f32_16x16x32_bf16 v[94:97], v[156:159], v[184:187], v[94:97]
	v_mfma_f32_16x16x32_bf16 v[90:93], v[176:179], v[184:187], v[90:93]
	v_mfma_f32_16x16x32_bf16 v[86:89], v[156:159], v[192:195], v[86:89]
	v_mfma_f32_16x16x32_bf16 v[82:85], v[176:179], v[192:195], v[82:85]
	v_mfma_f32_16x16x32_bf16 v[78:81], v[156:159], v[200:203], v[78:81]
	v_mfma_f32_16x16x32_bf16 v[74:77], v[176:179], v[200:203], v[74:77]
	v_mfma_f32_16x16x32_bf16 v[70:73], v[156:159], v[222:225], v[70:73]
	v_mfma_f32_16x16x32_bf16 v[66:69], v[176:179], v[222:225], v[66:69]
	v_mfma_f32_16x16x32_bf16 v[94:97], v[172:175], v[188:191], v[94:97]
	v_mfma_f32_16x16x32_bf16 v[90:93], v[180:183], v[188:191], v[90:93]
	v_mfma_f32_16x16x32_bf16 v[86:89], v[172:175], v[196:199], v[86:89]
	v_mfma_f32_16x16x32_bf16 v[82:85], v[180:183], v[196:199], v[82:85]
	v_mfma_f32_16x16x32_bf16 v[78:81], v[172:175], v[204:207], v[78:81]
	v_mfma_f32_16x16x32_bf16 v[74:77], v[180:183], v[204:207], v[74:77]
	v_mfma_f32_16x16x32_bf16 v[70:73], v[172:175], v[226:229], v[70:73]
	v_mfma_f32_16x16x32_bf16 v[66:69], v[180:183], v[226:229], v[66:69]
	s_setprio 0
	s_barrier
	s_add_i32 s36, s36, s60
	v_lshl_add_u64 v[160:161], s[24:25], 0, v[162:163]
	s_mov_b32 m0, s36
	ds_read_b128 v[184:187], v213 offset:16384
	ds_read_b128 v[188:191], v213 offset:17408
	ds_read_b128 v[192:195], v213 offset:18432
	ds_read_b128 v[196:199], v213 offset:19456
	ds_read_b128 v[200:203], v213 offset:20480
	ds_read_b128 v[204:207], v213 offset:21504
	ds_read_b128 v[222:225], v213 offset:22528
	ds_read_b128 v[226:229], v213 offset:23552
	global_load_lds_dwordx4 v[160:161], off
	s_add_i32 m0, s36, 0x2000
	s_add_u32 s36, s24, 0x80000
	v_lshl_add_u64 v[168:169], s[24:25], 0, v[134:135]
	s_addc_u32 s37, s25, 0
	s_add_i32 s38, s38, s60
	global_load_lds_dwordx4 v[168:169], off
	v_lshl_add_u64 v[170:171], s[36:37], 0, v[162:163]
	s_mov_b32 m0, s38
	v_lshl_add_u64 v[208:209], s[26:27], 0, v[132:133]
	global_load_lds_dwordx4 v[170:171], off
	v_lshl_add_u64 v[170:171], s[36:37], 0, v[134:135]
	s_add_i32 m0, s38, 0x2000
	s_nop 0
	global_load_lds_dwordx4 v[170:171], off
	v_lshl_add_u64 v[170:171], s[26:27], 0, v[130:131]
	s_mov_b32 m0, s61
	s_nop 0
	global_load_lds_dwordx4 v[170:171], off
	s_mov_b32 m0, s62
	s_nop 0
	global_load_lds_dwordx4 v[208:209], off
	s_waitcnt vmcnt(8)
	s_waitcnt lgkmcnt(0)
	s_barrier
	s_setprio 1
	v_mfma_f32_16x16x32_bf16 v[62:65], v[140:143], v[184:187], v[62:65]
	v_mfma_f32_16x16x32_bf16 v[58:61], v[148:151], v[184:187], v[58:61]
	v_mfma_f32_16x16x32_bf16 v[54:57], v[140:143], v[192:195], v[54:57]
	v_mfma_f32_16x16x32_bf16 v[50:53], v[148:151], v[192:195], v[50:53]
	v_mfma_f32_16x16x32_bf16 v[46:49], v[140:143], v[200:203], v[46:49]
	v_mfma_f32_16x16x32_bf16 v[42:45], v[148:151], v[200:203], v[42:45]
	v_mfma_f32_16x16x32_bf16 v[38:41], v[140:143], v[222:225], v[38:41]
	v_mfma_f32_16x16x32_bf16 v[34:37], v[148:151], v[222:225], v[34:37]
	v_mfma_f32_16x16x32_bf16 v[62:65], v[144:147], v[188:191], v[62:65]
	v_mfma_f32_16x16x32_bf16 v[58:61], v[152:155], v[188:191], v[58:61]
	v_mfma_f32_16x16x32_bf16 v[54:57], v[144:147], v[196:199], v[54:57]
	v_mfma_f32_16x16x32_bf16 v[50:53], v[152:155], v[196:199], v[50:53]
	v_mfma_f32_16x16x32_bf16 v[46:49], v[144:147], v[204:207], v[46:49]
	v_mfma_f32_16x16x32_bf16 v[42:45], v[152:155], v[204:207], v[42:45]
	v_mfma_f32_16x16x32_bf16 v[38:41], v[144:147], v[226:229], v[38:41]
	v_mfma_f32_16x16x32_bf16 v[34:37], v[152:155], v[226:229], v[34:37]
	v_mfma_f32_16x16x32_bf16 v[30:33], v[156:159], v[184:187], v[30:33]
	v_mfma_f32_16x16x32_bf16 v[26:29], v[176:179], v[184:187], v[26:29]
	v_mfma_f32_16x16x32_bf16 v[22:25], v[156:159], v[192:195], v[22:25]
	v_mfma_f32_16x16x32_bf16 v[18:21], v[176:179], v[192:195], v[18:21]
	v_mfma_f32_16x16x32_bf16 v[14:17], v[156:159], v[200:203], v[14:17]
	v_mfma_f32_16x16x32_bf16 v[10:13], v[176:179], v[200:203], v[10:13]
	v_mfma_f32_16x16x32_bf16 v[6:9], v[156:159], v[222:225], v[6:9]
	v_mfma_f32_16x16x32_bf16 v[2:5], v[176:179], v[222:225], v[2:5]
	v_mfma_f32_16x16x32_bf16 v[30:33], v[172:175], v[188:191], v[30:33]
	v_mfma_f32_16x16x32_bf16 v[26:29], v[180:183], v[188:191], v[26:29]
	v_mfma_f32_16x16x32_bf16 v[22:25], v[172:175], v[196:199], v[22:25]
	v_mfma_f32_16x16x32_bf16 v[18:21], v[180:183], v[196:199], v[18:21]
	v_mfma_f32_16x16x32_bf16 v[14:17], v[172:175], v[204:207], v[14:17]
	v_mfma_f32_16x16x32_bf16 v[10:13], v[180:183], v[204:207], v[10:13]
	v_mfma_f32_16x16x32_bf16 v[6:9], v[172:175], v[226:229], v[6:9]
	v_mfma_f32_16x16x32_bf16 v[2:5], v[180:183], v[226:229], v[2:5]
	s_setprio 0
	s_barrier
	s_add_i32 s36, 0, 0x18000
	s_add_i32 s37, 0, 0x1c000
	v_add_u32_e32 v152, s36, v211
	v_add_u32_e32 v180, s37, v211
	ds_read_b128 v[140:143], v152
	ds_read_b128 v[144:147], v152 offset:1024
	ds_read_b128 v[148:151], v152 offset:2048
	ds_read_b128 v[152:155], v152 offset:3072
	ds_read_b128 v[156:159], v180
	ds_read_b128 v[172:175], v180 offset:1024
	ds_read_b128 v[176:179], v180 offset:2048
	ds_read_b128 v[180:183], v180 offset:3072
	s_add_u32 s26, s26, 0x80000
	s_addc_u32 s27, s27, 0
	s_mov_b32 m0, s63
	v_lshl_add_u64 v[216:217], s[26:27], 0, v[130:131]
	ds_read_b128 v[184:187], v213 offset:32768
	ds_read_b128 v[188:191], v213 offset:33792
	ds_read_b128 v[192:195], v213 offset:34816
	ds_read_b128 v[196:199], v213 offset:35840
	ds_read_b128 v[200:203], v213 offset:36864
	ds_read_b128 v[204:207], v213 offset:37888
	ds_read_b128 v[222:225], v213 offset:38912
	ds_read_b128 v[226:229], v213 offset:39936
	global_load_lds_dwordx4 v[216:217], off
	v_lshl_add_u64 v[216:217], s[26:27], 0, v[132:133]
	s_mov_b32 m0, s64
	s_nop 0
	global_load_lds_dwordx4 v[216:217], off
	s_waitcnt vmcnt(8)
	s_waitcnt lgkmcnt(0)
	s_barrier
	s_setprio 1
	v_mfma_f32_16x16x32_bf16 v[126:129], v[140:143], v[184:187], v[126:129]
	v_mfma_f32_16x16x32_bf16 v[122:125], v[148:151], v[184:187], v[122:125]
	v_mfma_f32_16x16x32_bf16 v[118:121], v[140:143], v[192:195], v[118:121]
	v_mfma_f32_16x16x32_bf16 v[114:117], v[148:151], v[192:195], v[114:117]
	v_mfma_f32_16x16x32_bf16 v[110:113], v[140:143], v[200:203], v[110:113]
	v_mfma_f32_16x16x32_bf16 v[106:109], v[148:151], v[200:203], v[106:109]
	v_mfma_f32_16x16x32_bf16 v[102:105], v[140:143], v[222:225], v[102:105]
	v_mfma_f32_16x16x32_bf16 v[98:101], v[148:151], v[222:225], v[98:101]
	v_mfma_f32_16x16x32_bf16 v[126:129], v[144:147], v[188:191], v[126:129]
	v_mfma_f32_16x16x32_bf16 v[122:125], v[152:155], v[188:191], v[122:125]
	v_mfma_f32_16x16x32_bf16 v[118:121], v[144:147], v[196:199], v[118:121]
	v_mfma_f32_16x16x32_bf16 v[114:117], v[152:155], v[196:199], v[114:117]
	v_mfma_f32_16x16x32_bf16 v[110:113], v[144:147], v[204:207], v[110:113]
	v_mfma_f32_16x16x32_bf16 v[106:109], v[152:155], v[204:207], v[106:109]
	v_mfma_f32_16x16x32_bf16 v[102:105], v[144:147], v[226:229], v[102:105]
	v_mfma_f32_16x16x32_bf16 v[98:101], v[152:155], v[226:229], v[98:101]
	v_mfma_f32_16x16x32_bf16 v[94:97], v[156:159], v[184:187], v[94:97]
	v_mfma_f32_16x16x32_bf16 v[90:93], v[176:179], v[184:187], v[90:93]
	v_mfma_f32_16x16x32_bf16 v[86:89], v[156:159], v[192:195], v[86:89]
	v_mfma_f32_16x16x32_bf16 v[82:85], v[176:179], v[192:195], v[82:85]
	v_mfma_f32_16x16x32_bf16 v[78:81], v[156:159], v[200:203], v[78:81]
	v_mfma_f32_16x16x32_bf16 v[74:77], v[176:179], v[200:203], v[74:77]
	v_mfma_f32_16x16x32_bf16 v[70:73], v[156:159], v[222:225], v[70:73]
	v_mfma_f32_16x16x32_bf16 v[66:69], v[176:179], v[222:225], v[66:69]
	v_mfma_f32_16x16x32_bf16 v[94:97], v[172:175], v[188:191], v[94:97]
	v_mfma_f32_16x16x32_bf16 v[90:93], v[180:183], v[188:191], v[90:93]
	v_mfma_f32_16x16x32_bf16 v[86:89], v[172:175], v[196:199], v[86:89]
	v_mfma_f32_16x16x32_bf16 v[82:85], v[180:183], v[196:199], v[82:85]
	v_mfma_f32_16x16x32_bf16 v[78:81], v[172:175], v[204:207], v[78:81]
	v_mfma_f32_16x16x32_bf16 v[74:77], v[180:183], v[204:207], v[74:77]
	v_mfma_f32_16x16x32_bf16 v[70:73], v[172:175], v[226:229], v[70:73]
	v_mfma_f32_16x16x32_bf16 v[66:69], v[180:183], v[226:229], v[66:69]
	s_setprio 0
	s_barrier
	s_add_i32 s26, s36, s60
	v_lshl_add_u64 v[160:161], v[160:161], 0, s[44:45]
	s_mov_b32 m0, s26
	ds_read_b128 v[184:187], v213 offset:49152
	ds_read_b128 v[188:191], v213 offset:50176
	ds_read_b128 v[192:195], v213 offset:51200
	ds_read_b128 v[196:199], v213 offset:52224
	ds_read_b128 v[200:203], v213 offset:53248
	ds_read_b128 v[204:207], v213 offset:54272
	ds_read_b128 v[222:225], v213 offset:55296
	ds_read_b128 v[226:229], v213 offset:56320
	global_load_lds_dwordx4 v[160:161], off
	s_add_i32 m0, s26, 0x2000
	s_add_u32 s24, s24, 0x80080
	v_lshl_add_u64 v[160:161], v[168:169], 0, s[44:45]
	s_addc_u32 s25, s25, 0
	s_add_i32 s26, s37, s60
	global_load_lds_dwordx4 v[160:161], off
	v_lshl_add_u64 v[160:161], s[24:25], 0, v[162:163]
	s_mov_b32 m0, s26
	s_nop 0
	global_load_lds_dwordx4 v[160:161], off
	v_lshl_add_u64 v[160:161], s[24:25], 0, v[134:135]
	s_add_i32 m0, s26, 0x2000
	s_nop 0
	global_load_lds_dwordx4 v[160:161], off
	v_lshl_add_u64 v[160:161], v[170:171], 0, s[44:45]
	s_mov_b32 m0, s65
	s_nop 0
	global_load_lds_dwordx4 v[160:161], off
	v_lshl_add_u64 v[160:161], v[208:209], 0, s[44:45]
	s_mov_b32 m0, s66
	s_nop 0
	global_load_lds_dwordx4 v[160:161], off
	s_waitcnt vmcnt(8)
	s_waitcnt lgkmcnt(0)
	s_barrier
	s_setprio 1
	v_mfma_f32_16x16x32_bf16 v[62:65], v[140:143], v[184:187], v[62:65]
	v_mfma_f32_16x16x32_bf16 v[58:61], v[148:151], v[184:187], v[58:61]
	v_mfma_f32_16x16x32_bf16 v[54:57], v[140:143], v[192:195], v[54:57]
	v_mfma_f32_16x16x32_bf16 v[50:53], v[148:151], v[192:195], v[50:53]
	v_mfma_f32_16x16x32_bf16 v[46:49], v[140:143], v[200:203], v[46:49]
	v_mfma_f32_16x16x32_bf16 v[42:45], v[148:151], v[200:203], v[42:45]
	v_mfma_f32_16x16x32_bf16 v[38:41], v[140:143], v[222:225], v[38:41]
	v_mfma_f32_16x16x32_bf16 v[34:37], v[148:151], v[222:225], v[34:37]
	v_mfma_f32_16x16x32_bf16 v[62:65], v[144:147], v[188:191], v[62:65]
	v_mfma_f32_16x16x32_bf16 v[58:61], v[152:155], v[188:191], v[58:61]
	v_mfma_f32_16x16x32_bf16 v[54:57], v[144:147], v[196:199], v[54:57]
	v_mfma_f32_16x16x32_bf16 v[50:53], v[152:155], v[196:199], v[50:53]
	v_mfma_f32_16x16x32_bf16 v[46:49], v[144:147], v[204:207], v[46:49]
	v_mfma_f32_16x16x32_bf16 v[42:45], v[152:155], v[204:207], v[42:45]
	v_mfma_f32_16x16x32_bf16 v[38:41], v[144:147], v[226:229], v[38:41]
	v_mfma_f32_16x16x32_bf16 v[34:37], v[152:155], v[226:229], v[34:37]
	v_mfma_f32_16x16x32_bf16 v[30:33], v[156:159], v[184:187], v[30:33]
	v_mfma_f32_16x16x32_bf16 v[26:29], v[176:179], v[184:187], v[26:29]
	v_mfma_f32_16x16x32_bf16 v[22:25], v[156:159], v[192:195], v[22:25]
	v_mfma_f32_16x16x32_bf16 v[18:21], v[176:179], v[192:195], v[18:21]
	v_mfma_f32_16x16x32_bf16 v[14:17], v[156:159], v[200:203], v[14:17]
	v_mfma_f32_16x16x32_bf16 v[10:13], v[176:179], v[200:203], v[10:13]
	v_mfma_f32_16x16x32_bf16 v[6:9], v[156:159], v[222:225], v[6:9]
	v_mfma_f32_16x16x32_bf16 v[2:5], v[176:179], v[222:225], v[2:5]
	v_mfma_f32_16x16x32_bf16 v[30:33], v[172:175], v[188:191], v[30:33]
	v_mfma_f32_16x16x32_bf16 v[26:29], v[180:183], v[188:191], v[26:29]
	v_mfma_f32_16x16x32_bf16 v[22:25], v[172:175], v[196:199], v[22:25]
	v_mfma_f32_16x16x32_bf16 v[18:21], v[180:183], v[196:199], v[18:21]
	v_mfma_f32_16x16x32_bf16 v[14:17], v[172:175], v[204:207], v[14:17]
	v_mfma_f32_16x16x32_bf16 v[10:13], v[180:183], v[204:207], v[10:13]
	v_mfma_f32_16x16x32_bf16 v[6:9], v[172:175], v[226:229], v[6:9]
	v_mfma_f32_16x16x32_bf16 v[2:5], v[180:183], v[226:229], v[2:5]
	s_setprio 0
	s_barrier
	s_add_u32 s74, s74, 0x100
	s_addc_u32 s75, s75, 0
	s_add_u32 s22, s22, 0x100
	s_addc_u32 s23, s23, 0
	s_cmp_ge_i32 s76, s9
	s_mov_b32 s24, s76
	s_cbranch_scc0 .LBB0_968
	s_and_b64 vcc, exec, s[14:15]
	s_cbranch_vccz .LBB0_971
	s_barrier

.LBB0_1211:
	s_add_u32 s36, s56, 0xfff80080
	s_addc_u32 s37, s57, -1
	s_add_i32 s38, 0, 0x10000
	s_cmp_eq_u32 s78, 28
	s_cselect_b32 s61, s21, s37
	s_cselect_b32 s60, s20, s36
	s_cselect_b32 s59, s23, s62
	s_cselect_b32 s58, s22, s25
	s_add_i32 s39, 0, 0x14000
	v_add_u32_e32 v142, s38, v201
	v_add_u32_e32 v168, s39, v201
	ds_read_b128 v[110:113], v142
	ds_read_b128 v[118:121], v142 offset:1024
	ds_read_b128 v[138:141], v142 offset:2048
	ds_read_b128 v[142:145], v142 offset:3072
	ds_read_b128 v[146:149], v168
	ds_read_b128 v[150:153], v168 offset:1024
	ds_read_b128 v[174:177], v168 offset:2048
	ds_read_b128 v[178:181], v168 offset:3072
	v_lshl_add_u64 v[168:169], s[56:57], 0, v[172:173]
	s_add_i32 m0, s66, 0xc000
	ds_read_b128 v[182:185], v203
	ds_read_b128 v[186:189], v203 offset:1024
	ds_read_b128 v[190:193], v203 offset:2048
	ds_read_b128 v[194:197], v203 offset:3072
	ds_read_b128 v[204:207], v203 offset:4096
	ds_read_b128 v[208:211], v203 offset:5120
	ds_read_b128 v[212:215], v203 offset:6144
	ds_read_b128 v[222:225], v203 offset:7168
	global_load_lds_dwordx4 v[168:169], off
	v_lshl_add_u64 v[168:169], s[56:57], 0, v[160:161]
	s_add_i32 m0, s66, 0xe000
	s_nop 0
	global_load_lds_dwordx4 v[168:169], off
	s_waitcnt vmcnt(8)
	s_waitcnt lgkmcnt(0)
	s_barrier
	s_setprio 1
	v_mfma_f32_16x16x32_bf16 v[134:137], v[110:113], v[182:185], v[134:137]
	v_mfma_f32_16x16x32_bf16 v[130:133], v[138:141], v[182:185], v[130:133]
	v_mfma_f32_16x16x32_bf16 v[114:117], v[110:113], v[190:193], v[114:117]
	v_mfma_f32_16x16x32_bf16 v[106:109], v[138:141], v[190:193], v[106:109]
	v_mfma_f32_16x16x32_bf16 v[94:97], v[110:113], v[204:207], v[94:97]
	v_mfma_f32_16x16x32_bf16 v[90:93], v[138:141], v[204:207], v[90:93]
	v_mfma_f32_16x16x32_bf16 v[78:81], v[110:113], v[212:215], v[78:81]
	v_mfma_f32_16x16x32_bf16 v[74:77], v[138:141], v[212:215], v[74:77]
	v_mfma_f32_16x16x32_bf16 v[134:137], v[118:121], v[186:189], v[134:137]
	v_mfma_f32_16x16x32_bf16 v[130:133], v[142:145], v[186:189], v[130:133]
	v_mfma_f32_16x16x32_bf16 v[114:117], v[118:121], v[194:197], v[114:117]
	v_mfma_f32_16x16x32_bf16 v[106:109], v[142:145], v[194:197], v[106:109]
	v_mfma_f32_16x16x32_bf16 v[94:97], v[118:121], v[208:211], v[94:97]
	v_mfma_f32_16x16x32_bf16 v[90:93], v[142:145], v[208:211], v[90:93]
	v_mfma_f32_16x16x32_bf16 v[78:81], v[118:121], v[222:225], v[78:81]
	v_mfma_f32_16x16x32_bf16 v[74:77], v[142:145], v[222:225], v[74:77]
	v_mfma_f32_16x16x32_bf16 v[126:129], v[146:149], v[182:185], v[126:129]
	v_mfma_f32_16x16x32_bf16 v[122:125], v[174:177], v[182:185], v[122:125]
	v_mfma_f32_16x16x32_bf16 v[102:105], v[146:149], v[190:193], v[102:105]
	v_mfma_f32_16x16x32_bf16 v[98:101], v[174:177], v[190:193], v[98:101]
	v_mfma_f32_16x16x32_bf16 v[86:89], v[146:149], v[204:207], v[86:89]
	v_mfma_f32_16x16x32_bf16 v[82:85], v[174:177], v[204:207], v[82:85]
	v_mfma_f32_16x16x32_bf16 v[70:73], v[146:149], v[212:215], v[70:73]
	v_mfma_f32_16x16x32_bf16 v[66:69], v[174:177], v[212:215], v[66:69]
	v_mfma_f32_16x16x32_bf16 v[126:129], v[150:153], v[186:189], v[126:129]
	v_mfma_f32_16x16x32_bf16 v[122:125], v[178:181], v[186:189], v[122:125]
	v_mfma_f32_16x16x32_bf16 v[102:105], v[150:153], v[194:197], v[102:105]
	v_mfma_f32_16x16x32_bf16 v[98:101], v[178:181], v[194:197], v[98:101]
	v_mfma_f32_16x16x32_bf16 v[86:89], v[150:153], v[208:211], v[86:89]
	v_mfma_f32_16x16x32_bf16 v[82:85], v[178:181], v[208:211], v[82:85]
	v_mfma_f32_16x16x32_bf16 v[70:73], v[150:153], v[222:225], v[70:73]
	v_mfma_f32_16x16x32_bf16 v[66:69], v[178:181], v[222:225], v[66:69]
	s_setprio 0
	s_barrier
	s_add_i32 s36, s38, s27
	v_lshl_add_u64 v[168:169], s[58:59], 0, v[162:163]
	s_mov_b32 m0, s36
	ds_read_b128 v[182:185], v203 offset:16384
	ds_read_b128 v[186:189], v203 offset:17408
	ds_read_b128 v[190:193], v203 offset:18432
	ds_read_b128 v[194:197], v203 offset:19456
	ds_read_b128 v[204:207], v203 offset:20480
	ds_read_b128 v[208:211], v203 offset:21504
	ds_read_b128 v[212:215], v203 offset:22528
	ds_read_b128 v[222:225], v203 offset:23552
	global_load_lds_dwordx4 v[168:169], off
	s_add_i32 m0, s36, 0x2000
	s_add_u32 s36, s58, 0x80000
	v_lshl_add_u64 v[170:171], s[58:59], 0, v[158:159]
	s_addc_u32 s37, s59, 0
	s_add_i32 s38, s39, s27
	global_load_lds_dwordx4 v[170:171], off
	v_lshl_add_u64 v[198:199], s[36:37], 0, v[162:163]
	s_mov_b32 m0, s38
	v_lshl_add_u64 v[216:217], s[60:61], 0, v[156:157]
	global_load_lds_dwordx4 v[198:199], off
	v_lshl_add_u64 v[198:199], s[36:37], 0, v[158:159]
	s_add_i32 m0, s38, 0x2000
	s_nop 0
	global_load_lds_dwordx4 v[198:199], off
	v_lshl_add_u64 v[198:199], s[60:61], 0, v[154:155]
	s_mov_b32 m0, s66
	s_nop 0
	global_load_lds_dwordx4 v[198:199], off
	s_mov_b32 m0, s67
	s_nop 0
	global_load_lds_dwordx4 v[216:217], off
	s_waitcnt vmcnt(8)
	s_waitcnt lgkmcnt(0)
	s_barrier
	s_setprio 1
	v_mfma_f32_16x16x32_bf16 v[62:65], v[110:113], v[182:185], v[62:65]
	v_mfma_f32_16x16x32_bf16 v[58:61], v[138:141], v[182:185], v[58:61]
	v_mfma_f32_16x16x32_bf16 v[46:49], v[110:113], v[190:193], v[46:49]
	v_mfma_f32_16x16x32_bf16 v[42:45], v[138:141], v[190:193], v[42:45]
	v_mfma_f32_16x16x32_bf16 v[30:33], v[110:113], v[204:207], v[30:33]
	v_mfma_f32_16x16x32_bf16 v[26:29], v[138:141], v[204:207], v[26:29]
	v_mfma_f32_16x16x32_bf16 v[14:17], v[110:113], v[212:215], v[14:17]
	v_mfma_f32_16x16x32_bf16 v[10:13], v[138:141], v[212:215], v[10:13]
	v_mfma_f32_16x16x32_bf16 v[62:65], v[118:121], v[186:189], v[62:65]
	v_mfma_f32_16x16x32_bf16 v[58:61], v[142:145], v[186:189], v[58:61]
	v_mfma_f32_16x16x32_bf16 v[46:49], v[118:121], v[194:197], v[46:49]
	v_mfma_f32_16x16x32_bf16 v[42:45], v[142:145], v[194:197], v[42:45]
	v_mfma_f32_16x16x32_bf16 v[30:33], v[118:121], v[208:211], v[30:33]
	v_mfma_f32_16x16x32_bf16 v[26:29], v[142:145], v[208:211], v[26:29]
	v_mfma_f32_16x16x32_bf16 v[14:17], v[118:121], v[222:225], v[14:17]
	v_mfma_f32_16x16x32_bf16 v[10:13], v[142:145], v[222:225], v[10:13]
	v_mfma_f32_16x16x32_bf16 v[54:57], v[146:149], v[182:185], v[54:57]
	v_mfma_f32_16x16x32_bf16 v[50:53], v[174:177], v[182:185], v[50:53]
	v_mfma_f32_16x16x32_bf16 v[38:41], v[146:149], v[190:193], v[38:41]
	v_mfma_f32_16x16x32_bf16 v[34:37], v[174:177], v[190:193], v[34:37]
	v_mfma_f32_16x16x32_bf16 v[22:25], v[146:149], v[204:207], v[22:25]
	v_mfma_f32_16x16x32_bf16 v[18:21], v[174:177], v[204:207], v[18:21]
	v_mfma_f32_16x16x32_bf16 v[6:9], v[146:149], v[212:215], v[6:9]
	v_mfma_f32_16x16x32_bf16 v[2:5], v[174:177], v[212:215], v[2:5]
	v_mfma_f32_16x16x32_bf16 v[54:57], v[150:153], v[186:189], v[54:57]
	v_mfma_f32_16x16x32_bf16 v[50:53], v[178:181], v[186:189], v[50:53]
	v_mfma_f32_16x16x32_bf16 v[38:41], v[150:153], v[194:197], v[38:41]
	v_mfma_f32_16x16x32_bf16 v[34:37], v[178:181], v[194:197], v[34:37]
	v_mfma_f32_16x16x32_bf16 v[22:25], v[150:153], v[208:211], v[22:25]
	v_mfma_f32_16x16x32_bf16 v[18:21], v[178:181], v[208:211], v[18:21]
	v_mfma_f32_16x16x32_bf16 v[6:9], v[150:153], v[222:225], v[6:9]
	v_mfma_f32_16x16x32_bf16 v[2:5], v[178:181], v[222:225], v[2:5]
	s_setprio 0
	s_barrier
	s_add_i32 s38, 0, 0x18000
	s_add_i32 s39, 0, 0x1c000
	v_add_u32_e32 v142, s38, v201
	v_add_u32_e32 v178, s39, v201
	ds_read_b128 v[110:113], v142
	ds_read_b128 v[118:121], v142 offset:1024
	ds_read_b128 v[138:141], v142 offset:2048
	ds_read_b128 v[142:145], v142 offset:3072
	ds_read_b128 v[146:149], v178
	ds_read_b128 v[150:153], v178 offset:1024
	ds_read_b128 v[174:177], v178 offset:2048
	ds_read_b128 v[178:181], v178 offset:3072
	s_add_u32 s36, s60, 0x80000
	s_addc_u32 s37, s61, 0
	s_mov_b32 m0, s68
	v_lshl_add_u64 v[226:227], s[36:37], 0, v[154:155]
	ds_read_b128 v[182:185], v203 offset:32768
	ds_read_b128 v[186:189], v203 offset:33792
	ds_read_b128 v[190:193], v203 offset:34816
	ds_read_b128 v[194:197], v203 offset:35840
	ds_read_b128 v[204:207], v203 offset:36864
	ds_read_b128 v[208:211], v203 offset:37888
	ds_read_b128 v[212:215], v203 offset:38912
	ds_read_b128 v[222:225], v203 offset:39936
	global_load_lds_dwordx4 v[226:227], off
	v_lshl_add_u64 v[226:227], s[36:37], 0, v[156:157]
	s_mov_b32 m0, s69
	s_nop 0
	global_load_lds_dwordx4 v[226:227], off
	s_waitcnt vmcnt(8)
	s_waitcnt lgkmcnt(0)
	s_barrier
	s_setprio 1
	v_mfma_f32_16x16x32_bf16 v[134:137], v[110:113], v[182:185], v[134:137]
	v_mfma_f32_16x16x32_bf16 v[130:133], v[138:141], v[182:185], v[130:133]
	v_mfma_f32_16x16x32_bf16 v[114:117], v[110:113], v[190:193], v[114:117]
	v_mfma_f32_16x16x32_bf16 v[106:109], v[138:141], v[190:193], v[106:109]
	v_mfma_f32_16x16x32_bf16 v[94:97], v[110:113], v[204:207], v[94:97]
	v_mfma_f32_16x16x32_bf16 v[90:93], v[138:141], v[204:207], v[90:93]
	v_mfma_f32_16x16x32_bf16 v[78:81], v[110:113], v[212:215], v[78:81]
	v_mfma_f32_16x16x32_bf16 v[74:77], v[138:141], v[212:215], v[74:77]
	v_mfma_f32_16x16x32_bf16 v[134:137], v[118:121], v[186:189], v[134:137]
	v_mfma_f32_16x16x32_bf16 v[130:133], v[142:145], v[186:189], v[130:133]
	v_mfma_f32_16x16x32_bf16 v[114:117], v[118:121], v[194:197], v[114:117]
	v_mfma_f32_16x16x32_bf16 v[106:109], v[142:145], v[194:197], v[106:109]
	v_mfma_f32_16x16x32_bf16 v[94:97], v[118:121], v[208:211], v[94:97]
	v_mfma_f32_16x16x32_bf16 v[90:93], v[142:145], v[208:211], v[90:93]
	v_mfma_f32_16x16x32_bf16 v[78:81], v[118:121], v[222:225], v[78:81]
	v_mfma_f32_16x16x32_bf16 v[74:77], v[142:145], v[222:225], v[74:77]
	v_mfma_f32_16x16x32_bf16 v[126:129], v[146:149], v[182:185], v[126:129]
	v_mfma_f32_16x16x32_bf16 v[122:125], v[174:177], v[182:185], v[122:125]
	v_mfma_f32_16x16x32_bf16 v[102:105], v[146:149], v[190:193], v[102:105]
	v_mfma_f32_16x16x32_bf16 v[98:101], v[174:177], v[190:193], v[98:101]
	v_mfma_f32_16x16x32_bf16 v[86:89], v[146:149], v[204:207], v[86:89]
	v_mfma_f32_16x16x32_bf16 v[82:85], v[174:177], v[204:207], v[82:85]
	v_mfma_f32_16x16x32_bf16 v[70:73], v[146:149], v[212:215], v[70:73]
	v_mfma_f32_16x16x32_bf16 v[66:69], v[174:177], v[212:215], v[66:69]
	v_mfma_f32_16x16x32_bf16 v[126:129], v[150:153], v[186:189], v[126:129]
	v_mfma_f32_16x16x32_bf16 v[122:125], v[178:181], v[186:189], v[122:125]
	v_mfma_f32_16x16x32_bf16 v[102:105], v[150:153], v[194:197], v[102:105]
	v_mfma_f32_16x16x32_bf16 v[98:101], v[178:181], v[194:197], v[98:101]
	v_mfma_f32_16x16x32_bf16 v[86:89], v[150:153], v[208:211], v[86:89]
	v_mfma_f32_16x16x32_bf16 v[82:85], v[178:181], v[208:211], v[82:85]
	v_mfma_f32_16x16x32_bf16 v[70:73], v[150:153], v[222:225], v[70:73]
	v_mfma_f32_16x16x32_bf16 v[66:69], v[178:181], v[222:225], v[66:69]
	s_setprio 0
	s_barrier
	s_add_i32 s36, s38, s27
	v_lshl_add_u64 v[168:169], v[168:169], 0, s[44:45]
	s_mov_b32 m0, s36
	ds_read_b128 v[182:185], v203 offset:49152
	ds_read_b128 v[186:189], v203 offset:50176
	ds_read_b128 v[190:193], v203 offset:51200
	ds_read_b128 v[194:197], v203 offset:52224
	ds_read_b128 v[204:207], v203 offset:53248
	ds_read_b128 v[208:211], v203 offset:54272
	ds_read_b128 v[212:215], v203 offset:55296
	ds_read_b128 v[222:225], v203 offset:56320
	global_load_lds_dwordx4 v[168:169], off
	s_add_i32 m0, s36, 0x2000
	s_add_u32 s36, s58, 0x80080
	v_lshl_add_u64 v[168:169], v[170:171], 0, s[44:45]
	s_addc_u32 s37, s59, 0
	s_add_i32 s38, s39, s27
	global_load_lds_dwordx4 v[168:169], off
	v_lshl_add_u64 v[168:169], s[36:37], 0, v[162:163]
	s_mov_b32 m0, s38
	s_nop 0
	global_load_lds_dwordx4 v[168:169], off
	v_lshl_add_u64 v[168:169], s[36:37], 0, v[158:159]
	s_add_i32 m0, s38, 0x2000
	s_nop 0
	global_load_lds_dwordx4 v[168:169], off
	v_lshl_add_u64 v[168:169], v[198:199], 0, s[44:45]
	s_mov_b32 m0, s70
	s_nop 0
	global_load_lds_dwordx4 v[168:169], off
	v_lshl_add_u64 v[168:169], v[216:217], 0, s[44:45]
	s_mov_b32 m0, s71
	s_nop 0
	global_load_lds_dwordx4 v[168:169], off
	s_waitcnt vmcnt(8)
	s_waitcnt lgkmcnt(0)
	s_barrier
	s_setprio 1
	v_mfma_f32_16x16x32_bf16 v[62:65], v[110:113], v[182:185], v[62:65]
	v_mfma_f32_16x16x32_bf16 v[58:61], v[138:141], v[182:185], v[58:61]
	v_mfma_f32_16x16x32_bf16 v[46:49], v[110:113], v[190:193], v[46:49]
	v_mfma_f32_16x16x32_bf16 v[42:45], v[138:141], v[190:193], v[42:45]
	v_mfma_f32_16x16x32_bf16 v[30:33], v[110:113], v[204:207], v[30:33]
	v_mfma_f32_16x16x32_bf16 v[26:29], v[138:141], v[204:207], v[26:29]
	v_mfma_f32_16x16x32_bf16 v[14:17], v[110:113], v[212:215], v[14:17]
	v_mfma_f32_16x16x32_bf16 v[10:13], v[138:141], v[212:215], v[10:13]
	v_mfma_f32_16x16x32_bf16 v[62:65], v[118:121], v[186:189], v[62:65]
	v_mfma_f32_16x16x32_bf16 v[58:61], v[142:145], v[186:189], v[58:61]
	v_mfma_f32_16x16x32_bf16 v[46:49], v[118:121], v[194:197], v[46:49]
	v_mfma_f32_16x16x32_bf16 v[42:45], v[142:145], v[194:197], v[42:45]
	v_mfma_f32_16x16x32_bf16 v[30:33], v[118:121], v[208:211], v[30:33]
	v_mfma_f32_16x16x32_bf16 v[26:29], v[142:145], v[208:211], v[26:29]
	v_mfma_f32_16x16x32_bf16 v[14:17], v[118:121], v[222:225], v[14:17]
	v_mfma_f32_16x16x32_bf16 v[10:13], v[142:145], v[222:225], v[10:13]
	v_mfma_f32_16x16x32_bf16 v[54:57], v[146:149], v[182:185], v[54:57]
	v_mfma_f32_16x16x32_bf16 v[50:53], v[174:177], v[182:185], v[50:53]
	v_mfma_f32_16x16x32_bf16 v[38:41], v[146:149], v[190:193], v[38:41]
	v_mfma_f32_16x16x32_bf16 v[34:37], v[174:177], v[190:193], v[34:37]
	v_mfma_f32_16x16x32_bf16 v[22:25], v[146:149], v[204:207], v[22:25]
	v_mfma_f32_16x16x32_bf16 v[18:21], v[174:177], v[204:207], v[18:21]
	v_mfma_f32_16x16x32_bf16 v[6:9], v[146:149], v[212:215], v[6:9]
	v_mfma_f32_16x16x32_bf16 v[2:5], v[174:177], v[212:215], v[2:5]
	v_mfma_f32_16x16x32_bf16 v[54:57], v[150:153], v[186:189], v[54:57]
	v_mfma_f32_16x16x32_bf16 v[50:53], v[178:181], v[186:189], v[50:53]
	v_mfma_f32_16x16x32_bf16 v[38:41], v[150:153], v[194:197], v[38:41]
	v_mfma_f32_16x16x32_bf16 v[34:37], v[178:181], v[194:197], v[34:37]
	v_mfma_f32_16x16x32_bf16 v[22:25], v[150:153], v[208:211], v[22:25]
	v_mfma_f32_16x16x32_bf16 v[18:21], v[178:181], v[208:211], v[18:21]
	v_mfma_f32_16x16x32_bf16 v[6:9], v[150:153], v[222:225], v[6:9]
	v_mfma_f32_16x16x32_bf16 v[2:5], v[178:181], v[222:225], v[2:5]
	s_setprio 0
	s_barrier
	s_add_i32 s78, s78, 2
	s_add_u32 s25, s25, 0x100
	s_addc_u32 s62, s62, 0
	s_add_u32 s56, s56, 0x100
	s_addc_u32 s57, s57, 0
	s_cmp_gt_u32 s78, 29
	s_cbranch_scc0 .LBB0_1211
	s_and_b64 vcc, exec, s[18:19]
	s_cbranch_vccz .LBB0_1214
	s_barrier

.LBB0_1332:
	s_add_u32 s26, s24, 0xfffc0080
	s_addc_u32 s27, s25, -1
	s_add_i32 s36, 0, 0x10000
	s_cmp_eq_u32 s21, 12
	s_cselect_b32 s57, s17, s27
	s_cselect_b32 s56, s16, s26
	v_add_u32_e32 v142, s36, v161
	s_cselect_b32 s27, s19, s15
	s_cselect_b32 s26, s18, s13
	s_add_i32 s38, 0, 0x14000
	ds_read_b128 v[144:147], v142
	ds_read_b128 v[148:151], v142 offset:1024
	ds_read_b128 v[152:155], v142 offset:2048
	ds_read_b128 v[178:181], v142 offset:3072
	v_add_u32_e32 v142, s38, v161
	ds_read_b128 v[182:185], v142
	ds_read_b128 v[186:189], v142 offset:1024
	ds_read_b128 v[190:193], v142 offset:2048
	ds_read_b128 v[194:197], v142 offset:3072
	v_lshl_add_u64 v[156:157], s[24:25], 0, v[140:141]
	s_add_i32 m0, s69, 0xc000
	ds_read_b128 v[198:201], v177
	ds_read_b128 v[202:205], v177 offset:1024
	ds_read_b128 v[206:209], v177 offset:2048
	ds_read_b128 v[210:213], v177 offset:3072
	ds_read_b128 v[214:217], v177 offset:4096
	ds_read_b128 v[222:225], v177 offset:5120
	ds_read_b128 v[226:229], v177 offset:6144
	ds_read_b128 v[230:233], v177 offset:7168
	global_load_lds_dwordx4 v[156:157], off
	v_lshl_add_u64 v[156:157], s[24:25], 0, v[138:139]
	s_add_i32 m0, s69, 0xe000
	s_nop 0
	global_load_lds_dwordx4 v[156:157], off
	s_waitcnt vmcnt(8)
	s_waitcnt lgkmcnt(0)
	s_barrier
	s_setprio 1
	v_mfma_i32_16x16x64_i8 v[126:129], v[144:147], v[198:201], v[126:129]
	v_mfma_i32_16x16x64_i8 v[118:121], v[152:155], v[198:201], v[118:121]
	v_mfma_i32_16x16x64_i8 v[110:113], v[144:147], v[206:209], v[110:113]
	v_mfma_i32_16x16x64_i8 v[102:105], v[152:155], v[206:209], v[102:105]
	v_mfma_i32_16x16x64_i8 v[94:97], v[144:147], v[214:217], v[94:97]
	v_mfma_i32_16x16x64_i8 v[86:89], v[152:155], v[214:217], v[86:89]
	v_mfma_i32_16x16x64_i8 v[78:81], v[144:147], v[226:229], v[78:81]
	v_mfma_i32_16x16x64_i8 v[70:73], v[152:155], v[226:229], v[70:73]
	v_mfma_i32_16x16x64_i8 v[126:129], v[148:151], v[202:205], v[126:129]
	v_mfma_i32_16x16x64_i8 v[118:121], v[178:181], v[202:205], v[118:121]
	v_mfma_i32_16x16x64_i8 v[110:113], v[148:151], v[210:213], v[110:113]
	v_mfma_i32_16x16x64_i8 v[102:105], v[178:181], v[210:213], v[102:105]
	v_mfma_i32_16x16x64_i8 v[94:97], v[148:151], v[222:225], v[94:97]
	v_mfma_i32_16x16x64_i8 v[86:89], v[178:181], v[222:225], v[86:89]
	v_mfma_i32_16x16x64_i8 v[78:81], v[148:151], v[230:233], v[78:81]
	v_mfma_i32_16x16x64_i8 v[70:73], v[178:181], v[230:233], v[70:73]
	v_mfma_i32_16x16x64_i8 v[122:125], v[182:185], v[198:201], v[122:125]
	v_mfma_i32_16x16x64_i8 v[114:117], v[190:193], v[198:201], v[114:117]
	v_mfma_i32_16x16x64_i8 v[106:109], v[182:185], v[206:209], v[106:109]
	v_mfma_i32_16x16x64_i8 v[98:101], v[190:193], v[206:209], v[98:101]
	v_mfma_i32_16x16x64_i8 v[90:93], v[182:185], v[214:217], v[90:93]
	v_mfma_i32_16x16x64_i8 v[82:85], v[190:193], v[214:217], v[82:85]
	v_mfma_i32_16x16x64_i8 v[74:77], v[182:185], v[226:229], v[74:77]
	v_mfma_i32_16x16x64_i8 v[66:69], v[190:193], v[226:229], v[66:69]
	v_mfma_i32_16x16x64_i8 v[122:125], v[186:189], v[202:205], v[122:125]
	v_mfma_i32_16x16x64_i8 v[114:117], v[194:197], v[202:205], v[114:117]
	v_mfma_i32_16x16x64_i8 v[106:109], v[186:189], v[210:213], v[106:109]
	v_mfma_i32_16x16x64_i8 v[98:101], v[194:197], v[210:213], v[98:101]
	v_mfma_i32_16x16x64_i8 v[90:93], v[186:189], v[222:225], v[90:93]
	v_mfma_i32_16x16x64_i8 v[82:85], v[194:197], v[222:225], v[82:85]
	v_mfma_i32_16x16x64_i8 v[74:77], v[186:189], v[230:233], v[74:77]
	v_mfma_i32_16x16x64_i8 v[66:69], v[194:197], v[230:233], v[66:69]
	s_setprio 0
	s_barrier
	s_add_i32 s36, s36, s23
	v_lshl_add_u64 v[156:157], s[26:27], 0, v[162:163]
	s_mov_b32 m0, s36
	ds_read_b128 v[198:201], v177 offset:16384
	ds_read_b128 v[202:205], v177 offset:17408
	ds_read_b128 v[206:209], v177 offset:18432
	ds_read_b128 v[210:213], v177 offset:19456
	ds_read_b128 v[214:217], v177 offset:20480
	ds_read_b128 v[222:225], v177 offset:21504
	ds_read_b128 v[226:229], v177 offset:22528
	ds_read_b128 v[230:233], v177 offset:23552
	global_load_lds_dwordx4 v[156:157], off
	s_add_i32 m0, s36, 0x2000
	s_add_u32 s36, s26, 0x80000
	v_lshl_add_u64 v[168:169], s[26:27], 0, v[134:135]
	s_addc_u32 s37, s27, 0
	s_add_i32 s38, s38, s23
	global_load_lds_dwordx4 v[168:169], off
	v_lshl_add_u64 v[170:171], s[36:37], 0, v[162:163]
	s_mov_b32 m0, s38
	v_lshl_add_u64 v[174:175], s[56:57], 0, v[132:133]
	global_load_lds_dwordx4 v[170:171], off
	v_lshl_add_u64 v[170:171], s[36:37], 0, v[134:135]
	s_add_i32 m0, s38, 0x2000
	s_nop 0
	global_load_lds_dwordx4 v[170:171], off
	v_lshl_add_u64 v[170:171], s[56:57], 0, v[130:131]
	s_mov_b32 m0, s69
	s_nop 0
	global_load_lds_dwordx4 v[170:171], off
	s_mov_b32 m0, s70
	s_nop 0
	global_load_lds_dwordx4 v[174:175], off
	s_waitcnt vmcnt(8)
	s_waitcnt lgkmcnt(0)
	s_barrier
	s_setprio 1
	v_mfma_i32_16x16x64_i8 v[62:65], v[144:147], v[198:201], v[62:65]
	v_mfma_i32_16x16x64_i8 v[54:57], v[152:155], v[198:201], v[54:57]
	v_mfma_i32_16x16x64_i8 v[46:49], v[144:147], v[206:209], v[46:49]
	v_mfma_i32_16x16x64_i8 v[38:41], v[152:155], v[206:209], v[38:41]
	v_mfma_i32_16x16x64_i8 v[30:33], v[144:147], v[214:217], v[30:33]
	v_mfma_i32_16x16x64_i8 v[22:25], v[152:155], v[214:217], v[22:25]
	v_mfma_i32_16x16x64_i8 v[14:17], v[144:147], v[226:229], v[14:17]
	v_mfma_i32_16x16x64_i8 v[6:9], v[152:155], v[226:229], v[6:9]
	v_mfma_i32_16x16x64_i8 v[62:65], v[148:151], v[202:205], v[62:65]
	v_mfma_i32_16x16x64_i8 v[54:57], v[178:181], v[202:205], v[54:57]
	v_mfma_i32_16x16x64_i8 v[46:49], v[148:151], v[210:213], v[46:49]
	v_mfma_i32_16x16x64_i8 v[38:41], v[178:181], v[210:213], v[38:41]
	v_mfma_i32_16x16x64_i8 v[30:33], v[148:151], v[222:225], v[30:33]
	v_mfma_i32_16x16x64_i8 v[22:25], v[178:181], v[222:225], v[22:25]
	v_mfma_i32_16x16x64_i8 v[14:17], v[148:151], v[230:233], v[14:17]
	v_mfma_i32_16x16x64_i8 v[6:9], v[178:181], v[230:233], v[6:9]
	v_mfma_i32_16x16x64_i8 v[58:61], v[182:185], v[198:201], v[58:61]
	v_mfma_i32_16x16x64_i8 v[50:53], v[190:193], v[198:201], v[50:53]
	v_mfma_i32_16x16x64_i8 v[42:45], v[182:185], v[206:209], v[42:45]
	v_mfma_i32_16x16x64_i8 v[34:37], v[190:193], v[206:209], v[34:37]
	v_mfma_i32_16x16x64_i8 v[26:29], v[182:185], v[214:217], v[26:29]
	v_mfma_i32_16x16x64_i8 v[18:21], v[190:193], v[214:217], v[18:21]
	v_mfma_i32_16x16x64_i8 v[10:13], v[182:185], v[226:229], v[10:13]
	v_mfma_i32_16x16x64_i8 v[2:5], v[190:193], v[226:229], v[2:5]
	v_mfma_i32_16x16x64_i8 v[58:61], v[186:189], v[202:205], v[58:61]
	v_mfma_i32_16x16x64_i8 v[50:53], v[194:197], v[202:205], v[50:53]
	v_mfma_i32_16x16x64_i8 v[42:45], v[186:189], v[210:213], v[42:45]
	v_mfma_i32_16x16x64_i8 v[34:37], v[194:197], v[210:213], v[34:37]
	v_mfma_i32_16x16x64_i8 v[26:29], v[186:189], v[222:225], v[26:29]
	v_mfma_i32_16x16x64_i8 v[18:21], v[194:197], v[222:225], v[18:21]
	v_mfma_i32_16x16x64_i8 v[10:13], v[186:189], v[230:233], v[10:13]
	v_mfma_i32_16x16x64_i8 v[2:5], v[194:197], v[230:233], v[2:5]
	s_setprio 0
	s_barrier
	s_add_i32 s38, 0, 0x18000
	v_add_u32_e32 v142, s38, v161
	s_add_i32 s39, 0, 0x1c000
	ds_read_b128 v[144:147], v142
	ds_read_b128 v[148:151], v142 offset:1024
	ds_read_b128 v[152:155], v142 offset:2048
	ds_read_b128 v[178:181], v142 offset:3072
	v_add_u32_e32 v142, s39, v161
	ds_read_b128 v[182:185], v142
	ds_read_b128 v[186:189], v142 offset:1024
	ds_read_b128 v[190:193], v142 offset:2048
	ds_read_b128 v[194:197], v142 offset:3072
	s_add_u32 s36, s56, 0x40000
	s_addc_u32 s37, s57, 0
	s_mov_b32 m0, s71
	v_lshl_add_u64 v[234:235], s[36:37], 0, v[130:131]
	ds_read_b128 v[198:201], v177 offset:32768
	ds_read_b128 v[202:205], v177 offset:33792
	ds_read_b128 v[206:209], v177 offset:34816
	ds_read_b128 v[210:213], v177 offset:35840
	ds_read_b128 v[214:217], v177 offset:36864
	ds_read_b128 v[222:225], v177 offset:37888
	ds_read_b128 v[226:229], v177 offset:38912
	ds_read_b128 v[230:233], v177 offset:39936
	global_load_lds_dwordx4 v[234:235], off
	v_lshl_add_u64 v[234:235], s[36:37], 0, v[132:133]
	s_mov_b32 m0, s72
	s_nop 0
	global_load_lds_dwordx4 v[234:235], off
	s_waitcnt vmcnt(8)
	s_waitcnt lgkmcnt(0)
	s_barrier
	s_setprio 1
	v_mfma_i32_16x16x64_i8 v[126:129], v[144:147], v[198:201], v[126:129]
	v_mfma_i32_16x16x64_i8 v[118:121], v[152:155], v[198:201], v[118:121]
	v_mfma_i32_16x16x64_i8 v[110:113], v[144:147], v[206:209], v[110:113]
	v_mfma_i32_16x16x64_i8 v[102:105], v[152:155], v[206:209], v[102:105]
	v_mfma_i32_16x16x64_i8 v[94:97], v[144:147], v[214:217], v[94:97]
	v_mfma_i32_16x16x64_i8 v[86:89], v[152:155], v[214:217], v[86:89]
	v_mfma_i32_16x16x64_i8 v[78:81], v[144:147], v[226:229], v[78:81]
	v_mfma_i32_16x16x64_i8 v[70:73], v[152:155], v[226:229], v[70:73]
	v_mfma_i32_16x16x64_i8 v[126:129], v[148:151], v[202:205], v[126:129]
	v_mfma_i32_16x16x64_i8 v[118:121], v[178:181], v[202:205], v[118:121]
	v_mfma_i32_16x16x64_i8 v[110:113], v[148:151], v[210:213], v[110:113]
	v_mfma_i32_16x16x64_i8 v[102:105], v[178:181], v[210:213], v[102:105]
	v_mfma_i32_16x16x64_i8 v[94:97], v[148:151], v[222:225], v[94:97]
	v_mfma_i32_16x16x64_i8 v[86:89], v[178:181], v[222:225], v[86:89]
	v_mfma_i32_16x16x64_i8 v[78:81], v[148:151], v[230:233], v[78:81]
	v_mfma_i32_16x16x64_i8 v[70:73], v[178:181], v[230:233], v[70:73]
	v_mfma_i32_16x16x64_i8 v[122:125], v[182:185], v[198:201], v[122:125]
	v_mfma_i32_16x16x64_i8 v[114:117], v[190:193], v[198:201], v[114:117]
	v_mfma_i32_16x16x64_i8 v[106:109], v[182:185], v[206:209], v[106:109]
	v_mfma_i32_16x16x64_i8 v[98:101], v[190:193], v[206:209], v[98:101]
	v_mfma_i32_16x16x64_i8 v[90:93], v[182:185], v[214:217], v[90:93]
	v_mfma_i32_16x16x64_i8 v[82:85], v[190:193], v[214:217], v[82:85]
	v_mfma_i32_16x16x64_i8 v[74:77], v[182:185], v[226:229], v[74:77]
	v_mfma_i32_16x16x64_i8 v[66:69], v[190:193], v[226:229], v[66:69]
	v_mfma_i32_16x16x64_i8 v[122:125], v[186:189], v[202:205], v[122:125]
	v_mfma_i32_16x16x64_i8 v[114:117], v[194:197], v[202:205], v[114:117]
	v_mfma_i32_16x16x64_i8 v[106:109], v[186:189], v[210:213], v[106:109]
	v_mfma_i32_16x16x64_i8 v[98:101], v[194:197], v[210:213], v[98:101]
	v_mfma_i32_16x16x64_i8 v[90:93], v[186:189], v[222:225], v[90:93]
	v_mfma_i32_16x16x64_i8 v[82:85], v[194:197], v[222:225], v[82:85]
	v_mfma_i32_16x16x64_i8 v[74:77], v[186:189], v[230:233], v[74:77]
	v_mfma_i32_16x16x64_i8 v[66:69], v[194:197], v[230:233], v[66:69]
	s_setprio 0
	s_barrier
	s_add_i32 s36, s38, s23
	v_lshl_add_u64 v[156:157], v[156:157], 0, s[44:45]
	s_mov_b32 m0, s36
	ds_read_b128 v[198:201], v177 offset:49152
	ds_read_b128 v[202:205], v177 offset:50176
	ds_read_b128 v[206:209], v177 offset:51200
	ds_read_b128 v[210:213], v177 offset:52224
	ds_read_b128 v[214:217], v177 offset:53248
	ds_read_b128 v[222:225], v177 offset:54272
	ds_read_b128 v[226:229], v177 offset:55296
	ds_read_b128 v[230:233], v177 offset:56320
	global_load_lds_dwordx4 v[156:157], off
	s_add_i32 m0, s36, 0x2000
	s_add_u32 s26, s26, 0x80080
	v_lshl_add_u64 v[156:157], v[168:169], 0, s[44:45]
	s_addc_u32 s27, s27, 0
	s_add_i32 s36, s39, s23
	global_load_lds_dwordx4 v[156:157], off
	v_lshl_add_u64 v[156:157], s[26:27], 0, v[162:163]
	s_mov_b32 m0, s36
	s_nop 0
	global_load_lds_dwordx4 v[156:157], off
	v_lshl_add_u64 v[156:157], s[26:27], 0, v[134:135]
	s_add_i32 m0, s36, 0x2000
	s_nop 0
	global_load_lds_dwordx4 v[156:157], off
	v_lshl_add_u64 v[156:157], v[170:171], 0, s[44:45]
	s_mov_b32 m0, s73
	s_nop 0
	global_load_lds_dwordx4 v[156:157], off
	v_lshl_add_u64 v[156:157], v[174:175], 0, s[44:45]
	s_mov_b32 m0, s74
	s_nop 0
	global_load_lds_dwordx4 v[156:157], off
	s_waitcnt vmcnt(8)
	s_waitcnt lgkmcnt(0)
	s_barrier
	s_setprio 1
	v_mfma_i32_16x16x64_i8 v[62:65], v[144:147], v[198:201], v[62:65]
	v_mfma_i32_16x16x64_i8 v[54:57], v[152:155], v[198:201], v[54:57]
	v_mfma_i32_16x16x64_i8 v[46:49], v[144:147], v[206:209], v[46:49]
	v_mfma_i32_16x16x64_i8 v[38:41], v[152:155], v[206:209], v[38:41]
	v_mfma_i32_16x16x64_i8 v[30:33], v[144:147], v[214:217], v[30:33]
	v_mfma_i32_16x16x64_i8 v[22:25], v[152:155], v[214:217], v[22:25]
	v_mfma_i32_16x16x64_i8 v[14:17], v[144:147], v[226:229], v[14:17]
	v_mfma_i32_16x16x64_i8 v[6:9], v[152:155], v[226:229], v[6:9]
	v_mfma_i32_16x16x64_i8 v[62:65], v[148:151], v[202:205], v[62:65]
	v_mfma_i32_16x16x64_i8 v[54:57], v[178:181], v[202:205], v[54:57]
	v_mfma_i32_16x16x64_i8 v[46:49], v[148:151], v[210:213], v[46:49]
	v_mfma_i32_16x16x64_i8 v[38:41], v[178:181], v[210:213], v[38:41]
	v_mfma_i32_16x16x64_i8 v[30:33], v[148:151], v[222:225], v[30:33]
	v_mfma_i32_16x16x64_i8 v[22:25], v[178:181], v[222:225], v[22:25]
	v_mfma_i32_16x16x64_i8 v[14:17], v[148:151], v[230:233], v[14:17]
	v_mfma_i32_16x16x64_i8 v[6:9], v[178:181], v[230:233], v[6:9]
	v_mfma_i32_16x16x64_i8 v[58:61], v[182:185], v[198:201], v[58:61]
	v_mfma_i32_16x16x64_i8 v[50:53], v[190:193], v[198:201], v[50:53]
	v_mfma_i32_16x16x64_i8 v[42:45], v[182:185], v[206:209], v[42:45]
	v_mfma_i32_16x16x64_i8 v[34:37], v[190:193], v[206:209], v[34:37]
	v_mfma_i32_16x16x64_i8 v[26:29], v[182:185], v[214:217], v[26:29]
	v_mfma_i32_16x16x64_i8 v[18:21], v[190:193], v[214:217], v[18:21]
	v_mfma_i32_16x16x64_i8 v[10:13], v[182:185], v[226:229], v[10:13]
	v_mfma_i32_16x16x64_i8 v[2:5], v[190:193], v[226:229], v[2:5]
	v_mfma_i32_16x16x64_i8 v[58:61], v[186:189], v[202:205], v[58:61]
	v_mfma_i32_16x16x64_i8 v[50:53], v[194:197], v[202:205], v[50:53]
	v_mfma_i32_16x16x64_i8 v[42:45], v[186:189], v[210:213], v[42:45]
	v_mfma_i32_16x16x64_i8 v[34:37], v[194:197], v[210:213], v[34:37]
	v_mfma_i32_16x16x64_i8 v[26:29], v[186:189], v[222:225], v[26:29]
	v_mfma_i32_16x16x64_i8 v[18:21], v[194:197], v[222:225], v[18:21]
	v_mfma_i32_16x16x64_i8 v[10:13], v[186:189], v[230:233], v[10:13]
	v_mfma_i32_16x16x64_i8 v[2:5], v[194:197], v[230:233], v[2:5]
	s_setprio 0
	s_barrier
	s_add_i32 s21, s21, 2
	s_add_u32 s13, s13, 0x100
	s_addc_u32 s15, s15, 0
	s_add_u32 s24, s24, 0x100
	s_addc_u32 s25, s25, 0
	s_cmp_gt_u32 s21, 13
	s_cbranch_scc0 .LBB0_1332
	s_and_b64 vcc, exec, s[10:11]
	s_cbranch_vccz .LBB0_1335
	s_barrier

.LBB0_1446:
	s_add_u32 s8, s26, 0x4000
	s_addc_u32 s9, s27, 0
	s_cmpk_eq_i32 s84, 0x54
	s_cselect_b32 s60, s22, s8
	s_cselect_b32 s61, s23, s9
	s_cselect_b32 s58, s24, s82
	s_cselect_b32 s59, s25, s83
	s_add_u32 s56, s60, 0x8000
	s_addc_u32 s57, s61, 0
	s_add_i32 s8, 0, 0x10000
	s_add_i32 s36, 0, 0x14000
	v_add_u32_e32 v142, s8, v201
	v_add_u32_e32 v168, s36, v201
	ds_read_b128 v[110:113], v142
	ds_read_b128 v[118:121], v142 offset:1024
	ds_read_b128 v[138:141], v142 offset:2048
	ds_read_b128 v[142:145], v142 offset:3072
	ds_read_b128 v[146:149], v168
	ds_read_b128 v[150:153], v168 offset:1024
	ds_read_b128 v[174:177], v168 offset:2048
	ds_read_b128 v[178:181], v168 offset:3072
	v_lshl_add_u64 v[168:169], s[26:27], 0, v[172:173]
	s_add_i32 m0, s65, 0xc000
	ds_read_b128 v[182:185], v203
	ds_read_b128 v[186:189], v203 offset:1024
	ds_read_b128 v[190:193], v203 offset:2048
	ds_read_b128 v[194:197], v203 offset:3072
	ds_read_b128 v[204:207], v203 offset:4096
	ds_read_b128 v[208:211], v203 offset:5120
	ds_read_b128 v[212:215], v203 offset:6144
	ds_read_b128 v[222:225], v203 offset:7168
	global_load_lds_dwordx4 v[168:169], off
	v_lshl_add_u64 v[168:169], s[26:27], 0, v[160:161]
	s_add_i32 m0, s65, 0xe000
	s_nop 0
	global_load_lds_dwordx4 v[168:169], off
	s_waitcnt vmcnt(8)
	s_waitcnt lgkmcnt(0)
	s_barrier
	s_setprio 1
	v_mfma_f32_16x16x32_bf16 v[134:137], v[110:113], v[182:185], v[134:137]
	v_mfma_f32_16x16x32_bf16 v[130:133], v[138:141], v[182:185], v[130:133]
	v_mfma_f32_16x16x32_bf16 v[114:117], v[110:113], v[190:193], v[114:117]
	v_mfma_f32_16x16x32_bf16 v[106:109], v[138:141], v[190:193], v[106:109]
	v_mfma_f32_16x16x32_bf16 v[94:97], v[110:113], v[204:207], v[94:97]
	v_mfma_f32_16x16x32_bf16 v[90:93], v[138:141], v[204:207], v[90:93]
	v_mfma_f32_16x16x32_bf16 v[78:81], v[110:113], v[212:215], v[78:81]
	v_mfma_f32_16x16x32_bf16 v[74:77], v[138:141], v[212:215], v[74:77]
	v_mfma_f32_16x16x32_bf16 v[134:137], v[118:121], v[186:189], v[134:137]
	v_mfma_f32_16x16x32_bf16 v[130:133], v[142:145], v[186:189], v[130:133]
	v_mfma_f32_16x16x32_bf16 v[114:117], v[118:121], v[194:197], v[114:117]
	v_mfma_f32_16x16x32_bf16 v[106:109], v[142:145], v[194:197], v[106:109]
	v_mfma_f32_16x16x32_bf16 v[94:97], v[118:121], v[208:211], v[94:97]
	v_mfma_f32_16x16x32_bf16 v[90:93], v[142:145], v[208:211], v[90:93]
	v_mfma_f32_16x16x32_bf16 v[78:81], v[118:121], v[222:225], v[78:81]
	v_mfma_f32_16x16x32_bf16 v[74:77], v[142:145], v[222:225], v[74:77]
	v_mfma_f32_16x16x32_bf16 v[126:129], v[146:149], v[182:185], v[126:129]
	v_mfma_f32_16x16x32_bf16 v[122:125], v[174:177], v[182:185], v[122:125]
	v_mfma_f32_16x16x32_bf16 v[102:105], v[146:149], v[190:193], v[102:105]
	v_mfma_f32_16x16x32_bf16 v[98:101], v[174:177], v[190:193], v[98:101]
	v_mfma_f32_16x16x32_bf16 v[86:89], v[146:149], v[204:207], v[86:89]
	v_mfma_f32_16x16x32_bf16 v[82:85], v[174:177], v[204:207], v[82:85]
	v_mfma_f32_16x16x32_bf16 v[70:73], v[146:149], v[212:215], v[70:73]
	v_mfma_f32_16x16x32_bf16 v[66:69], v[174:177], v[212:215], v[66:69]
	v_mfma_f32_16x16x32_bf16 v[126:129], v[150:153], v[186:189], v[126:129]
	v_mfma_f32_16x16x32_bf16 v[122:125], v[178:181], v[186:189], v[122:125]
	v_mfma_f32_16x16x32_bf16 v[102:105], v[150:153], v[194:197], v[102:105]
	v_mfma_f32_16x16x32_bf16 v[98:101], v[178:181], v[194:197], v[98:101]
	v_mfma_f32_16x16x32_bf16 v[86:89], v[150:153], v[208:211], v[86:89]
	v_mfma_f32_16x16x32_bf16 v[82:85], v[178:181], v[208:211], v[82:85]
	v_mfma_f32_16x16x32_bf16 v[70:73], v[150:153], v[222:225], v[70:73]
	v_mfma_f32_16x16x32_bf16 v[66:69], v[178:181], v[222:225], v[66:69]
	s_setprio 0
	s_barrier
	s_add_i32 s8, s8, s64
	v_lshl_add_u64 v[168:169], s[58:59], 0, v[162:163]
	s_mov_b32 m0, s8
	ds_read_b128 v[182:185], v203 offset:16384
	ds_read_b128 v[186:189], v203 offset:17408
	ds_read_b128 v[190:193], v203 offset:18432
	ds_read_b128 v[194:197], v203 offset:19456
	ds_read_b128 v[204:207], v203 offset:20480
	ds_read_b128 v[208:211], v203 offset:21504
	ds_read_b128 v[212:215], v203 offset:22528
	ds_read_b128 v[222:225], v203 offset:23552
	global_load_lds_dwordx4 v[168:169], off
	s_add_i32 m0, s8, 0x2000
	s_add_u32 s8, s58, 0x160000
	v_lshl_add_u64 v[170:171], s[58:59], 0, v[158:159]
	s_addc_u32 s9, s59, 0
	s_add_i32 s36, s36, s64
	global_load_lds_dwordx4 v[170:171], off
	v_lshl_add_u64 v[198:199], s[8:9], 0, v[162:163]
	s_mov_b32 m0, s36
	s_nop 0
	global_load_lds_dwordx4 v[198:199], off
	v_lshl_add_u64 v[198:199], s[8:9], 0, v[158:159]
	s_add_i32 m0, s36, 0x2000
	s_nop 0
	global_load_lds_dwordx4 v[198:199], off
	v_lshl_add_u64 v[198:199], s[60:61], 0, v[154:155]
	s_mov_b32 m0, s65
	s_nop 0
	global_load_lds_dwordx4 v[198:199], off
	v_lshl_add_u64 v[198:199], s[60:61], 0, v[156:157]
	s_mov_b32 m0, s66
	s_nop 0
	global_load_lds_dwordx4 v[198:199], off
	s_waitcnt vmcnt(8)
	s_waitcnt lgkmcnt(0)
	s_barrier
	s_setprio 1
	v_mfma_f32_16x16x32_bf16 v[62:65], v[110:113], v[182:185], v[62:65]
	v_mfma_f32_16x16x32_bf16 v[58:61], v[138:141], v[182:185], v[58:61]
	v_mfma_f32_16x16x32_bf16 v[46:49], v[110:113], v[190:193], v[46:49]
	v_mfma_f32_16x16x32_bf16 v[42:45], v[138:141], v[190:193], v[42:45]
	v_mfma_f32_16x16x32_bf16 v[30:33], v[110:113], v[204:207], v[30:33]
	v_mfma_f32_16x16x32_bf16 v[26:29], v[138:141], v[204:207], v[26:29]
	v_mfma_f32_16x16x32_bf16 v[14:17], v[110:113], v[212:215], v[14:17]
	v_mfma_f32_16x16x32_bf16 v[10:13], v[138:141], v[212:215], v[10:13]
	v_mfma_f32_16x16x32_bf16 v[62:65], v[118:121], v[186:189], v[62:65]
	v_mfma_f32_16x16x32_bf16 v[58:61], v[142:145], v[186:189], v[58:61]
	v_mfma_f32_16x16x32_bf16 v[46:49], v[118:121], v[194:197], v[46:49]
	v_mfma_f32_16x16x32_bf16 v[42:45], v[142:145], v[194:197], v[42:45]
	v_mfma_f32_16x16x32_bf16 v[30:33], v[118:121], v[208:211], v[30:33]
	v_mfma_f32_16x16x32_bf16 v[26:29], v[142:145], v[208:211], v[26:29]
	v_mfma_f32_16x16x32_bf16 v[14:17], v[118:121], v[222:225], v[14:17]
	v_mfma_f32_16x16x32_bf16 v[10:13], v[142:145], v[222:225], v[10:13]
	v_mfma_f32_16x16x32_bf16 v[54:57], v[146:149], v[182:185], v[54:57]
	v_mfma_f32_16x16x32_bf16 v[50:53], v[174:177], v[182:185], v[50:53]
	v_mfma_f32_16x16x32_bf16 v[38:41], v[146:149], v[190:193], v[38:41]
	v_mfma_f32_16x16x32_bf16 v[34:37], v[174:177], v[190:193], v[34:37]
	v_mfma_f32_16x16x32_bf16 v[22:25], v[146:149], v[204:207], v[22:25]
	v_mfma_f32_16x16x32_bf16 v[18:21], v[174:177], v[204:207], v[18:21]
	v_mfma_f32_16x16x32_bf16 v[6:9], v[146:149], v[212:215], v[6:9]
	v_mfma_f32_16x16x32_bf16 v[2:5], v[174:177], v[212:215], v[2:5]
	v_mfma_f32_16x16x32_bf16 v[54:57], v[150:153], v[186:189], v[54:57]
	v_mfma_f32_16x16x32_bf16 v[50:53], v[178:181], v[186:189], v[50:53]
	v_mfma_f32_16x16x32_bf16 v[38:41], v[150:153], v[194:197], v[38:41]
	v_mfma_f32_16x16x32_bf16 v[34:37], v[178:181], v[194:197], v[34:37]
	v_mfma_f32_16x16x32_bf16 v[22:25], v[150:153], v[208:211], v[22:25]
	v_mfma_f32_16x16x32_bf16 v[18:21], v[178:181], v[208:211], v[18:21]
	v_mfma_f32_16x16x32_bf16 v[6:9], v[150:153], v[222:225], v[6:9]
	v_mfma_f32_16x16x32_bf16 v[2:5], v[178:181], v[222:225], v[2:5]
	s_setprio 0
	s_barrier
	s_add_i32 s36, 0, 0x18000
	s_add_i32 s37, 0, 0x1c000
	v_add_u32_e32 v142, s36, v201
	v_add_u32_e32 v178, s37, v201
	ds_read_b128 v[110:113], v142
	ds_read_b128 v[118:121], v142 offset:1024
	ds_read_b128 v[138:141], v142 offset:2048
	ds_read_b128 v[142:145], v142 offset:3072
	ds_read_b128 v[146:149], v178
	ds_read_b128 v[150:153], v178 offset:1024
	ds_read_b128 v[174:177], v178 offset:2048
	ds_read_b128 v[178:181], v178 offset:3072
	s_add_u32 s8, s60, 0x4000
	s_addc_u32 s9, s61, 0
	s_mov_b32 m0, s67
	v_lshl_add_u64 v[198:199], s[8:9], 0, v[154:155]
	ds_read_b128 v[182:185], v203 offset:32768
	ds_read_b128 v[186:189], v203 offset:33792
	ds_read_b128 v[190:193], v203 offset:34816
	ds_read_b128 v[194:197], v203 offset:35840
	ds_read_b128 v[204:207], v203 offset:36864
	ds_read_b128 v[208:211], v203 offset:37888
	ds_read_b128 v[212:215], v203 offset:38912
	ds_read_b128 v[222:225], v203 offset:39936
	global_load_lds_dwordx4 v[198:199], off
	v_lshl_add_u64 v[198:199], s[8:9], 0, v[156:157]
	s_mov_b32 m0, s68
	s_nop 0
	global_load_lds_dwordx4 v[198:199], off
	s_waitcnt vmcnt(8)
	s_waitcnt lgkmcnt(0)
	s_barrier
	s_setprio 1
	v_mfma_f32_16x16x32_bf16 v[134:137], v[110:113], v[182:185], v[134:137]
	v_mfma_f32_16x16x32_bf16 v[130:133], v[138:141], v[182:185], v[130:133]
	v_mfma_f32_16x16x32_bf16 v[114:117], v[110:113], v[190:193], v[114:117]
	v_mfma_f32_16x16x32_bf16 v[106:109], v[138:141], v[190:193], v[106:109]
	v_mfma_f32_16x16x32_bf16 v[94:97], v[110:113], v[204:207], v[94:97]
	v_mfma_f32_16x16x32_bf16 v[90:93], v[138:141], v[204:207], v[90:93]
	v_mfma_f32_16x16x32_bf16 v[78:81], v[110:113], v[212:215], v[78:81]
	v_mfma_f32_16x16x32_bf16 v[74:77], v[138:141], v[212:215], v[74:77]
	v_mfma_f32_16x16x32_bf16 v[134:137], v[118:121], v[186:189], v[134:137]
	v_mfma_f32_16x16x32_bf16 v[130:133], v[142:145], v[186:189], v[130:133]
	v_mfma_f32_16x16x32_bf16 v[114:117], v[118:121], v[194:197], v[114:117]
	v_mfma_f32_16x16x32_bf16 v[106:109], v[142:145], v[194:197], v[106:109]
	v_mfma_f32_16x16x32_bf16 v[94:97], v[118:121], v[208:211], v[94:97]
	v_mfma_f32_16x16x32_bf16 v[90:93], v[142:145], v[208:211], v[90:93]
	v_mfma_f32_16x16x32_bf16 v[78:81], v[118:121], v[222:225], v[78:81]
	v_mfma_f32_16x16x32_bf16 v[74:77], v[142:145], v[222:225], v[74:77]
	v_mfma_f32_16x16x32_bf16 v[126:129], v[146:149], v[182:185], v[126:129]
	v_mfma_f32_16x16x32_bf16 v[122:125], v[174:177], v[182:185], v[122:125]
	v_mfma_f32_16x16x32_bf16 v[102:105], v[146:149], v[190:193], v[102:105]
	v_mfma_f32_16x16x32_bf16 v[98:101], v[174:177], v[190:193], v[98:101]
	v_mfma_f32_16x16x32_bf16 v[86:89], v[146:149], v[204:207], v[86:89]
	v_mfma_f32_16x16x32_bf16 v[82:85], v[174:177], v[204:207], v[82:85]
	v_mfma_f32_16x16x32_bf16 v[70:73], v[146:149], v[212:215], v[70:73]
	v_mfma_f32_16x16x32_bf16 v[66:69], v[174:177], v[212:215], v[66:69]
	v_mfma_f32_16x16x32_bf16 v[126:129], v[150:153], v[186:189], v[126:129]
	v_mfma_f32_16x16x32_bf16 v[122:125], v[178:181], v[186:189], v[122:125]
	v_mfma_f32_16x16x32_bf16 v[102:105], v[150:153], v[194:197], v[102:105]
	v_mfma_f32_16x16x32_bf16 v[98:101], v[178:181], v[194:197], v[98:101]
	v_mfma_f32_16x16x32_bf16 v[86:89], v[150:153], v[208:211], v[86:89]
	v_mfma_f32_16x16x32_bf16 v[82:85], v[178:181], v[208:211], v[82:85]
	v_mfma_f32_16x16x32_bf16 v[70:73], v[150:153], v[222:225], v[70:73]
	v_mfma_f32_16x16x32_bf16 v[66:69], v[178:181], v[222:225], v[66:69]
	s_setprio 0
	s_barrier
	s_add_i32 s8, s36, s64
	v_lshl_add_u64 v[168:169], v[168:169], 0, s[44:45]
	s_mov_b32 m0, s8
	ds_read_b128 v[182:185], v203 offset:49152
	ds_read_b128 v[186:189], v203 offset:50176
	ds_read_b128 v[190:193], v203 offset:51200
	ds_read_b128 v[194:197], v203 offset:52224
	ds_read_b128 v[204:207], v203 offset:53248
	ds_read_b128 v[208:211], v203 offset:54272
	ds_read_b128 v[212:215], v203 offset:55296
	ds_read_b128 v[222:225], v203 offset:56320
	global_load_lds_dwordx4 v[168:169], off
	s_add_i32 m0, s8, 0x2000
	s_add_u32 s8, s58, 0x160080
	v_lshl_add_u64 v[168:169], v[170:171], 0, s[44:45]
	s_addc_u32 s9, s59, 0
	s_add_i32 s36, s37, s64
	global_load_lds_dwordx4 v[168:169], off
	v_lshl_add_u64 v[168:169], s[8:9], 0, v[162:163]
	s_mov_b32 m0, s36
	s_nop 0
	global_load_lds_dwordx4 v[168:169], off
	v_lshl_add_u64 v[168:169], s[8:9], 0, v[158:159]
	s_add_i32 m0, s36, 0x2000
	s_nop 0
	global_load_lds_dwordx4 v[168:169], off
	v_lshl_add_u64 v[168:169], s[56:57], 0, v[154:155]
	s_mov_b32 m0, s69
	s_nop 0
	global_load_lds_dwordx4 v[168:169], off
	v_lshl_add_u64 v[168:169], s[56:57], 0, v[156:157]
	s_mov_b32 m0, s70
	s_nop 0
	global_load_lds_dwordx4 v[168:169], off
	s_waitcnt vmcnt(8)
	s_waitcnt lgkmcnt(0)
	s_barrier
	s_setprio 1
	v_mfma_f32_16x16x32_bf16 v[62:65], v[110:113], v[182:185], v[62:65]
	v_mfma_f32_16x16x32_bf16 v[58:61], v[138:141], v[182:185], v[58:61]
	v_mfma_f32_16x16x32_bf16 v[46:49], v[110:113], v[190:193], v[46:49]
	v_mfma_f32_16x16x32_bf16 v[42:45], v[138:141], v[190:193], v[42:45]
	v_mfma_f32_16x16x32_bf16 v[30:33], v[110:113], v[204:207], v[30:33]
	v_mfma_f32_16x16x32_bf16 v[26:29], v[138:141], v[204:207], v[26:29]
	v_mfma_f32_16x16x32_bf16 v[14:17], v[110:113], v[212:215], v[14:17]
	v_mfma_f32_16x16x32_bf16 v[10:13], v[138:141], v[212:215], v[10:13]
	v_mfma_f32_16x16x32_bf16 v[62:65], v[118:121], v[186:189], v[62:65]
	v_mfma_f32_16x16x32_bf16 v[58:61], v[142:145], v[186:189], v[58:61]
	v_mfma_f32_16x16x32_bf16 v[46:49], v[118:121], v[194:197], v[46:49]
	v_mfma_f32_16x16x32_bf16 v[42:45], v[142:145], v[194:197], v[42:45]
	v_mfma_f32_16x16x32_bf16 v[30:33], v[118:121], v[208:211], v[30:33]
	v_mfma_f32_16x16x32_bf16 v[26:29], v[142:145], v[208:211], v[26:29]
	v_mfma_f32_16x16x32_bf16 v[14:17], v[118:121], v[222:225], v[14:17]
	v_mfma_f32_16x16x32_bf16 v[10:13], v[142:145], v[222:225], v[10:13]
	v_mfma_f32_16x16x32_bf16 v[54:57], v[146:149], v[182:185], v[54:57]
	v_mfma_f32_16x16x32_bf16 v[50:53], v[174:177], v[182:185], v[50:53]
	v_mfma_f32_16x16x32_bf16 v[38:41], v[146:149], v[190:193], v[38:41]
	v_mfma_f32_16x16x32_bf16 v[34:37], v[174:177], v[190:193], v[34:37]
	v_mfma_f32_16x16x32_bf16 v[22:25], v[146:149], v[204:207], v[22:25]
	v_mfma_f32_16x16x32_bf16 v[18:21], v[174:177], v[204:207], v[18:21]
	v_mfma_f32_16x16x32_bf16 v[6:9], v[146:149], v[212:215], v[6:9]
	v_mfma_f32_16x16x32_bf16 v[2:5], v[174:177], v[212:215], v[2:5]
	v_mfma_f32_16x16x32_bf16 v[54:57], v[150:153], v[186:189], v[54:57]
	v_mfma_f32_16x16x32_bf16 v[50:53], v[178:181], v[186:189], v[50:53]
	v_mfma_f32_16x16x32_bf16 v[38:41], v[150:153], v[194:197], v[38:41]
	v_mfma_f32_16x16x32_bf16 v[34:37], v[178:181], v[194:197], v[34:37]
	v_mfma_f32_16x16x32_bf16 v[22:25], v[150:153], v[208:211], v[22:25]
	v_mfma_f32_16x16x32_bf16 v[18:21], v[178:181], v[208:211], v[18:21]
	v_mfma_f32_16x16x32_bf16 v[6:9], v[150:153], v[222:225], v[6:9]
	v_mfma_f32_16x16x32_bf16 v[2:5], v[178:181], v[222:225], v[2:5]
	s_setprio 0
	s_barrier
	s_add_i32 s84, s84, 2
	s_add_u32 s26, s26, 0x10000
	s_addc_u32 s27, s27, 0
	s_add_u32 s82, s82, 0x100
	s_addc_u32 s83, s83, 0
	s_cmpk_gt_u32 s84, 0x55
	s_cbranch_scc0 .LBB0_1446
	s_and_b64 vcc, exec, s[20:21]
	s_cbranch_vccz .LBB0_1449
	s_barrier

.LBB0_1574:
	s_add_u32 s36, s20, s60
	s_addc_u32 s37, s21, 0
	s_add_u32 s38, s36, 0x100
	s_addc_u32 s39, s37, 0
	s_and_b64 s[8:9], s[58:59], exec
	s_cselect_b32 s63, s25, s39
	s_cselect_b32 s62, s24, s38
	s_add_u32 s8, s22, s60
	s_addc_u32 s9, s23, 0
	s_add_u32 s38, s8, 0x100
	s_addc_u32 s39, s9, 0
	s_add_i32 s31, 0, 0x10000
	s_and_b64 s[8:9], s[58:59], exec
	s_cselect_b32 s65, s27, s39
	s_cselect_b32 s64, s26, s38
	s_add_i32 s38, 0, 0x14000
	s_add_u32 vcc_lo, s36, 0x80080
	s_addc_u32 vcc_hi, s37, 0
	s_add_i32 s8, s31, s72
	s_add_i32 m0, s17, 0xc000
	s_add_i32 s39, s17, 0xe000
	s_add_i32 s36, s8, 0x2000
	v_add_u32_e32 v136, s31, v139
	s_add_u32 s66, s64, 0x90000
	ds_read_b128 v[142:145], v136
	ds_read_b128 v[146:149], v136 offset:1024
	ds_read_b128 v[150:153], v136 offset:2048
	ds_read_b128 v[154:157], v136 offset:3072
	v_add_u32_e32 v136, s38, v139
	s_addc_u32 s67, s65, 0
	s_add_i32 s9, s38, s72
	ds_read_b128 v[158:161], v136
	ds_read_b128 v[172:175], v136 offset:1024
	ds_read_b128 v[176:179], v136 offset:2048
	ds_read_b128 v[180:183], v136 offset:3072
	s_add_i32 s43, s9, 0x2000
	s_add_i32 s89, 0, 0x18000
	s_add_i32 s88, 0, 0x1c000
	s_add_u32 s60, s62, 0x80000
	s_addc_u32 s61, s63, 0
	s_add_i32 s87, s89, s72
	s_add_i32 s86, s87, 0x2000
	s_add_u32 s58, s64, 0x90080
	s_addc_u32 s59, s65, 0
	s_add_i32 s38, s88, s72
	s_add_i32 s37, s38, 0x2000
	v_lshl_add_u64 v[136:137], vcc, 0, v[130:131]
	ds_read_b128 v[184:187], v141
	ds_read_b128 v[188:191], v141 offset:1024
	ds_read_b128 v[192:195], v141 offset:2048
	ds_read_b128 v[196:199], v141 offset:3072
	ds_read_b128 v[200:203], v141 offset:4096
	ds_read_b128 v[204:207], v141 offset:5120
	ds_read_b128 v[208:211], v141 offset:6144
	ds_read_b128 v[212:215], v141 offset:7168
	global_load_lds_dwordx4 v[136:137], off
	v_lshl_add_u64 v[136:137], vcc, 0, v[132:133]
	s_mov_b32 m0, s39
	s_nop 0
	global_load_lds_dwordx4 v[136:137], off
	s_waitcnt vmcnt(8)
	s_waitcnt lgkmcnt(0)
	s_barrier
	s_setprio 1
	v_mfma_f32_16x16x32_bf16 v[126:129], v[142:145], v[184:187], v[126:129]
	v_mfma_f32_16x16x32_bf16 v[122:125], v[150:153], v[184:187], v[122:125]
	v_mfma_f32_16x16x32_bf16 v[118:121], v[142:145], v[192:195], v[118:121]
	v_mfma_f32_16x16x32_bf16 v[110:113], v[150:153], v[192:195], v[110:113]
	v_mfma_f32_16x16x32_bf16 v[102:105], v[142:145], v[200:203], v[102:105]
	v_mfma_f32_16x16x32_bf16 v[94:97], v[150:153], v[200:203], v[94:97]
	v_mfma_f32_16x16x32_bf16 v[86:89], v[142:145], v[208:211], v[86:89]
	v_mfma_f32_16x16x32_bf16 v[78:81], v[150:153], v[208:211], v[78:81]
	v_mfma_f32_16x16x32_bf16 v[126:129], v[146:149], v[188:191], v[126:129]
	v_mfma_f32_16x16x32_bf16 v[122:125], v[154:157], v[188:191], v[122:125]
	v_mfma_f32_16x16x32_bf16 v[118:121], v[146:149], v[196:199], v[118:121]
	v_mfma_f32_16x16x32_bf16 v[110:113], v[154:157], v[196:199], v[110:113]
	v_mfma_f32_16x16x32_bf16 v[102:105], v[146:149], v[204:207], v[102:105]
	v_mfma_f32_16x16x32_bf16 v[94:97], v[154:157], v[204:207], v[94:97]
	v_mfma_f32_16x16x32_bf16 v[86:89], v[146:149], v[212:215], v[86:89]
	v_mfma_f32_16x16x32_bf16 v[78:81], v[154:157], v[212:215], v[78:81]
	v_mfma_f32_16x16x32_bf16 v[114:117], v[158:161], v[184:187], v[114:117]
	v_mfma_f32_16x16x32_bf16 v[106:109], v[176:179], v[184:187], v[106:109]
	v_mfma_f32_16x16x32_bf16 v[98:101], v[158:161], v[192:195], v[98:101]
	v_mfma_f32_16x16x32_bf16 v[90:93], v[176:179], v[192:195], v[90:93]
	v_mfma_f32_16x16x32_bf16 v[82:85], v[158:161], v[200:203], v[82:85]
	v_mfma_f32_16x16x32_bf16 v[74:77], v[176:179], v[200:203], v[74:77]
	v_mfma_f32_16x16x32_bf16 v[70:73], v[158:161], v[208:211], v[70:73]
	v_mfma_f32_16x16x32_bf16 v[66:69], v[176:179], v[208:211], v[66:69]
	v_mfma_f32_16x16x32_bf16 v[114:117], v[172:175], v[188:191], v[114:117]
	v_mfma_f32_16x16x32_bf16 v[106:109], v[180:183], v[188:191], v[106:109]
	v_mfma_f32_16x16x32_bf16 v[98:101], v[172:175], v[196:199], v[98:101]
	v_mfma_f32_16x16x32_bf16 v[90:93], v[180:183], v[196:199], v[90:93]
	v_mfma_f32_16x16x32_bf16 v[82:85], v[172:175], v[204:207], v[82:85]
	v_mfma_f32_16x16x32_bf16 v[74:77], v[180:183], v[204:207], v[74:77]
	v_mfma_f32_16x16x32_bf16 v[70:73], v[172:175], v[212:215], v[70:73]
	v_mfma_f32_16x16x32_bf16 v[66:69], v[180:183], v[212:215], v[66:69]
	s_setprio 0
	s_barrier
	s_mov_b32 m0, s8
	v_lshl_add_u64 v[136:137], s[64:65], 0, v[162:163]
	ds_read_b128 v[184:187], v141 offset:16384
	ds_read_b128 v[188:191], v141 offset:17408
	ds_read_b128 v[192:195], v141 offset:18432
	ds_read_b128 v[196:199], v141 offset:19456
	ds_read_b128 v[200:203], v141 offset:20480
	ds_read_b128 v[204:207], v141 offset:21504
	ds_read_b128 v[208:211], v141 offset:22528
	ds_read_b128 v[212:215], v141 offset:23552
	global_load_lds_dwordx4 v[136:137], off
	v_lshl_add_u64 v[168:169], s[64:65], 0, v[134:135]
	s_mov_b32 m0, s36
	v_lshl_add_u64 v[170:171], s[66:67], 0, v[162:163]
	global_load_lds_dwordx4 v[168:169], off
	s_mov_b32 m0, s9
	v_lshl_add_u64 v[216:217], s[62:63], 0, v[132:133]
	global_load_lds_dwordx4 v[170:171], off
	v_lshl_add_u64 v[170:171], s[66:67], 0, v[134:135]
	s_mov_b32 m0, s43
	s_nop 0
	global_load_lds_dwordx4 v[170:171], off
	v_lshl_add_u64 v[170:171], s[62:63], 0, v[130:131]
	s_mov_b32 m0, s17
	s_nop 0
	global_load_lds_dwordx4 v[170:171], off
	s_mov_b32 m0, s73
	s_nop 0
	global_load_lds_dwordx4 v[216:217], off
	s_waitcnt vmcnt(8)
	s_waitcnt lgkmcnt(0)
	s_barrier
	s_setprio 1
	v_mfma_f32_16x16x32_bf16 v[62:65], v[142:145], v[184:187], v[62:65]
	v_mfma_f32_16x16x32_bf16 v[58:61], v[150:153], v[184:187], v[58:61]
	v_mfma_f32_16x16x32_bf16 v[54:57], v[142:145], v[192:195], v[54:57]
	v_mfma_f32_16x16x32_bf16 v[46:49], v[150:153], v[192:195], v[46:49]
	v_mfma_f32_16x16x32_bf16 v[38:41], v[142:145], v[200:203], v[38:41]
	v_mfma_f32_16x16x32_bf16 v[30:33], v[150:153], v[200:203], v[30:33]
	v_mfma_f32_16x16x32_bf16 v[22:25], v[142:145], v[208:211], v[22:25]
	v_mfma_f32_16x16x32_bf16 v[14:17], v[150:153], v[208:211], v[14:17]
	v_mfma_f32_16x16x32_bf16 v[62:65], v[146:149], v[188:191], v[62:65]
	v_mfma_f32_16x16x32_bf16 v[58:61], v[154:157], v[188:191], v[58:61]
	v_mfma_f32_16x16x32_bf16 v[54:57], v[146:149], v[196:199], v[54:57]
	v_mfma_f32_16x16x32_bf16 v[46:49], v[154:157], v[196:199], v[46:49]
	v_mfma_f32_16x16x32_bf16 v[38:41], v[146:149], v[204:207], v[38:41]
	v_mfma_f32_16x16x32_bf16 v[30:33], v[154:157], v[204:207], v[30:33]
	v_mfma_f32_16x16x32_bf16 v[22:25], v[146:149], v[212:215], v[22:25]
	v_mfma_f32_16x16x32_bf16 v[14:17], v[154:157], v[212:215], v[14:17]
	v_mfma_f32_16x16x32_bf16 v[50:53], v[158:161], v[184:187], v[50:53]
	v_mfma_f32_16x16x32_bf16 v[42:45], v[176:179], v[184:187], v[42:45]
	v_mfma_f32_16x16x32_bf16 v[34:37], v[158:161], v[192:195], v[34:37]
	v_mfma_f32_16x16x32_bf16 v[26:29], v[176:179], v[192:195], v[26:29]
	v_mfma_f32_16x16x32_bf16 v[18:21], v[158:161], v[200:203], v[18:21]
	v_mfma_f32_16x16x32_bf16 v[10:13], v[176:179], v[200:203], v[10:13]
	v_mfma_f32_16x16x32_bf16 v[6:9], v[158:161], v[208:211], v[6:9]
	v_mfma_f32_16x16x32_bf16 v[2:5], v[176:179], v[208:211], v[2:5]
	v_mfma_f32_16x16x32_bf16 v[50:53], v[172:175], v[188:191], v[50:53]
	v_mfma_f32_16x16x32_bf16 v[42:45], v[180:183], v[188:191], v[42:45]
	v_mfma_f32_16x16x32_bf16 v[34:37], v[172:175], v[196:199], v[34:37]
	v_mfma_f32_16x16x32_bf16 v[26:29], v[180:183], v[196:199], v[26:29]
	v_mfma_f32_16x16x32_bf16 v[18:21], v[172:175], v[204:207], v[18:21]
	v_mfma_f32_16x16x32_bf16 v[10:13], v[180:183], v[204:207], v[10:13]
	v_mfma_f32_16x16x32_bf16 v[6:9], v[172:175], v[212:215], v[6:9]
	v_mfma_f32_16x16x32_bf16 v[2:5], v[180:183], v[212:215], v[2:5]
	s_setprio 0
	s_barrier
	v_add_u32_e32 v154, s89, v139
	v_add_u32_e32 v180, s88, v139
	ds_read_b128 v[142:145], v154
	ds_read_b128 v[146:149], v154 offset:1024
	ds_read_b128 v[150:153], v154 offset:2048
	ds_read_b128 v[154:157], v154 offset:3072
	ds_read_b128 v[158:161], v180
	ds_read_b128 v[172:175], v180 offset:1024
	ds_read_b128 v[176:179], v180 offset:2048
	ds_read_b128 v[180:183], v180 offset:3072
	s_mov_b32 m0, s74
	v_lshl_add_u64 v[222:223], s[60:61], 0, v[130:131]
	ds_read_b128 v[184:187], v141 offset:32768
	ds_read_b128 v[188:191], v141 offset:33792
	ds_read_b128 v[192:195], v141 offset:34816
	ds_read_b128 v[196:199], v141 offset:35840
	ds_read_b128 v[200:203], v141 offset:36864
	ds_read_b128 v[204:207], v141 offset:37888
	ds_read_b128 v[208:211], v141 offset:38912
	ds_read_b128 v[212:215], v141 offset:39936
	global_load_lds_dwordx4 v[222:223], off
	v_lshl_add_u64 v[222:223], s[60:61], 0, v[132:133]
	s_mov_b32 m0, s75
	s_nop 0
	global_load_lds_dwordx4 v[222:223], off
	s_waitcnt vmcnt(8)
	s_waitcnt lgkmcnt(0)
	s_barrier
	s_setprio 1
	v_mfma_f32_16x16x32_bf16 v[126:129], v[142:145], v[184:187], v[126:129]
	v_mfma_f32_16x16x32_bf16 v[122:125], v[150:153], v[184:187], v[122:125]
	v_mfma_f32_16x16x32_bf16 v[118:121], v[142:145], v[192:195], v[118:121]
	v_mfma_f32_16x16x32_bf16 v[110:113], v[150:153], v[192:195], v[110:113]
	v_mfma_f32_16x16x32_bf16 v[102:105], v[142:145], v[200:203], v[102:105]
	v_mfma_f32_16x16x32_bf16 v[94:97], v[150:153], v[200:203], v[94:97]
	v_mfma_f32_16x16x32_bf16 v[86:89], v[142:145], v[208:211], v[86:89]
	v_mfma_f32_16x16x32_bf16 v[78:81], v[150:153], v[208:211], v[78:81]
	v_mfma_f32_16x16x32_bf16 v[126:129], v[146:149], v[188:191], v[126:129]
	v_mfma_f32_16x16x32_bf16 v[122:125], v[154:157], v[188:191], v[122:125]
	v_mfma_f32_16x16x32_bf16 v[118:121], v[146:149], v[196:199], v[118:121]
	v_mfma_f32_16x16x32_bf16 v[110:113], v[154:157], v[196:199], v[110:113]
	v_mfma_f32_16x16x32_bf16 v[102:105], v[146:149], v[204:207], v[102:105]
	v_mfma_f32_16x16x32_bf16 v[94:97], v[154:157], v[204:207], v[94:97]
	v_mfma_f32_16x16x32_bf16 v[86:89], v[146:149], v[212:215], v[86:89]
	v_mfma_f32_16x16x32_bf16 v[78:81], v[154:157], v[212:215], v[78:81]
	v_mfma_f32_16x16x32_bf16 v[114:117], v[158:161], v[184:187], v[114:117]
	v_mfma_f32_16x16x32_bf16 v[106:109], v[176:179], v[184:187], v[106:109]
	v_mfma_f32_16x16x32_bf16 v[98:101], v[158:161], v[192:195], v[98:101]
	v_mfma_f32_16x16x32_bf16 v[90:93], v[176:179], v[192:195], v[90:93]
	v_mfma_f32_16x16x32_bf16 v[82:85], v[158:161], v[200:203], v[82:85]
	v_mfma_f32_16x16x32_bf16 v[74:77], v[176:179], v[200:203], v[74:77]
	v_mfma_f32_16x16x32_bf16 v[70:73], v[158:161], v[208:211], v[70:73]
	v_mfma_f32_16x16x32_bf16 v[66:69], v[176:179], v[208:211], v[66:69]
	v_mfma_f32_16x16x32_bf16 v[114:117], v[172:175], v[188:191], v[114:117]
	v_mfma_f32_16x16x32_bf16 v[106:109], v[180:183], v[188:191], v[106:109]
	v_mfma_f32_16x16x32_bf16 v[98:101], v[172:175], v[196:199], v[98:101]
	v_mfma_f32_16x16x32_bf16 v[90:93], v[180:183], v[196:199], v[90:93]
	v_mfma_f32_16x16x32_bf16 v[82:85], v[172:175], v[204:207], v[82:85]
	v_mfma_f32_16x16x32_bf16 v[74:77], v[180:183], v[204:207], v[74:77]
	v_mfma_f32_16x16x32_bf16 v[70:73], v[172:175], v[212:215], v[70:73]
	v_mfma_f32_16x16x32_bf16 v[66:69], v[180:183], v[212:215], v[66:69]
	s_setprio 0
	s_barrier
	s_mov_b32 m0, s87
	v_lshl_add_u64 v[136:137], v[136:137], 0, s[44:45]
	ds_read_b128 v[184:187], v141 offset:49152
	ds_read_b128 v[188:191], v141 offset:50176
	ds_read_b128 v[192:195], v141 offset:51200
	ds_read_b128 v[196:199], v141 offset:52224
	ds_read_b128 v[200:203], v141 offset:53248
	ds_read_b128 v[204:207], v141 offset:54272
	ds_read_b128 v[208:211], v141 offset:55296
	ds_read_b128 v[212:215], v141 offset:56320
	global_load_lds_dwordx4 v[136:137], off
	v_lshl_add_u64 v[136:137], v[168:169], 0, s[44:45]
	s_mov_b32 m0, s86
	s_nop 0
	global_load_lds_dwordx4 v[136:137], off
	v_lshl_add_u64 v[136:137], s[58:59], 0, v[162:163]
	s_mov_b32 m0, s38
	s_nop 0
	global_load_lds_dwordx4 v[136:137], off
	v_lshl_add_u64 v[136:137], s[58:59], 0, v[134:135]
	s_mov_b32 m0, s37
	s_nop 0
	global_load_lds_dwordx4 v[136:137], off
	v_lshl_add_u64 v[136:137], v[170:171], 0, s[44:45]
	s_mov_b32 m0, s76
	s_nop 0
	global_load_lds_dwordx4 v[136:137], off
	v_lshl_add_u64 v[136:137], v[216:217], 0, s[44:45]
	s_mov_b32 m0, s77
	s_nop 0
	global_load_lds_dwordx4 v[136:137], off
	s_waitcnt vmcnt(8)
	s_waitcnt lgkmcnt(0)
	s_barrier
	s_setprio 1
	v_mfma_f32_16x16x32_bf16 v[62:65], v[142:145], v[184:187], v[62:65]
	v_mfma_f32_16x16x32_bf16 v[58:61], v[150:153], v[184:187], v[58:61]
	v_mfma_f32_16x16x32_bf16 v[54:57], v[142:145], v[192:195], v[54:57]
	v_mfma_f32_16x16x32_bf16 v[46:49], v[150:153], v[192:195], v[46:49]
	v_mfma_f32_16x16x32_bf16 v[38:41], v[142:145], v[200:203], v[38:41]
	v_mfma_f32_16x16x32_bf16 v[30:33], v[150:153], v[200:203], v[30:33]
	v_mfma_f32_16x16x32_bf16 v[22:25], v[142:145], v[208:211], v[22:25]
	v_mfma_f32_16x16x32_bf16 v[14:17], v[150:153], v[208:211], v[14:17]
	v_mfma_f32_16x16x32_bf16 v[62:65], v[146:149], v[188:191], v[62:65]
	v_mfma_f32_16x16x32_bf16 v[58:61], v[154:157], v[188:191], v[58:61]
	v_mfma_f32_16x16x32_bf16 v[54:57], v[146:149], v[196:199], v[54:57]
	v_mfma_f32_16x16x32_bf16 v[46:49], v[154:157], v[196:199], v[46:49]
	v_mfma_f32_16x16x32_bf16 v[38:41], v[146:149], v[204:207], v[38:41]
	v_mfma_f32_16x16x32_bf16 v[30:33], v[154:157], v[204:207], v[30:33]
	v_mfma_f32_16x16x32_bf16 v[22:25], v[146:149], v[212:215], v[22:25]
	v_mfma_f32_16x16x32_bf16 v[14:17], v[154:157], v[212:215], v[14:17]
	v_mfma_f32_16x16x32_bf16 v[50:53], v[158:161], v[184:187], v[50:53]
	v_mfma_f32_16x16x32_bf16 v[42:45], v[176:179], v[184:187], v[42:45]
	v_mfma_f32_16x16x32_bf16 v[34:37], v[158:161], v[192:195], v[34:37]
	v_mfma_f32_16x16x32_bf16 v[26:29], v[176:179], v[192:195], v[26:29]
	v_mfma_f32_16x16x32_bf16 v[18:21], v[158:161], v[200:203], v[18:21]
	v_mfma_f32_16x16x32_bf16 v[10:13], v[176:179], v[200:203], v[10:13]
	v_mfma_f32_16x16x32_bf16 v[6:9], v[158:161], v[208:211], v[6:9]
	v_mfma_f32_16x16x32_bf16 v[2:5], v[176:179], v[208:211], v[2:5]
	v_mfma_f32_16x16x32_bf16 v[50:53], v[172:175], v[188:191], v[50:53]
	v_mfma_f32_16x16x32_bf16 v[42:45], v[180:183], v[188:191], v[42:45]
	v_mfma_f32_16x16x32_bf16 v[34:37], v[172:175], v[196:199], v[34:37]
	v_mfma_f32_16x16x32_bf16 v[26:29], v[180:183], v[196:199], v[26:29]
	v_mfma_f32_16x16x32_bf16 v[18:21], v[172:175], v[204:207], v[18:21]
	v_mfma_f32_16x16x32_bf16 v[10:13], v[180:183], v[204:207], v[10:13]
	v_mfma_f32_16x16x32_bf16 v[6:9], v[172:175], v[212:215], v[6:9]
	v_mfma_f32_16x16x32_bf16 v[2:5], v[180:183], v[212:215], v[2:5]
	s_setprio 0
	s_barrier
	s_movk_i32 s60, 0x100
	s_andn2_b64 vcc, exec, s[56:57]
	s_mov_b64 s[58:59], -1
	s_mov_b64 s[56:57], 0
	s_cbranch_vccz .LBB0_1574
	s_and_b64 vcc, exec, s[18:19]
	s_cbranch_vccz .LBB0_1577
	s_barrier

.LBB0_1615:
	s_add_u32 s31, s64, 0xfffc0080
	s_addc_u32 s36, s65, -1
	s_add_i32 s37, 0, 0x10000
	s_cmp_eq_u32 s27, 12
	s_cselect_b32 vcc_hi, s57, s36
	s_cselect_b32 vcc_lo, s56, s31
	s_cselect_b32 s67, s59, s26
	s_cselect_b32 s66, s58, s25
	s_add_i32 s31, 0, 0x14000
	v_add_u32_e32 v142, s37, v201
	v_add_u32_e32 v158, s31, v201
	ds_read_b128 v[66:69], v142
	ds_read_b128 v[70:73], v142 offset:1024
	ds_read_b128 v[138:141], v142 offset:2048
	ds_read_b128 v[142:145], v142 offset:3072
	ds_read_b128 v[146:149], v158
	ds_read_b128 v[150:153], v158 offset:1024
	ds_read_b128 v[154:157], v158 offset:2048
	ds_read_b128 v[158:161], v158 offset:3072
	v_lshl_add_u64 v[168:169], s[64:65], 0, v[180:181]
	s_add_i32 m0, s63, 0xc000
	ds_read_b128 v[182:185], v222
	ds_read_b128 v[186:189], v222 offset:1024
	ds_read_b128 v[190:193], v222 offset:2048
	ds_read_b128 v[202:205], v222 offset:3072
	ds_read_b128 v[206:209], v222 offset:4096
	ds_read_b128 v[210:213], v222 offset:5120
	ds_read_b128 v[224:227], v222 offset:6144
	ds_read_b128 v[228:231], v222 offset:7168
	global_load_lds_dwordx4 v[168:169], off
	v_lshl_add_u64 v[168:169], s[64:65], 0, v[178:179]
	s_add_i32 m0, s63, 0xe000
	s_nop 0
	global_load_lds_dwordx4 v[168:169], off
	s_waitcnt vmcnt(8)
	s_waitcnt lgkmcnt(0)
	s_barrier
	s_setprio 1
	v_mfma_i32_16x16x64_i8 v[134:137], v[66:69], v[182:185], v[134:137]
	v_mfma_i32_16x16x64_i8 v[130:133], v[138:141], v[182:185], v[130:133]
	v_mfma_i32_16x16x64_i8 v[126:129], v[66:69], v[190:193], v[126:129]
	v_mfma_i32_16x16x64_i8 v[122:125], v[138:141], v[190:193], v[122:125]
	v_mfma_i32_16x16x64_i8 v[118:121], v[66:69], v[206:209], v[118:121]
	v_mfma_i32_16x16x64_i8 v[114:117], v[138:141], v[206:209], v[114:117]
	v_mfma_i32_16x16x64_i8 v[78:81], v[66:69], v[224:227], v[78:81]
	v_mfma_i32_16x16x64_i8 v[74:77], v[138:141], v[224:227], v[74:77]
	v_mfma_i32_16x16x64_i8 v[134:137], v[70:73], v[186:189], v[134:137]
	v_mfma_i32_16x16x64_i8 v[130:133], v[142:145], v[186:189], v[130:133]
	v_mfma_i32_16x16x64_i8 v[126:129], v[70:73], v[202:205], v[126:129]
	v_mfma_i32_16x16x64_i8 v[122:125], v[142:145], v[202:205], v[122:125]
	v_mfma_i32_16x16x64_i8 v[118:121], v[70:73], v[210:213], v[118:121]
	v_mfma_i32_16x16x64_i8 v[114:117], v[142:145], v[210:213], v[114:117]
	v_mfma_i32_16x16x64_i8 v[78:81], v[70:73], v[228:231], v[78:81]
	v_mfma_i32_16x16x64_i8 v[74:77], v[142:145], v[228:231], v[74:77]
	v_mfma_i32_16x16x64_i8 v[110:113], v[146:149], v[182:185], v[110:113]
	v_mfma_i32_16x16x64_i8 v[106:109], v[154:157], v[182:185], v[106:109]
	v_mfma_i32_16x16x64_i8 v[102:105], v[146:149], v[190:193], v[102:105]
	v_mfma_i32_16x16x64_i8 v[98:101], v[154:157], v[190:193], v[98:101]
	v_mfma_i32_16x16x64_i8 v[94:97], v[146:149], v[206:209], v[94:97]
	v_mfma_i32_16x16x64_i8 v[90:93], v[154:157], v[206:209], v[90:93]
	v_mfma_i32_16x16x64_i8 v[86:89], v[146:149], v[224:227], v[86:89]
	v_mfma_i32_16x16x64_i8 v[82:85], v[154:157], v[224:227], v[82:85]
	v_mfma_i32_16x16x64_i8 v[110:113], v[150:153], v[186:189], v[110:113]
	v_mfma_i32_16x16x64_i8 v[106:109], v[158:161], v[186:189], v[106:109]
	v_mfma_i32_16x16x64_i8 v[102:105], v[150:153], v[202:205], v[102:105]
	v_mfma_i32_16x16x64_i8 v[98:101], v[158:161], v[202:205], v[98:101]
	v_mfma_i32_16x16x64_i8 v[94:97], v[150:153], v[210:213], v[94:97]
	v_mfma_i32_16x16x64_i8 v[90:93], v[158:161], v[210:213], v[90:93]
	v_mfma_i32_16x16x64_i8 v[86:89], v[150:153], v[228:231], v[86:89]
	v_mfma_i32_16x16x64_i8 v[82:85], v[158:161], v[228:231], v[82:85]
	s_setprio 0
	s_barrier
	s_add_i32 s36, s37, s61
	v_lshl_add_u64 v[168:169], s[66:67], 0, v[162:163]
	s_mov_b32 m0, s36
	ds_read_b128 v[182:185], v222 offset:16384
	ds_read_b128 v[186:189], v222 offset:17408
	ds_read_b128 v[190:193], v222 offset:18432
	ds_read_b128 v[202:205], v222 offset:19456
	ds_read_b128 v[206:209], v222 offset:20480
	ds_read_b128 v[210:213], v222 offset:21504
	ds_read_b128 v[224:227], v222 offset:22528
	ds_read_b128 v[228:231], v222 offset:23552
	global_load_lds_dwordx4 v[168:169], off
	s_add_i32 m0, s36, 0x2000
	s_add_u32 s36, s66, 0x90000
	v_lshl_add_u64 v[170:171], s[66:67], 0, v[176:177]
	s_addc_u32 s37, s67, 0
	s_add_i32 s31, s31, s61
	global_load_lds_dwordx4 v[170:171], off
	v_lshl_add_u64 v[214:215], s[36:37], 0, v[162:163]
	s_mov_b32 m0, s31
	v_lshl_add_u64 v[232:233], vcc, 0, v[174:175]
	global_load_lds_dwordx4 v[214:215], off
	v_lshl_add_u64 v[214:215], s[36:37], 0, v[176:177]
	s_add_i32 m0, s31, 0x2000
	s_nop 0
	global_load_lds_dwordx4 v[214:215], off
	v_lshl_add_u64 v[214:215], vcc, 0, v[172:173]
	s_mov_b32 m0, s63
	s_nop 0
	global_load_lds_dwordx4 v[214:215], off
	s_mov_b32 m0, s78
	s_nop 0
	global_load_lds_dwordx4 v[232:233], off
	s_waitcnt vmcnt(8)
	s_waitcnt lgkmcnt(0)
	s_barrier
	s_setprio 1
	v_mfma_i32_16x16x64_i8 v[62:65], v[66:69], v[182:185], v[62:65]
	v_mfma_i32_16x16x64_i8 v[58:61], v[138:141], v[182:185], v[58:61]
	v_mfma_i32_16x16x64_i8 v[54:57], v[66:69], v[190:193], v[54:57]
	v_mfma_i32_16x16x64_i8 v[50:53], v[138:141], v[190:193], v[50:53]
	v_mfma_i32_16x16x64_i8 v[46:49], v[66:69], v[206:209], v[46:49]
	v_mfma_i32_16x16x64_i8 v[42:45], v[138:141], v[206:209], v[42:45]
	v_mfma_i32_16x16x64_i8 v[38:41], v[66:69], v[224:227], v[38:41]
	v_mfma_i32_16x16x64_i8 v[34:37], v[138:141], v[224:227], v[34:37]
	v_mfma_i32_16x16x64_i8 v[62:65], v[70:73], v[186:189], v[62:65]
	v_mfma_i32_16x16x64_i8 v[58:61], v[142:145], v[186:189], v[58:61]
	v_mfma_i32_16x16x64_i8 v[54:57], v[70:73], v[202:205], v[54:57]
	v_mfma_i32_16x16x64_i8 v[50:53], v[142:145], v[202:205], v[50:53]
	v_mfma_i32_16x16x64_i8 v[46:49], v[70:73], v[210:213], v[46:49]
	v_mfma_i32_16x16x64_i8 v[42:45], v[142:145], v[210:213], v[42:45]
	v_mfma_i32_16x16x64_i8 v[38:41], v[70:73], v[228:231], v[38:41]
	v_mfma_i32_16x16x64_i8 v[34:37], v[142:145], v[228:231], v[34:37]
	v_mfma_i32_16x16x64_i8 v[30:33], v[146:149], v[182:185], v[30:33]
	v_mfma_i32_16x16x64_i8 v[26:29], v[154:157], v[182:185], v[26:29]
	v_mfma_i32_16x16x64_i8 v[22:25], v[146:149], v[190:193], v[22:25]
	v_mfma_i32_16x16x64_i8 v[18:21], v[154:157], v[190:193], v[18:21]
	v_mfma_i32_16x16x64_i8 v[14:17], v[146:149], v[206:209], v[14:17]
	v_mfma_i32_16x16x64_i8 v[10:13], v[154:157], v[206:209], v[10:13]
	v_mfma_i32_16x16x64_i8 v[6:9], v[146:149], v[224:227], v[6:9]
	v_mfma_i32_16x16x64_i8 v[2:5], v[154:157], v[224:227], v[2:5]
	v_mfma_i32_16x16x64_i8 v[30:33], v[150:153], v[186:189], v[30:33]
	v_mfma_i32_16x16x64_i8 v[26:29], v[158:161], v[186:189], v[26:29]
	v_mfma_i32_16x16x64_i8 v[22:25], v[150:153], v[202:205], v[22:25]
	v_mfma_i32_16x16x64_i8 v[18:21], v[158:161], v[202:205], v[18:21]
	v_mfma_i32_16x16x64_i8 v[14:17], v[150:153], v[210:213], v[14:17]
	v_mfma_i32_16x16x64_i8 v[10:13], v[158:161], v[210:213], v[10:13]
	v_mfma_i32_16x16x64_i8 v[6:9], v[150:153], v[228:231], v[6:9]
	v_mfma_i32_16x16x64_i8 v[2:5], v[158:161], v[228:231], v[2:5]
	s_setprio 0
	s_barrier
	s_add_i32 s31, 0, 0x18000
	s_add_i32 s38, 0, 0x1c000
	v_add_u32_e32 v142, s31, v201
	v_add_u32_e32 v158, s38, v201
	ds_read_b128 v[66:69], v142
	ds_read_b128 v[70:73], v142 offset:1024
	ds_read_b128 v[138:141], v142 offset:2048
	ds_read_b128 v[142:145], v142 offset:3072
	ds_read_b128 v[146:149], v158
	ds_read_b128 v[150:153], v158 offset:1024
	ds_read_b128 v[154:157], v158 offset:2048
	ds_read_b128 v[158:161], v158 offset:3072
	s_add_u32 s36, vcc_lo, 0x40000
	s_addc_u32 s37, vcc_hi, 0
	s_mov_b32 m0, s79
	v_lshl_add_u64 v[234:235], s[36:37], 0, v[172:173]
	ds_read_b128 v[182:185], v222 offset:32768
	ds_read_b128 v[186:189], v222 offset:33792
	ds_read_b128 v[190:193], v222 offset:34816
	ds_read_b128 v[202:205], v222 offset:35840
	ds_read_b128 v[206:209], v222 offset:36864
	ds_read_b128 v[210:213], v222 offset:37888
	ds_read_b128 v[224:227], v222 offset:38912
	ds_read_b128 v[228:231], v222 offset:39936
	global_load_lds_dwordx4 v[234:235], off
	v_lshl_add_u64 v[234:235], s[36:37], 0, v[174:175]
	s_mov_b32 m0, s80
	s_nop 0
	global_load_lds_dwordx4 v[234:235], off
	s_waitcnt vmcnt(8)
	s_waitcnt lgkmcnt(0)
	s_barrier
	s_setprio 1
	v_mfma_i32_16x16x64_i8 v[134:137], v[66:69], v[182:185], v[134:137]
	v_mfma_i32_16x16x64_i8 v[130:133], v[138:141], v[182:185], v[130:133]
	v_mfma_i32_16x16x64_i8 v[126:129], v[66:69], v[190:193], v[126:129]
	v_mfma_i32_16x16x64_i8 v[122:125], v[138:141], v[190:193], v[122:125]
	v_mfma_i32_16x16x64_i8 v[118:121], v[66:69], v[206:209], v[118:121]
	v_mfma_i32_16x16x64_i8 v[114:117], v[138:141], v[206:209], v[114:117]
	v_mfma_i32_16x16x64_i8 v[78:81], v[66:69], v[224:227], v[78:81]
	v_mfma_i32_16x16x64_i8 v[74:77], v[138:141], v[224:227], v[74:77]
	v_mfma_i32_16x16x64_i8 v[134:137], v[70:73], v[186:189], v[134:137]
	v_mfma_i32_16x16x64_i8 v[130:133], v[142:145], v[186:189], v[130:133]
	v_mfma_i32_16x16x64_i8 v[126:129], v[70:73], v[202:205], v[126:129]
	v_mfma_i32_16x16x64_i8 v[122:125], v[142:145], v[202:205], v[122:125]
	v_mfma_i32_16x16x64_i8 v[118:121], v[70:73], v[210:213], v[118:121]
	v_mfma_i32_16x16x64_i8 v[114:117], v[142:145], v[210:213], v[114:117]
	v_mfma_i32_16x16x64_i8 v[78:81], v[70:73], v[228:231], v[78:81]
	v_mfma_i32_16x16x64_i8 v[74:77], v[142:145], v[228:231], v[74:77]
	v_mfma_i32_16x16x64_i8 v[110:113], v[146:149], v[182:185], v[110:113]
	v_mfma_i32_16x16x64_i8 v[106:109], v[154:157], v[182:185], v[106:109]
	v_mfma_i32_16x16x64_i8 v[102:105], v[146:149], v[190:193], v[102:105]
	v_mfma_i32_16x16x64_i8 v[98:101], v[154:157], v[190:193], v[98:101]
	v_mfma_i32_16x16x64_i8 v[94:97], v[146:149], v[206:209], v[94:97]
	v_mfma_i32_16x16x64_i8 v[90:93], v[154:157], v[206:209], v[90:93]
	v_mfma_i32_16x16x64_i8 v[86:89], v[146:149], v[224:227], v[86:89]
	v_mfma_i32_16x16x64_i8 v[82:85], v[154:157], v[224:227], v[82:85]
	v_mfma_i32_16x16x64_i8 v[110:113], v[150:153], v[186:189], v[110:113]
	v_mfma_i32_16x16x64_i8 v[106:109], v[158:161], v[186:189], v[106:109]
	v_mfma_i32_16x16x64_i8 v[102:105], v[150:153], v[202:205], v[102:105]
	v_mfma_i32_16x16x64_i8 v[98:101], v[158:161], v[202:205], v[98:101]
	v_mfma_i32_16x16x64_i8 v[94:97], v[150:153], v[210:213], v[94:97]
	v_mfma_i32_16x16x64_i8 v[90:93], v[158:161], v[210:213], v[90:93]
	v_mfma_i32_16x16x64_i8 v[86:89], v[150:153], v[228:231], v[86:89]
	v_mfma_i32_16x16x64_i8 v[82:85], v[158:161], v[228:231], v[82:85]
	s_setprio 0
	s_barrier
	s_add_i32 s31, s31, s61
	v_lshl_add_u64 v[168:169], v[168:169], 0, s[44:45]
	s_mov_b32 m0, s31
	ds_read_b128 v[182:185], v222 offset:49152
	ds_read_b128 v[186:189], v222 offset:50176
	ds_read_b128 v[190:193], v222 offset:51200
	ds_read_b128 v[202:205], v222 offset:52224
	ds_read_b128 v[206:209], v222 offset:53248
	ds_read_b128 v[210:213], v222 offset:54272
	ds_read_b128 v[224:227], v222 offset:55296
	ds_read_b128 v[228:231], v222 offset:56320
	global_load_lds_dwordx4 v[168:169], off
	s_add_i32 m0, s31, 0x2000
	s_add_u32 s36, s66, 0x90080
	v_lshl_add_u64 v[168:169], v[170:171], 0, s[44:45]
	s_addc_u32 s37, s67, 0
	s_add_i32 s31, s38, s61
	global_load_lds_dwordx4 v[168:169], off
	v_lshl_add_u64 v[168:169], s[36:37], 0, v[162:163]
	s_mov_b32 m0, s31
	s_nop 0
	global_load_lds_dwordx4 v[168:169], off
	v_lshl_add_u64 v[168:169], s[36:37], 0, v[176:177]
	s_add_i32 m0, s31, 0x2000
	s_nop 0
	global_load_lds_dwordx4 v[168:169], off
	v_lshl_add_u64 v[168:169], v[214:215], 0, s[44:45]
	s_mov_b32 m0, s82
	s_nop 0
	global_load_lds_dwordx4 v[168:169], off
	v_lshl_add_u64 v[168:169], v[232:233], 0, s[44:45]
	s_mov_b32 m0, s83
	s_nop 0
	global_load_lds_dwordx4 v[168:169], off
	s_waitcnt vmcnt(8)
	s_waitcnt lgkmcnt(0)
	s_barrier
	s_setprio 1
	v_mfma_i32_16x16x64_i8 v[62:65], v[66:69], v[182:185], v[62:65]
	v_mfma_i32_16x16x64_i8 v[58:61], v[138:141], v[182:185], v[58:61]
	v_mfma_i32_16x16x64_i8 v[54:57], v[66:69], v[190:193], v[54:57]
	v_mfma_i32_16x16x64_i8 v[50:53], v[138:141], v[190:193], v[50:53]
	v_mfma_i32_16x16x64_i8 v[46:49], v[66:69], v[206:209], v[46:49]
	v_mfma_i32_16x16x64_i8 v[42:45], v[138:141], v[206:209], v[42:45]
	v_mfma_i32_16x16x64_i8 v[38:41], v[66:69], v[224:227], v[38:41]
	v_mfma_i32_16x16x64_i8 v[34:37], v[138:141], v[224:227], v[34:37]
	v_mfma_i32_16x16x64_i8 v[62:65], v[70:73], v[186:189], v[62:65]
	v_mfma_i32_16x16x64_i8 v[58:61], v[142:145], v[186:189], v[58:61]
	v_mfma_i32_16x16x64_i8 v[54:57], v[70:73], v[202:205], v[54:57]
	v_mfma_i32_16x16x64_i8 v[50:53], v[142:145], v[202:205], v[50:53]
	v_mfma_i32_16x16x64_i8 v[46:49], v[70:73], v[210:213], v[46:49]
	v_mfma_i32_16x16x64_i8 v[42:45], v[142:145], v[210:213], v[42:45]
	v_mfma_i32_16x16x64_i8 v[38:41], v[70:73], v[228:231], v[38:41]
	v_mfma_i32_16x16x64_i8 v[34:37], v[142:145], v[228:231], v[34:37]
	v_mfma_i32_16x16x64_i8 v[30:33], v[146:149], v[182:185], v[30:33]
	v_mfma_i32_16x16x64_i8 v[26:29], v[154:157], v[182:185], v[26:29]
	v_mfma_i32_16x16x64_i8 v[22:25], v[146:149], v[190:193], v[22:25]
	v_mfma_i32_16x16x64_i8 v[18:21], v[154:157], v[190:193], v[18:21]
	v_mfma_i32_16x16x64_i8 v[14:17], v[146:149], v[206:209], v[14:17]
	v_mfma_i32_16x16x64_i8 v[10:13], v[154:157], v[206:209], v[10:13]
	v_mfma_i32_16x16x64_i8 v[6:9], v[146:149], v[224:227], v[6:9]
	v_mfma_i32_16x16x64_i8 v[2:5], v[154:157], v[224:227], v[2:5]
	v_mfma_i32_16x16x64_i8 v[30:33], v[150:153], v[186:189], v[30:33]
	v_mfma_i32_16x16x64_i8 v[26:29], v[158:161], v[186:189], v[26:29]
	v_mfma_i32_16x16x64_i8 v[22:25], v[150:153], v[202:205], v[22:25]
	v_mfma_i32_16x16x64_i8 v[18:21], v[158:161], v[202:205], v[18:21]
	v_mfma_i32_16x16x64_i8 v[14:17], v[150:153], v[210:213], v[14:17]
	v_mfma_i32_16x16x64_i8 v[10:13], v[158:161], v[210:213], v[10:13]
	v_mfma_i32_16x16x64_i8 v[6:9], v[150:153], v[228:231], v[6:9]
	v_mfma_i32_16x16x64_i8 v[2:5], v[158:161], v[228:231], v[2:5]
	s_setprio 0
	s_barrier
	s_add_i32 s27, s27, 2
	s_add_u32 s25, s25, 0x100
	s_addc_u32 s26, s26, 0
	s_add_u32 s64, s64, 0x100
	s_addc_u32 s65, s65, 0
	s_cmp_gt_u32 s27, 13
	s_cbranch_scc0 .LBB0_1615
	s_and_b64 vcc, exec, s[22:23]
	s_cbranch_vccz .LBB0_1618
	s_barrier
